# residual epilogues: byte-select unpack without shifts and a DPP select for the lane-pair exchange (same arithmetic, 21% fewer instructions)
# speedup vs baseline: 1.0158x; 1.0031x over previous
.LBB0_1191:
	s_ashr_i32 s12, s55, 31
	s_lshr_b32 s12, s12, 29
	s_add_i32 s12, s55, s12
	s_ashr_i32 s12, s12, 3
	s_mul_i32 s27, s12, 0x6000
	s_mul_hi_i32 s25, s12, 0x6000
	s_add_u32 s80, s40, s27
	s_addc_u32 s81, s41, s25
	s_add_u32 s82, s47, s27
	s_addc_u32 s83, s48, s25
	s_mov_b32 s62, 0xaaaaaaaa
	s_mov_b32 s63, 0xaaaaaaaa
	s_mov_b32 s66, 0x55555555
	s_mov_b32 s67, 0x55555555
	s_mov_b32 s32, 0x0504000c
	s_mov_b32 s61, 0x0504020c
	s_mov_b32 s98, 0x0706030c
	v_mbcnt_lo_u32_b32 v150, -1, 0
	v_mbcnt_hi_u32_b32 v150, -1, v150
	v_and_b32_e32 v150, 1, v150
	v_and_b32_e32 v149, 0x60, v194
	v_add_u32_e32 v149, v149, v194
	v_lshl_or_b32 v149, s4, 8, v149
	v_lshlrev_b32_e32 v28, 2, v149
	v_lshl_add_u32 v149, v150, 5, v149
	v_lshl_add_u32 v148, s55, 8, v192
	v_sub_u32_e32 v148, v148, v150
	v_lshl_add_u32 v148, v148, 10, v149
	v_lshlrev_b32_e32 v149, 1, v148
	global_load_dwordx4 v[176:179], v28, s[80:81] offset:0
	global_load_dwordx4 v[180:183], v28, s[80:81] offset:16
	global_load_dwordx4 v[210:213], v28, s[20:21] offset:0
	global_load_dwordx4 v[214:217], v28, s[20:21] offset:16
	global_load_dwordx4 v[184:187], v28, s[80:81] offset:128
	global_load_dwordx4 v[188:191], v28, s[80:81] offset:144
	global_load_dwordx4 v[218:221], v28, s[20:21] offset:128
	global_load_dwordx4 v[222:225], v28, s[20:21] offset:144
	global_load_dwordx4 v[226:229], v28, s[82:83] offset:0
	global_load_dwordx4 v[230:233], v28, s[82:83] offset:16
	s_waitcnt vmcnt(0)
	v_pk_add_f32 v[226:227], v[226:227], 1.0 op_sel_hi:[1,0]
	v_pk_add_f32 v[228:229], v[228:229], 1.0 op_sel_hi:[1,0]
	v_pk_add_f32 v[230:231], v[230:231], 1.0 op_sel_hi:[1,0]
	v_pk_add_f32 v[232:233], v[232:233], 1.0 op_sel_hi:[1,0]
	v_pk_mul_f32 v[210:211], v[210:211], v[226:227]
	v_pk_mul_f32 v[212:213], v[212:213], v[228:229]
	v_pk_mul_f32 v[214:215], v[214:215], v[230:231]
	v_pk_mul_f32 v[216:217], v[216:217], v[232:233]
	s_nop 1
	global_load_dwordx4 v[226:229], v28, s[82:83] offset:128
	global_load_dwordx4 v[230:233], v28, s[82:83] offset:144
	s_waitcnt vmcnt(0)
	v_pk_add_f32 v[226:227], v[226:227], 1.0 op_sel_hi:[1,0]
	v_pk_add_f32 v[228:229], v[228:229], 1.0 op_sel_hi:[1,0]
	v_pk_add_f32 v[230:231], v[230:231], 1.0 op_sel_hi:[1,0]
	v_pk_add_f32 v[232:233], v[232:233], 1.0 op_sel_hi:[1,0]
	v_pk_mul_f32 v[218:219], v[218:219], v[226:227]
	v_pk_mul_f32 v[220:221], v[220:221], v[228:229]
	v_pk_mul_f32 v[222:223], v[222:223], v[230:231]
	v_pk_mul_f32 v[224:225], v[224:225], v[232:233]
	s_add_u32 s84, s58, 0x0
	s_addc_u32 s85, s59, 0
	s_add_u32 s86, s74, 0x0
	s_addc_u32 s87, s75, 0
	global_load_dwordx4 v[226:229], v149, s[84:85]
	global_load_dwordx2 v[152:153], v148, s[86:87]
	global_load_dwordx4 v[230:233], v149, s[84:85] offset:2048
	global_load_dwordx2 v[196:197], v148, s[86:87] offset:1024
	s_waitcnt vmcnt(0)
	s_mov_b64 vcc, s[66:67]
	v_cndmask_b32_dpp v32, v230, v226, vcc quad_perm:[1,0,3,2] row_mask:0xf bank_mask:0xf
	v_cndmask_b32_dpp v33, v231, v227, vcc quad_perm:[1,0,3,2] row_mask:0xf bank_mask:0xf
	v_cndmask_b32_dpp v34, v232, v228, vcc quad_perm:[1,0,3,2] row_mask:0xf bank_mask:0xf
	v_cndmask_b32_dpp v35, v233, v229, vcc quad_perm:[1,0,3,2] row_mask:0xf bank_mask:0xf
	s_mov_b64 vcc, s[62:63]
	v_cndmask_b32_dpp v230, v226, v230, vcc quad_perm:[1,0,3,2] row_mask:0xf bank_mask:0xf
	v_cndmask_b32_dpp v231, v227, v231, vcc quad_perm:[1,0,3,2] row_mask:0xf bank_mask:0xf
	v_cndmask_b32_dpp v232, v228, v232, vcc quad_perm:[1,0,3,2] row_mask:0xf bank_mask:0xf
	v_cndmask_b32_dpp v233, v229, v233, vcc quad_perm:[1,0,3,2] row_mask:0xf bank_mask:0xf
	s_mov_b64 vcc, s[66:67]
	v_cndmask_b32_dpp v36, v196, v152, vcc quad_perm:[1,0,3,2] row_mask:0xf bank_mask:0xf
	v_cndmask_b32_dpp v37, v197, v153, vcc quad_perm:[1,0,3,2] row_mask:0xf bank_mask:0xf
	s_mov_b64 vcc, s[62:63]
	v_cndmask_b32_dpp v196, v152, v196, vcc quad_perm:[1,0,3,2] row_mask:0xf bank_mask:0xf
	v_cndmask_b32_dpp v197, v153, v197, vcc quad_perm:[1,0,3,2] row_mask:0xf bank_mask:0xf
	v_perm_b32 v28, v32, v36, s32
	v_perm_b32 v29, v32, v36, s8
	v_perm_b32 v30, v33, v36, s61
	v_perm_b32 v31, v33, v36, s98
	v_pk_fma_f32 v[142:143], v[142:143], v[176:177], v[28:29]
	v_pk_fma_f32 v[144:145], v[144:145], v[178:179], v[30:31]
	v_perm_b32 v28, v34, v37, s32
	v_perm_b32 v29, v34, v37, s8
	v_perm_b32 v30, v35, v37, s61
	v_perm_b32 v31, v35, v37, s98
	v_pk_fma_f32 v[138:139], v[138:139], v[180:181], v[28:29]
	v_pk_fma_f32 v[140:141], v[140:141], v[182:183], v[30:31]
	v_perm_b32 v28, v230, v196, s32
	v_perm_b32 v29, v230, v196, s8
	v_perm_b32 v30, v231, v196, s61
	v_perm_b32 v31, v231, v196, s98
	v_pk_fma_f32 v[134:135], v[134:135], v[184:185], v[28:29]
	v_pk_fma_f32 v[136:137], v[136:137], v[186:187], v[30:31]
	v_perm_b32 v28, v232, v197, s32
	v_perm_b32 v29, v232, v197, s8
	v_perm_b32 v30, v233, v197, s61
	v_perm_b32 v31, v233, v197, s98
	v_pk_fma_f32 v[130:131], v[130:131], v[188:189], v[28:29]
	v_pk_fma_f32 v[132:133], v[132:133], v[190:191], v[30:31]
	v_mul_f32_e32 v28, v143, v143
	v_mul_f32_e32 v29, v145, v145
	v_mul_f32_e32 v30, v139, v139
	v_mul_f32_e32 v31, v141, v141
	v_fmac_f32_e32 v28, v142, v142
	v_fmac_f32_e32 v29, v144, v144
	v_fmac_f32_e32 v30, v138, v138
	v_fmac_f32_e32 v31, v140, v140
	v_add_f32_e32 v28, v28, v29
	v_add_f32_e32 v30, v30, v31
	v_add_f32_e32 v151, v28, v30
	v_add_u32_e32 v28, 0x80, v142
	v_add_u32_e32 v29, 0x80, v143
	v_add_u32_e32 v30, 0x80, v144
	v_add_u32_e32 v31, 0x80, v145
	v_perm_b32 v32, v29, v28, s78
	v_perm_b32 v33, v31, v30, s78
	v_perm_b32 v26, v29, v28, s79
	v_perm_b32 v27, v31, v30, s79
	v_perm_b32 v40, v27, v26, s60
	v_add_u32_e32 v28, 0x80, v138
	v_add_u32_e32 v29, 0x80, v139
	v_add_u32_e32 v30, 0x80, v140
	v_add_u32_e32 v31, 0x80, v141
	v_perm_b32 v34, v29, v28, s78
	v_perm_b32 v35, v31, v30, s78
	v_perm_b32 v26, v29, v28, s79
	v_perm_b32 v27, v31, v30, s79
	v_perm_b32 v41, v27, v26, s60
	v_mul_f32_e32 v28, v135, v135
	v_mul_f32_e32 v29, v137, v137
	v_mul_f32_e32 v30, v131, v131
	v_mul_f32_e32 v31, v133, v133
	v_fmac_f32_e32 v28, v134, v134
	v_fmac_f32_e32 v29, v136, v136
	v_fmac_f32_e32 v30, v130, v130
	v_fmac_f32_e32 v31, v132, v132
	v_add_f32_e32 v28, v28, v29
	v_add_f32_e32 v30, v30, v31
	v_add_f32_e32 v28, v28, v30
	v_add_f32_e32 v151, v151, v28
	v_add_u32_e32 v28, 0x80, v134
	v_add_u32_e32 v29, 0x80, v135
	v_add_u32_e32 v30, 0x80, v136
	v_add_u32_e32 v31, 0x80, v137
	v_perm_b32 v36, v29, v28, s78
	v_perm_b32 v37, v31, v30, s78
	v_perm_b32 v26, v29, v28, s79
	v_perm_b32 v27, v31, v30, s79
	v_perm_b32 v146, v27, v26, s60
	v_add_u32_e32 v28, 0x80, v130
	v_add_u32_e32 v29, 0x80, v131
	v_add_u32_e32 v30, 0x80, v132
	v_add_u32_e32 v31, 0x80, v133
	v_perm_b32 v38, v29, v28, s78
	v_perm_b32 v39, v31, v30, s78
	v_perm_b32 v26, v29, v28, s79
	v_perm_b32 v27, v31, v30, s79
	v_perm_b32 v147, v27, v26, s60
	s_mov_b64 vcc, s[66:67]
	v_cndmask_b32_dpp v226, v36, v32, vcc quad_perm:[1,0,3,2] row_mask:0xf bank_mask:0xf
	v_cndmask_b32_dpp v227, v37, v33, vcc quad_perm:[1,0,3,2] row_mask:0xf bank_mask:0xf
	v_cndmask_b32_dpp v228, v38, v34, vcc quad_perm:[1,0,3,2] row_mask:0xf bank_mask:0xf
	v_cndmask_b32_dpp v229, v39, v35, vcc quad_perm:[1,0,3,2] row_mask:0xf bank_mask:0xf
	s_mov_b64 vcc, s[62:63]
	v_cndmask_b32_dpp v36, v32, v36, vcc quad_perm:[1,0,3,2] row_mask:0xf bank_mask:0xf
	v_cndmask_b32_dpp v37, v33, v37, vcc quad_perm:[1,0,3,2] row_mask:0xf bank_mask:0xf
	v_cndmask_b32_dpp v38, v34, v38, vcc quad_perm:[1,0,3,2] row_mask:0xf bank_mask:0xf
	v_cndmask_b32_dpp v39, v35, v39, vcc quad_perm:[1,0,3,2] row_mask:0xf bank_mask:0xf
	s_mov_b64 vcc, s[66:67]
	v_cndmask_b32_dpp v230, v146, v40, vcc quad_perm:[1,0,3,2] row_mask:0xf bank_mask:0xf
	v_cndmask_b32_dpp v231, v147, v41, vcc quad_perm:[1,0,3,2] row_mask:0xf bank_mask:0xf
	s_mov_b64 vcc, s[62:63]
	v_cndmask_b32_dpp v146, v40, v146, vcc quad_perm:[1,0,3,2] row_mask:0xf bank_mask:0xf
	v_cndmask_b32_dpp v147, v41, v147, vcc quad_perm:[1,0,3,2] row_mask:0xf bank_mask:0xf
	s_add_u32 s88, s58, 0x0
	s_addc_u32 s89, s59, 0
	s_add_u32 s90, s74, 0x0
	s_addc_u32 s91, s75, 0
	global_store_dwordx4 v149, v[226:229], s[88:89]
	global_store_dwordx4 v149, v[36:39], s[88:89] offset:2048
	global_store_dwordx2 v148, v[230:231], s[90:91]
	global_store_dwordx2 v148, v[146:147], s[90:91] offset:1024
	s_add_u32 s92, s96, 0x0
	s_addc_u32 s93, s97, 0
	v_pk_mul_f32 v[142:143], v[210:211], v[142:143]
	v_pk_mul_f32 v[144:145], v[212:213], v[144:145]
	v_pk_mul_f32 v[138:139], v[214:215], v[138:139]
	v_pk_mul_f32 v[140:141], v[216:217], v[140:141]
	v_cvt_pk_bf16_f32 v32, v142, v143
	v_cvt_pk_bf16_f32 v33, v144, v145
	v_cvt_pk_bf16_f32 v34, v138, v139
	v_cvt_pk_bf16_f32 v35, v140, v141
	v_pk_mul_f32 v[134:135], v[218:219], v[134:135]
	v_pk_mul_f32 v[136:137], v[220:221], v[136:137]
	v_pk_mul_f32 v[130:131], v[222:223], v[130:131]
	v_pk_mul_f32 v[132:133], v[224:225], v[132:133]
	v_cvt_pk_bf16_f32 v36, v134, v135
	v_cvt_pk_bf16_f32 v37, v136, v137
	v_cvt_pk_bf16_f32 v38, v130, v131
	v_cvt_pk_bf16_f32 v39, v132, v133
	s_mov_b64 vcc, s[66:67]
	v_cndmask_b32_dpp v226, v36, v32, vcc quad_perm:[1,0,3,2] row_mask:0xf bank_mask:0xf
	v_cndmask_b32_dpp v227, v37, v33, vcc quad_perm:[1,0,3,2] row_mask:0xf bank_mask:0xf
	v_cndmask_b32_dpp v228, v38, v34, vcc quad_perm:[1,0,3,2] row_mask:0xf bank_mask:0xf
	v_cndmask_b32_dpp v229, v39, v35, vcc quad_perm:[1,0,3,2] row_mask:0xf bank_mask:0xf
	s_mov_b64 vcc, s[62:63]
	v_cndmask_b32_dpp v36, v32, v36, vcc quad_perm:[1,0,3,2] row_mask:0xf bank_mask:0xf
	v_cndmask_b32_dpp v37, v33, v37, vcc quad_perm:[1,0,3,2] row_mask:0xf bank_mask:0xf
	v_cndmask_b32_dpp v38, v34, v38, vcc quad_perm:[1,0,3,2] row_mask:0xf bank_mask:0xf
	v_cndmask_b32_dpp v39, v35, v39, vcc quad_perm:[1,0,3,2] row_mask:0xf bank_mask:0xf
	global_store_dwordx4 v149, v[226:229], s[92:93]
	global_store_dwordx4 v149, v[36:39], s[92:93] offset:2048
	v_mov_b32_e32 v130, v151
	s_add_u32 s84, s58, 0x8000
	s_addc_u32 s85, s59, 0
	s_add_u32 s86, s74, 0x4000
	s_addc_u32 s87, s75, 0
	global_load_dwordx4 v[132:135], v149, s[84:85]
	global_load_dwordx2 v[136:137], v148, s[86:87]
	global_load_dwordx4 v[138:141], v149, s[84:85] offset:2048
	global_load_dwordx2 v[142:143], v148, s[86:87] offset:1024
	s_add_u32 s84, s58, 0x10000
	s_addc_u32 s85, s59, 0
	s_add_u32 s86, s74, 0x8000
	s_addc_u32 s87, s75, 0
	global_load_dwordx4 v[226:229], v149, s[84:85]
	global_load_dwordx2 v[144:145], v148, s[86:87]
	global_load_dwordx4 v[230:233], v149, s[84:85] offset:2048
	global_load_dwordx2 v[152:153], v148, s[86:87] offset:1024
	s_waitcnt vmcnt(4)
	s_mov_b64 vcc, s[66:67]
	v_cndmask_b32_dpp v32, v138, v132, vcc quad_perm:[1,0,3,2] row_mask:0xf bank_mask:0xf
	v_cndmask_b32_dpp v33, v139, v133, vcc quad_perm:[1,0,3,2] row_mask:0xf bank_mask:0xf
	v_cndmask_b32_dpp v34, v140, v134, vcc quad_perm:[1,0,3,2] row_mask:0xf bank_mask:0xf
	v_cndmask_b32_dpp v35, v141, v135, vcc quad_perm:[1,0,3,2] row_mask:0xf bank_mask:0xf
	s_mov_b64 vcc, s[62:63]
	v_cndmask_b32_dpp v138, v132, v138, vcc quad_perm:[1,0,3,2] row_mask:0xf bank_mask:0xf
	v_cndmask_b32_dpp v139, v133, v139, vcc quad_perm:[1,0,3,2] row_mask:0xf bank_mask:0xf
	v_cndmask_b32_dpp v140, v134, v140, vcc quad_perm:[1,0,3,2] row_mask:0xf bank_mask:0xf
	v_cndmask_b32_dpp v141, v135, v141, vcc quad_perm:[1,0,3,2] row_mask:0xf bank_mask:0xf
	s_mov_b64 vcc, s[66:67]
	v_cndmask_b32_dpp v36, v142, v136, vcc quad_perm:[1,0,3,2] row_mask:0xf bank_mask:0xf
	v_cndmask_b32_dpp v37, v143, v137, vcc quad_perm:[1,0,3,2] row_mask:0xf bank_mask:0xf
	s_mov_b64 vcc, s[62:63]
	v_cndmask_b32_dpp v142, v136, v142, vcc quad_perm:[1,0,3,2] row_mask:0xf bank_mask:0xf
	v_cndmask_b32_dpp v143, v137, v143, vcc quad_perm:[1,0,3,2] row_mask:0xf bank_mask:0xf
	v_perm_b32 v28, v32, v36, s32
	v_perm_b32 v29, v32, v36, s8
	v_perm_b32 v30, v33, v36, s61
	v_perm_b32 v31, v33, v36, s98
	v_pk_fma_f32 v[126:127], v[126:127], v[176:177], v[28:29]
	v_pk_fma_f32 v[128:129], v[128:129], v[178:179], v[30:31]
	v_perm_b32 v28, v34, v37, s32
	v_perm_b32 v29, v34, v37, s8
	v_perm_b32 v30, v35, v37, s61
	v_perm_b32 v31, v35, v37, s98
	v_pk_fma_f32 v[122:123], v[122:123], v[180:181], v[28:29]
	v_pk_fma_f32 v[124:125], v[124:125], v[182:183], v[30:31]
	v_perm_b32 v28, v138, v142, s32
	v_perm_b32 v29, v138, v142, s8
	v_perm_b32 v30, v139, v142, s61
	v_perm_b32 v31, v139, v142, s98
	v_pk_fma_f32 v[118:119], v[118:119], v[184:185], v[28:29]
	v_pk_fma_f32 v[120:121], v[120:121], v[186:187], v[30:31]
	v_perm_b32 v28, v140, v143, s32
	v_perm_b32 v29, v140, v143, s8
	v_perm_b32 v30, v141, v143, s61
	v_perm_b32 v31, v141, v143, s98
	v_pk_fma_f32 v[114:115], v[114:115], v[188:189], v[28:29]
	v_pk_fma_f32 v[116:117], v[116:117], v[190:191], v[30:31]
	v_mul_f32_e32 v28, v127, v127
	v_mul_f32_e32 v29, v129, v129
	v_mul_f32_e32 v30, v123, v123
	v_mul_f32_e32 v31, v125, v125
	v_fmac_f32_e32 v28, v126, v126
	v_fmac_f32_e32 v29, v128, v128
	v_fmac_f32_e32 v30, v122, v122
	v_fmac_f32_e32 v31, v124, v124
	v_add_f32_e32 v28, v28, v29
	v_add_f32_e32 v30, v30, v31
	v_add_f32_e32 v151, v28, v30
	v_add_u32_e32 v28, 0x80, v126
	v_add_u32_e32 v29, 0x80, v127
	v_add_u32_e32 v30, 0x80, v128
	v_add_u32_e32 v31, 0x80, v129
	v_perm_b32 v32, v29, v28, s78
	v_perm_b32 v33, v31, v30, s78
	v_perm_b32 v26, v29, v28, s79
	v_perm_b32 v27, v31, v30, s79
	v_perm_b32 v40, v27, v26, s60
	v_add_u32_e32 v28, 0x80, v122
	v_add_u32_e32 v29, 0x80, v123
	v_add_u32_e32 v30, 0x80, v124
	v_add_u32_e32 v31, 0x80, v125
	v_perm_b32 v34, v29, v28, s78
	v_perm_b32 v35, v31, v30, s78
	v_perm_b32 v26, v29, v28, s79
	v_perm_b32 v27, v31, v30, s79
	v_perm_b32 v41, v27, v26, s60
	v_mul_f32_e32 v28, v119, v119
	v_mul_f32_e32 v29, v121, v121
	v_mul_f32_e32 v30, v115, v115
	v_mul_f32_e32 v31, v117, v117
	v_fmac_f32_e32 v28, v118, v118
	v_fmac_f32_e32 v29, v120, v120
	v_fmac_f32_e32 v30, v114, v114
	v_fmac_f32_e32 v31, v116, v116
	v_add_f32_e32 v28, v28, v29
	v_add_f32_e32 v30, v30, v31
	v_add_f32_e32 v28, v28, v30
	v_add_f32_e32 v151, v151, v28
	v_add_u32_e32 v28, 0x80, v118
	v_add_u32_e32 v29, 0x80, v119
	v_add_u32_e32 v30, 0x80, v120
	v_add_u32_e32 v31, 0x80, v121
	v_perm_b32 v36, v29, v28, s78
	v_perm_b32 v37, v31, v30, s78
	v_perm_b32 v26, v29, v28, s79
	v_perm_b32 v27, v31, v30, s79
	v_perm_b32 v146, v27, v26, s60
	v_add_u32_e32 v28, 0x80, v114
	v_add_u32_e32 v29, 0x80, v115
	v_add_u32_e32 v30, 0x80, v116
	v_add_u32_e32 v31, 0x80, v117
	v_perm_b32 v38, v29, v28, s78
	v_perm_b32 v39, v31, v30, s78
	v_perm_b32 v26, v29, v28, s79
	v_perm_b32 v27, v31, v30, s79
	v_perm_b32 v147, v27, v26, s60
	s_mov_b64 vcc, s[66:67]
	v_cndmask_b32_dpp v132, v36, v32, vcc quad_perm:[1,0,3,2] row_mask:0xf bank_mask:0xf
	v_cndmask_b32_dpp v133, v37, v33, vcc quad_perm:[1,0,3,2] row_mask:0xf bank_mask:0xf
	v_cndmask_b32_dpp v134, v38, v34, vcc quad_perm:[1,0,3,2] row_mask:0xf bank_mask:0xf
	v_cndmask_b32_dpp v135, v39, v35, vcc quad_perm:[1,0,3,2] row_mask:0xf bank_mask:0xf
	s_mov_b64 vcc, s[62:63]
	v_cndmask_b32_dpp v36, v32, v36, vcc quad_perm:[1,0,3,2] row_mask:0xf bank_mask:0xf
	v_cndmask_b32_dpp v37, v33, v37, vcc quad_perm:[1,0,3,2] row_mask:0xf bank_mask:0xf
	v_cndmask_b32_dpp v38, v34, v38, vcc quad_perm:[1,0,3,2] row_mask:0xf bank_mask:0xf
	v_cndmask_b32_dpp v39, v35, v39, vcc quad_perm:[1,0,3,2] row_mask:0xf bank_mask:0xf
	s_mov_b64 vcc, s[66:67]
	v_cndmask_b32_dpp v138, v146, v40, vcc quad_perm:[1,0,3,2] row_mask:0xf bank_mask:0xf
	v_cndmask_b32_dpp v139, v147, v41, vcc quad_perm:[1,0,3,2] row_mask:0xf bank_mask:0xf
	s_mov_b64 vcc, s[62:63]
	v_cndmask_b32_dpp v146, v40, v146, vcc quad_perm:[1,0,3,2] row_mask:0xf bank_mask:0xf
	v_cndmask_b32_dpp v147, v41, v147, vcc quad_perm:[1,0,3,2] row_mask:0xf bank_mask:0xf
	s_add_u32 s88, s58, 0x8000
	s_addc_u32 s89, s59, 0
	s_add_u32 s90, s74, 0x4000
	s_addc_u32 s91, s75, 0
	global_store_dwordx4 v149, v[132:135], s[88:89]
	global_store_dwordx4 v149, v[36:39], s[88:89] offset:2048
	global_store_dwordx2 v148, v[138:139], s[90:91]
	global_store_dwordx2 v148, v[146:147], s[90:91] offset:1024
	s_add_u32 s92, s96, 0x8000
	s_addc_u32 s93, s97, 0
	v_pk_mul_f32 v[126:127], v[210:211], v[126:127]
	v_pk_mul_f32 v[128:129], v[212:213], v[128:129]
	v_pk_mul_f32 v[122:123], v[214:215], v[122:123]
	v_pk_mul_f32 v[124:125], v[216:217], v[124:125]
	v_cvt_pk_bf16_f32 v32, v126, v127
	v_cvt_pk_bf16_f32 v33, v128, v129
	v_cvt_pk_bf16_f32 v34, v122, v123
	v_cvt_pk_bf16_f32 v35, v124, v125
	v_pk_mul_f32 v[118:119], v[218:219], v[118:119]
	v_pk_mul_f32 v[120:121], v[220:221], v[120:121]
	v_pk_mul_f32 v[114:115], v[222:223], v[114:115]
	v_pk_mul_f32 v[116:117], v[224:225], v[116:117]
	v_cvt_pk_bf16_f32 v36, v118, v119
	v_cvt_pk_bf16_f32 v37, v120, v121
	v_cvt_pk_bf16_f32 v38, v114, v115
	v_cvt_pk_bf16_f32 v39, v116, v117
	s_mov_b64 vcc, s[66:67]
	v_cndmask_b32_dpp v132, v36, v32, vcc quad_perm:[1,0,3,2] row_mask:0xf bank_mask:0xf
	v_cndmask_b32_dpp v133, v37, v33, vcc quad_perm:[1,0,3,2] row_mask:0xf bank_mask:0xf
	v_cndmask_b32_dpp v134, v38, v34, vcc quad_perm:[1,0,3,2] row_mask:0xf bank_mask:0xf
	v_cndmask_b32_dpp v135, v39, v35, vcc quad_perm:[1,0,3,2] row_mask:0xf bank_mask:0xf
	s_mov_b64 vcc, s[62:63]
	v_cndmask_b32_dpp v36, v32, v36, vcc quad_perm:[1,0,3,2] row_mask:0xf bank_mask:0xf
	v_cndmask_b32_dpp v37, v33, v37, vcc quad_perm:[1,0,3,2] row_mask:0xf bank_mask:0xf
	v_cndmask_b32_dpp v38, v34, v38, vcc quad_perm:[1,0,3,2] row_mask:0xf bank_mask:0xf
	v_cndmask_b32_dpp v39, v35, v39, vcc quad_perm:[1,0,3,2] row_mask:0xf bank_mask:0xf
	global_store_dwordx4 v149, v[132:135], s[92:93]
	global_store_dwordx4 v149, v[36:39], s[92:93] offset:2048
	v_mov_b32_e32 v114, v151
	s_add_u32 s84, s58, 0x18000
	s_addc_u32 s85, s59, 0
	s_add_u32 s86, s74, 0xc000
	s_addc_u32 s87, s75, 0
	global_load_dwordx4 v[116:119], v149, s[84:85]
	global_load_dwordx2 v[120:121], v148, s[86:87]
	global_load_dwordx4 v[122:125], v149, s[84:85] offset:2048
	global_load_dwordx2 v[126:127], v148, s[86:87] offset:1024
	s_waitcnt vmcnt(10)
	s_mov_b64 vcc, s[66:67]
	v_cndmask_b32_dpp v32, v230, v226, vcc quad_perm:[1,0,3,2] row_mask:0xf bank_mask:0xf
	v_cndmask_b32_dpp v33, v231, v227, vcc quad_perm:[1,0,3,2] row_mask:0xf bank_mask:0xf
	v_cndmask_b32_dpp v34, v232, v228, vcc quad_perm:[1,0,3,2] row_mask:0xf bank_mask:0xf
	v_cndmask_b32_dpp v35, v233, v229, vcc quad_perm:[1,0,3,2] row_mask:0xf bank_mask:0xf
	s_mov_b64 vcc, s[62:63]
	v_cndmask_b32_dpp v230, v226, v230, vcc quad_perm:[1,0,3,2] row_mask:0xf bank_mask:0xf
	v_cndmask_b32_dpp v231, v227, v231, vcc quad_perm:[1,0,3,2] row_mask:0xf bank_mask:0xf
	v_cndmask_b32_dpp v232, v228, v232, vcc quad_perm:[1,0,3,2] row_mask:0xf bank_mask:0xf
	v_cndmask_b32_dpp v233, v229, v233, vcc quad_perm:[1,0,3,2] row_mask:0xf bank_mask:0xf
	s_mov_b64 vcc, s[66:67]
	v_cndmask_b32_dpp v36, v152, v144, vcc quad_perm:[1,0,3,2] row_mask:0xf bank_mask:0xf
	v_cndmask_b32_dpp v37, v153, v145, vcc quad_perm:[1,0,3,2] row_mask:0xf bank_mask:0xf
	s_mov_b64 vcc, s[62:63]
	v_cndmask_b32_dpp v152, v144, v152, vcc quad_perm:[1,0,3,2] row_mask:0xf bank_mask:0xf
	v_cndmask_b32_dpp v153, v145, v153, vcc quad_perm:[1,0,3,2] row_mask:0xf bank_mask:0xf
	v_perm_b32 v28, v32, v36, s32
	v_perm_b32 v29, v32, v36, s8
	v_perm_b32 v30, v33, v36, s61
	v_perm_b32 v31, v33, v36, s98
	v_pk_fma_f32 v[110:111], v[110:111], v[176:177], v[28:29]
	v_pk_fma_f32 v[112:113], v[112:113], v[178:179], v[30:31]
	v_perm_b32 v28, v34, v37, s32
	v_perm_b32 v29, v34, v37, s8
	v_perm_b32 v30, v35, v37, s61
	v_perm_b32 v31, v35, v37, s98
	v_pk_fma_f32 v[106:107], v[106:107], v[180:181], v[28:29]
	v_pk_fma_f32 v[108:109], v[108:109], v[182:183], v[30:31]
	v_perm_b32 v28, v230, v152, s32
	v_perm_b32 v29, v230, v152, s8
	v_perm_b32 v30, v231, v152, s61
	v_perm_b32 v31, v231, v152, s98
	v_pk_fma_f32 v[102:103], v[102:103], v[184:185], v[28:29]
	v_pk_fma_f32 v[104:105], v[104:105], v[186:187], v[30:31]
	v_perm_b32 v28, v232, v153, s32
	v_perm_b32 v29, v232, v153, s8
	v_perm_b32 v30, v233, v153, s61
	v_perm_b32 v31, v233, v153, s98
	v_pk_fma_f32 v[98:99], v[98:99], v[188:189], v[28:29]
	v_pk_fma_f32 v[100:101], v[100:101], v[190:191], v[30:31]
	v_mul_f32_e32 v28, v111, v111
	v_mul_f32_e32 v29, v113, v113
	v_mul_f32_e32 v30, v107, v107
	v_mul_f32_e32 v31, v109, v109
	v_fmac_f32_e32 v28, v110, v110
	v_fmac_f32_e32 v29, v112, v112
	v_fmac_f32_e32 v30, v106, v106
	v_fmac_f32_e32 v31, v108, v108
	v_add_f32_e32 v28, v28, v29
	v_add_f32_e32 v30, v30, v31
	v_add_f32_e32 v151, v28, v30
	v_add_u32_e32 v28, 0x80, v110
	v_add_u32_e32 v29, 0x80, v111
	v_add_u32_e32 v30, 0x80, v112
	v_add_u32_e32 v31, 0x80, v113
	v_perm_b32 v32, v29, v28, s78
	v_perm_b32 v33, v31, v30, s78
	v_perm_b32 v26, v29, v28, s79
	v_perm_b32 v27, v31, v30, s79
	v_perm_b32 v40, v27, v26, s60
	v_add_u32_e32 v28, 0x80, v106
	v_add_u32_e32 v29, 0x80, v107
	v_add_u32_e32 v30, 0x80, v108
	v_add_u32_e32 v31, 0x80, v109
	v_perm_b32 v34, v29, v28, s78
	v_perm_b32 v35, v31, v30, s78
	v_perm_b32 v26, v29, v28, s79
	v_perm_b32 v27, v31, v30, s79
	v_perm_b32 v41, v27, v26, s60
	v_mul_f32_e32 v28, v103, v103
	v_mul_f32_e32 v29, v105, v105
	v_mul_f32_e32 v30, v99, v99
	v_mul_f32_e32 v31, v101, v101
	v_fmac_f32_e32 v28, v102, v102
	v_fmac_f32_e32 v29, v104, v104
	v_fmac_f32_e32 v30, v98, v98
	v_fmac_f32_e32 v31, v100, v100
	v_add_f32_e32 v28, v28, v29
	v_add_f32_e32 v30, v30, v31
	v_add_f32_e32 v28, v28, v30
	v_add_f32_e32 v151, v151, v28
	v_add_u32_e32 v28, 0x80, v102
	v_add_u32_e32 v29, 0x80, v103
	v_add_u32_e32 v30, 0x80, v104
	v_add_u32_e32 v31, 0x80, v105
	v_perm_b32 v36, v29, v28, s78
	v_perm_b32 v37, v31, v30, s78
	v_perm_b32 v26, v29, v28, s79
	v_perm_b32 v27, v31, v30, s79
	v_perm_b32 v146, v27, v26, s60
	v_add_u32_e32 v28, 0x80, v98
	v_add_u32_e32 v29, 0x80, v99
	v_add_u32_e32 v30, 0x80, v100
	v_add_u32_e32 v31, 0x80, v101
	v_perm_b32 v38, v29, v28, s78
	v_perm_b32 v39, v31, v30, s78
	v_perm_b32 v26, v29, v28, s79
	v_perm_b32 v27, v31, v30, s79
	v_perm_b32 v147, v27, v26, s60
	s_mov_b64 vcc, s[66:67]
	v_cndmask_b32_dpp v226, v36, v32, vcc quad_perm:[1,0,3,2] row_mask:0xf bank_mask:0xf
	v_cndmask_b32_dpp v227, v37, v33, vcc quad_perm:[1,0,3,2] row_mask:0xf bank_mask:0xf
	v_cndmask_b32_dpp v228, v38, v34, vcc quad_perm:[1,0,3,2] row_mask:0xf bank_mask:0xf
	v_cndmask_b32_dpp v229, v39, v35, vcc quad_perm:[1,0,3,2] row_mask:0xf bank_mask:0xf
	s_mov_b64 vcc, s[62:63]
	v_cndmask_b32_dpp v36, v32, v36, vcc quad_perm:[1,0,3,2] row_mask:0xf bank_mask:0xf
	v_cndmask_b32_dpp v37, v33, v37, vcc quad_perm:[1,0,3,2] row_mask:0xf bank_mask:0xf
	v_cndmask_b32_dpp v38, v34, v38, vcc quad_perm:[1,0,3,2] row_mask:0xf bank_mask:0xf
	v_cndmask_b32_dpp v39, v35, v39, vcc quad_perm:[1,0,3,2] row_mask:0xf bank_mask:0xf
	s_mov_b64 vcc, s[66:67]
	v_cndmask_b32_dpp v230, v146, v40, vcc quad_perm:[1,0,3,2] row_mask:0xf bank_mask:0xf
	v_cndmask_b32_dpp v231, v147, v41, vcc quad_perm:[1,0,3,2] row_mask:0xf bank_mask:0xf
	s_mov_b64 vcc, s[62:63]
	v_cndmask_b32_dpp v146, v40, v146, vcc quad_perm:[1,0,3,2] row_mask:0xf bank_mask:0xf
	v_cndmask_b32_dpp v147, v41, v147, vcc quad_perm:[1,0,3,2] row_mask:0xf bank_mask:0xf
	s_add_u32 s88, s58, 0x10000
	s_addc_u32 s89, s59, 0
	s_add_u32 s90, s74, 0x8000
	s_addc_u32 s91, s75, 0
	global_store_dwordx4 v149, v[226:229], s[88:89]
	global_store_dwordx4 v149, v[36:39], s[88:89] offset:2048
	global_store_dwordx2 v148, v[230:231], s[90:91]
	global_store_dwordx2 v148, v[146:147], s[90:91] offset:1024
	s_add_u32 s92, s96, 0x10000
	s_addc_u32 s93, s97, 0
	v_pk_mul_f32 v[110:111], v[210:211], v[110:111]
	v_pk_mul_f32 v[112:113], v[212:213], v[112:113]
	v_pk_mul_f32 v[106:107], v[214:215], v[106:107]
	v_pk_mul_f32 v[108:109], v[216:217], v[108:109]
	v_cvt_pk_bf16_f32 v32, v110, v111
	v_cvt_pk_bf16_f32 v33, v112, v113
	v_cvt_pk_bf16_f32 v34, v106, v107
	v_cvt_pk_bf16_f32 v35, v108, v109
	v_pk_mul_f32 v[102:103], v[218:219], v[102:103]
	v_pk_mul_f32 v[104:105], v[220:221], v[104:105]
	v_pk_mul_f32 v[98:99], v[222:223], v[98:99]
	v_pk_mul_f32 v[100:101], v[224:225], v[100:101]
	v_cvt_pk_bf16_f32 v36, v102, v103
	v_cvt_pk_bf16_f32 v37, v104, v105
	v_cvt_pk_bf16_f32 v38, v98, v99
	v_cvt_pk_bf16_f32 v39, v100, v101
	s_mov_b64 vcc, s[66:67]
	v_cndmask_b32_dpp v226, v36, v32, vcc quad_perm:[1,0,3,2] row_mask:0xf bank_mask:0xf
	v_cndmask_b32_dpp v227, v37, v33, vcc quad_perm:[1,0,3,2] row_mask:0xf bank_mask:0xf
	v_cndmask_b32_dpp v228, v38, v34, vcc quad_perm:[1,0,3,2] row_mask:0xf bank_mask:0xf
	v_cndmask_b32_dpp v229, v39, v35, vcc quad_perm:[1,0,3,2] row_mask:0xf bank_mask:0xf
	s_mov_b64 vcc, s[62:63]
	v_cndmask_b32_dpp v36, v32, v36, vcc quad_perm:[1,0,3,2] row_mask:0xf bank_mask:0xf
	v_cndmask_b32_dpp v37, v33, v37, vcc quad_perm:[1,0,3,2] row_mask:0xf bank_mask:0xf
	v_cndmask_b32_dpp v38, v34, v38, vcc quad_perm:[1,0,3,2] row_mask:0xf bank_mask:0xf
	v_cndmask_b32_dpp v39, v35, v39, vcc quad_perm:[1,0,3,2] row_mask:0xf bank_mask:0xf
	global_store_dwordx4 v149, v[226:229], s[92:93]
	global_store_dwordx4 v149, v[36:39], s[92:93] offset:2048
	v_mov_b32_e32 v98, v151
	s_add_u32 s84, s58, 0x40000
	s_addc_u32 s85, s59, 0
	s_add_u32 s86, s74, 0x20000
	s_addc_u32 s87, s75, 0
	global_load_dwordx4 v[100:103], v149, s[84:85]
	global_load_dwordx2 v[104:105], v148, s[86:87]
	global_load_dwordx4 v[106:109], v149, s[84:85] offset:2048
	global_load_dwordx2 v[110:111], v148, s[86:87] offset:1024
	s_waitcnt vmcnt(10)
	s_mov_b64 vcc, s[66:67]
	v_cndmask_b32_dpp v32, v122, v116, vcc quad_perm:[1,0,3,2] row_mask:0xf bank_mask:0xf
	v_cndmask_b32_dpp v33, v123, v117, vcc quad_perm:[1,0,3,2] row_mask:0xf bank_mask:0xf
	v_cndmask_b32_dpp v34, v124, v118, vcc quad_perm:[1,0,3,2] row_mask:0xf bank_mask:0xf
	v_cndmask_b32_dpp v35, v125, v119, vcc quad_perm:[1,0,3,2] row_mask:0xf bank_mask:0xf
	s_mov_b64 vcc, s[62:63]
	v_cndmask_b32_dpp v122, v116, v122, vcc quad_perm:[1,0,3,2] row_mask:0xf bank_mask:0xf
	v_cndmask_b32_dpp v123, v117, v123, vcc quad_perm:[1,0,3,2] row_mask:0xf bank_mask:0xf
	v_cndmask_b32_dpp v124, v118, v124, vcc quad_perm:[1,0,3,2] row_mask:0xf bank_mask:0xf
	v_cndmask_b32_dpp v125, v119, v125, vcc quad_perm:[1,0,3,2] row_mask:0xf bank_mask:0xf
	s_mov_b64 vcc, s[66:67]
	v_cndmask_b32_dpp v36, v126, v120, vcc quad_perm:[1,0,3,2] row_mask:0xf bank_mask:0xf
	v_cndmask_b32_dpp v37, v127, v121, vcc quad_perm:[1,0,3,2] row_mask:0xf bank_mask:0xf
	s_mov_b64 vcc, s[62:63]
	v_cndmask_b32_dpp v126, v120, v126, vcc quad_perm:[1,0,3,2] row_mask:0xf bank_mask:0xf
	v_cndmask_b32_dpp v127, v121, v127, vcc quad_perm:[1,0,3,2] row_mask:0xf bank_mask:0xf
	v_perm_b32 v28, v32, v36, s32
	v_perm_b32 v29, v32, v36, s8
	v_perm_b32 v30, v33, v36, s61
	v_perm_b32 v31, v33, v36, s98
	v_pk_fma_f32 v[94:95], v[94:95], v[176:177], v[28:29]
	v_pk_fma_f32 v[96:97], v[96:97], v[178:179], v[30:31]
	v_perm_b32 v28, v34, v37, s32
	v_perm_b32 v29, v34, v37, s8
	v_perm_b32 v30, v35, v37, s61
	v_perm_b32 v31, v35, v37, s98
	v_pk_fma_f32 v[90:91], v[90:91], v[180:181], v[28:29]
	v_pk_fma_f32 v[92:93], v[92:93], v[182:183], v[30:31]
	v_perm_b32 v28, v122, v126, s32
	v_perm_b32 v29, v122, v126, s8
	v_perm_b32 v30, v123, v126, s61
	v_perm_b32 v31, v123, v126, s98
	v_pk_fma_f32 v[86:87], v[86:87], v[184:185], v[28:29]
	v_pk_fma_f32 v[88:89], v[88:89], v[186:187], v[30:31]
	v_perm_b32 v28, v124, v127, s32
	v_perm_b32 v29, v124, v127, s8
	v_perm_b32 v30, v125, v127, s61
	v_perm_b32 v31, v125, v127, s98
	v_pk_fma_f32 v[82:83], v[82:83], v[188:189], v[28:29]
	v_pk_fma_f32 v[84:85], v[84:85], v[190:191], v[30:31]
	v_mul_f32_e32 v28, v95, v95
	v_mul_f32_e32 v29, v97, v97
	v_mul_f32_e32 v30, v91, v91
	v_mul_f32_e32 v31, v93, v93
	v_fmac_f32_e32 v28, v94, v94
	v_fmac_f32_e32 v29, v96, v96
	v_fmac_f32_e32 v30, v90, v90
	v_fmac_f32_e32 v31, v92, v92
	v_add_f32_e32 v28, v28, v29
	v_add_f32_e32 v30, v30, v31
	v_add_f32_e32 v151, v28, v30
	v_add_u32_e32 v28, 0x80, v94
	v_add_u32_e32 v29, 0x80, v95
	v_add_u32_e32 v30, 0x80, v96
	v_add_u32_e32 v31, 0x80, v97
	v_perm_b32 v32, v29, v28, s78
	v_perm_b32 v33, v31, v30, s78
	v_perm_b32 v26, v29, v28, s79
	v_perm_b32 v27, v31, v30, s79
	v_perm_b32 v40, v27, v26, s60
	v_add_u32_e32 v28, 0x80, v90
	v_add_u32_e32 v29, 0x80, v91
	v_add_u32_e32 v30, 0x80, v92
	v_add_u32_e32 v31, 0x80, v93
	v_perm_b32 v34, v29, v28, s78
	v_perm_b32 v35, v31, v30, s78
	v_perm_b32 v26, v29, v28, s79
	v_perm_b32 v27, v31, v30, s79
	v_perm_b32 v41, v27, v26, s60
	v_mul_f32_e32 v28, v87, v87
	v_mul_f32_e32 v29, v89, v89
	v_mul_f32_e32 v30, v83, v83
	v_mul_f32_e32 v31, v85, v85
	v_fmac_f32_e32 v28, v86, v86
	v_fmac_f32_e32 v29, v88, v88
	v_fmac_f32_e32 v30, v82, v82
	v_fmac_f32_e32 v31, v84, v84
	v_add_f32_e32 v28, v28, v29
	v_add_f32_e32 v30, v30, v31
	v_add_f32_e32 v28, v28, v30
	v_add_f32_e32 v151, v151, v28
	v_add_u32_e32 v28, 0x80, v86
	v_add_u32_e32 v29, 0x80, v87
	v_add_u32_e32 v30, 0x80, v88
	v_add_u32_e32 v31, 0x80, v89
	v_perm_b32 v36, v29, v28, s78
	v_perm_b32 v37, v31, v30, s78
	v_perm_b32 v26, v29, v28, s79
	v_perm_b32 v27, v31, v30, s79
	v_perm_b32 v146, v27, v26, s60
	v_add_u32_e32 v28, 0x80, v82
	v_add_u32_e32 v29, 0x80, v83
	v_add_u32_e32 v30, 0x80, v84
	v_add_u32_e32 v31, 0x80, v85
	v_perm_b32 v38, v29, v28, s78
	v_perm_b32 v39, v31, v30, s78
	v_perm_b32 v26, v29, v28, s79
	v_perm_b32 v27, v31, v30, s79
	v_perm_b32 v147, v27, v26, s60
	s_mov_b64 vcc, s[66:67]
	v_cndmask_b32_dpp v116, v36, v32, vcc quad_perm:[1,0,3,2] row_mask:0xf bank_mask:0xf
	v_cndmask_b32_dpp v117, v37, v33, vcc quad_perm:[1,0,3,2] row_mask:0xf bank_mask:0xf
	v_cndmask_b32_dpp v118, v38, v34, vcc quad_perm:[1,0,3,2] row_mask:0xf bank_mask:0xf
	v_cndmask_b32_dpp v119, v39, v35, vcc quad_perm:[1,0,3,2] row_mask:0xf bank_mask:0xf
	s_mov_b64 vcc, s[62:63]
	v_cndmask_b32_dpp v36, v32, v36, vcc quad_perm:[1,0,3,2] row_mask:0xf bank_mask:0xf
	v_cndmask_b32_dpp v37, v33, v37, vcc quad_perm:[1,0,3,2] row_mask:0xf bank_mask:0xf
	v_cndmask_b32_dpp v38, v34, v38, vcc quad_perm:[1,0,3,2] row_mask:0xf bank_mask:0xf
	v_cndmask_b32_dpp v39, v35, v39, vcc quad_perm:[1,0,3,2] row_mask:0xf bank_mask:0xf
	s_mov_b64 vcc, s[66:67]
	v_cndmask_b32_dpp v122, v146, v40, vcc quad_perm:[1,0,3,2] row_mask:0xf bank_mask:0xf
	v_cndmask_b32_dpp v123, v147, v41, vcc quad_perm:[1,0,3,2] row_mask:0xf bank_mask:0xf
	s_mov_b64 vcc, s[62:63]
	v_cndmask_b32_dpp v146, v40, v146, vcc quad_perm:[1,0,3,2] row_mask:0xf bank_mask:0xf
	v_cndmask_b32_dpp v147, v41, v147, vcc quad_perm:[1,0,3,2] row_mask:0xf bank_mask:0xf
	s_add_u32 s88, s58, 0x18000
	s_addc_u32 s89, s59, 0
	s_add_u32 s90, s74, 0xc000
	s_addc_u32 s91, s75, 0
	global_store_dwordx4 v149, v[116:119], s[88:89]
	global_store_dwordx4 v149, v[36:39], s[88:89] offset:2048
	global_store_dwordx2 v148, v[122:123], s[90:91]
	global_store_dwordx2 v148, v[146:147], s[90:91] offset:1024
	s_add_u32 s92, s96, 0x18000
	s_addc_u32 s93, s97, 0
	v_pk_mul_f32 v[94:95], v[210:211], v[94:95]
	v_pk_mul_f32 v[96:97], v[212:213], v[96:97]
	v_pk_mul_f32 v[90:91], v[214:215], v[90:91]
	v_pk_mul_f32 v[92:93], v[216:217], v[92:93]
	v_cvt_pk_bf16_f32 v32, v94, v95
	v_cvt_pk_bf16_f32 v33, v96, v97
	v_cvt_pk_bf16_f32 v34, v90, v91
	v_cvt_pk_bf16_f32 v35, v92, v93
	v_pk_mul_f32 v[86:87], v[218:219], v[86:87]
	v_pk_mul_f32 v[88:89], v[220:221], v[88:89]
	v_pk_mul_f32 v[82:83], v[222:223], v[82:83]
	v_pk_mul_f32 v[84:85], v[224:225], v[84:85]
	v_cvt_pk_bf16_f32 v36, v86, v87
	v_cvt_pk_bf16_f32 v37, v88, v89
	v_cvt_pk_bf16_f32 v38, v82, v83
	v_cvt_pk_bf16_f32 v39, v84, v85
	s_mov_b64 vcc, s[66:67]
	v_cndmask_b32_dpp v116, v36, v32, vcc quad_perm:[1,0,3,2] row_mask:0xf bank_mask:0xf
	v_cndmask_b32_dpp v117, v37, v33, vcc quad_perm:[1,0,3,2] row_mask:0xf bank_mask:0xf
	v_cndmask_b32_dpp v118, v38, v34, vcc quad_perm:[1,0,3,2] row_mask:0xf bank_mask:0xf
	v_cndmask_b32_dpp v119, v39, v35, vcc quad_perm:[1,0,3,2] row_mask:0xf bank_mask:0xf
	s_mov_b64 vcc, s[62:63]
	v_cndmask_b32_dpp v36, v32, v36, vcc quad_perm:[1,0,3,2] row_mask:0xf bank_mask:0xf
	v_cndmask_b32_dpp v37, v33, v37, vcc quad_perm:[1,0,3,2] row_mask:0xf bank_mask:0xf
	v_cndmask_b32_dpp v38, v34, v38, vcc quad_perm:[1,0,3,2] row_mask:0xf bank_mask:0xf
	v_cndmask_b32_dpp v39, v35, v39, vcc quad_perm:[1,0,3,2] row_mask:0xf bank_mask:0xf
	global_store_dwordx4 v149, v[116:119], s[92:93]
	global_store_dwordx4 v149, v[36:39], s[92:93] offset:2048
	v_mov_b32_e32 v82, v151
	s_add_u32 s84, s58, 0x48000
	s_addc_u32 s85, s59, 0
	s_add_u32 s86, s74, 0x24000
	s_addc_u32 s87, s75, 0
	global_load_dwordx4 v[84:87], v149, s[84:85]
	global_load_dwordx2 v[88:89], v148, s[86:87]
	global_load_dwordx4 v[90:93], v149, s[84:85] offset:2048
	global_load_dwordx2 v[94:95], v148, s[86:87] offset:1024
	s_waitcnt vmcnt(10)
	s_mov_b64 vcc, s[66:67]
	v_cndmask_b32_dpp v32, v106, v100, vcc quad_perm:[1,0,3,2] row_mask:0xf bank_mask:0xf
	v_cndmask_b32_dpp v33, v107, v101, vcc quad_perm:[1,0,3,2] row_mask:0xf bank_mask:0xf
	v_cndmask_b32_dpp v34, v108, v102, vcc quad_perm:[1,0,3,2] row_mask:0xf bank_mask:0xf
	v_cndmask_b32_dpp v35, v109, v103, vcc quad_perm:[1,0,3,2] row_mask:0xf bank_mask:0xf
	s_mov_b64 vcc, s[62:63]
	v_cndmask_b32_dpp v106, v100, v106, vcc quad_perm:[1,0,3,2] row_mask:0xf bank_mask:0xf
	v_cndmask_b32_dpp v107, v101, v107, vcc quad_perm:[1,0,3,2] row_mask:0xf bank_mask:0xf
	v_cndmask_b32_dpp v108, v102, v108, vcc quad_perm:[1,0,3,2] row_mask:0xf bank_mask:0xf
	v_cndmask_b32_dpp v109, v103, v109, vcc quad_perm:[1,0,3,2] row_mask:0xf bank_mask:0xf
	s_mov_b64 vcc, s[66:67]
	v_cndmask_b32_dpp v36, v110, v104, vcc quad_perm:[1,0,3,2] row_mask:0xf bank_mask:0xf
	v_cndmask_b32_dpp v37, v111, v105, vcc quad_perm:[1,0,3,2] row_mask:0xf bank_mask:0xf
	s_mov_b64 vcc, s[62:63]
	v_cndmask_b32_dpp v110, v104, v110, vcc quad_perm:[1,0,3,2] row_mask:0xf bank_mask:0xf
	v_cndmask_b32_dpp v111, v105, v111, vcc quad_perm:[1,0,3,2] row_mask:0xf bank_mask:0xf
	v_perm_b32 v28, v32, v36, s32
	v_perm_b32 v29, v32, v36, s8
	v_perm_b32 v30, v33, v36, s61
	v_perm_b32 v31, v33, v36, s98
	v_pk_fma_f32 v[78:79], v[78:79], v[176:177], v[28:29]
	v_pk_fma_f32 v[80:81], v[80:81], v[178:179], v[30:31]
	v_perm_b32 v28, v34, v37, s32
	v_perm_b32 v29, v34, v37, s8
	v_perm_b32 v30, v35, v37, s61
	v_perm_b32 v31, v35, v37, s98
	v_pk_fma_f32 v[74:75], v[74:75], v[180:181], v[28:29]
	v_pk_fma_f32 v[76:77], v[76:77], v[182:183], v[30:31]
	v_perm_b32 v28, v106, v110, s32
	v_perm_b32 v29, v106, v110, s8
	v_perm_b32 v30, v107, v110, s61
	v_perm_b32 v31, v107, v110, s98
	v_pk_fma_f32 v[70:71], v[70:71], v[184:185], v[28:29]
	v_pk_fma_f32 v[72:73], v[72:73], v[186:187], v[30:31]
	v_perm_b32 v28, v108, v111, s32
	v_perm_b32 v29, v108, v111, s8
	v_perm_b32 v30, v109, v111, s61
	v_perm_b32 v31, v109, v111, s98
	v_pk_fma_f32 v[66:67], v[66:67], v[188:189], v[28:29]
	v_pk_fma_f32 v[68:69], v[68:69], v[190:191], v[30:31]
	v_mul_f32_e32 v28, v79, v79
	v_mul_f32_e32 v29, v81, v81
	v_mul_f32_e32 v30, v75, v75
	v_mul_f32_e32 v31, v77, v77
	v_fmac_f32_e32 v28, v78, v78
	v_fmac_f32_e32 v29, v80, v80
	v_fmac_f32_e32 v30, v74, v74
	v_fmac_f32_e32 v31, v76, v76
	v_add_f32_e32 v28, v28, v29
	v_add_f32_e32 v30, v30, v31
	v_add_f32_e32 v151, v28, v30
	v_add_u32_e32 v28, 0x80, v78
	v_add_u32_e32 v29, 0x80, v79
	v_add_u32_e32 v30, 0x80, v80
	v_add_u32_e32 v31, 0x80, v81
	v_perm_b32 v32, v29, v28, s78
	v_perm_b32 v33, v31, v30, s78
	v_perm_b32 v26, v29, v28, s79
	v_perm_b32 v27, v31, v30, s79
	v_perm_b32 v40, v27, v26, s60
	v_add_u32_e32 v28, 0x80, v74
	v_add_u32_e32 v29, 0x80, v75
	v_add_u32_e32 v30, 0x80, v76
	v_add_u32_e32 v31, 0x80, v77
	v_perm_b32 v34, v29, v28, s78
	v_perm_b32 v35, v31, v30, s78
	v_perm_b32 v26, v29, v28, s79
	v_perm_b32 v27, v31, v30, s79
	v_perm_b32 v41, v27, v26, s60
	v_mul_f32_e32 v28, v71, v71
	v_mul_f32_e32 v29, v73, v73
	v_mul_f32_e32 v30, v67, v67
	v_mul_f32_e32 v31, v69, v69
	v_fmac_f32_e32 v28, v70, v70
	v_fmac_f32_e32 v29, v72, v72
	v_fmac_f32_e32 v30, v66, v66
	v_fmac_f32_e32 v31, v68, v68
	v_add_f32_e32 v28, v28, v29
	v_add_f32_e32 v30, v30, v31
	v_add_f32_e32 v28, v28, v30
	v_add_f32_e32 v151, v151, v28
	v_add_u32_e32 v28, 0x80, v70
	v_add_u32_e32 v29, 0x80, v71
	v_add_u32_e32 v30, 0x80, v72
	v_add_u32_e32 v31, 0x80, v73
	v_perm_b32 v36, v29, v28, s78
	v_perm_b32 v37, v31, v30, s78
	v_perm_b32 v26, v29, v28, s79
	v_perm_b32 v27, v31, v30, s79
	v_perm_b32 v146, v27, v26, s60
	v_add_u32_e32 v28, 0x80, v66
	v_add_u32_e32 v29, 0x80, v67
	v_add_u32_e32 v30, 0x80, v68
	v_add_u32_e32 v31, 0x80, v69
	v_perm_b32 v38, v29, v28, s78
	v_perm_b32 v39, v31, v30, s78
	v_perm_b32 v26, v29, v28, s79
	v_perm_b32 v27, v31, v30, s79
	v_perm_b32 v147, v27, v26, s60
	s_mov_b64 vcc, s[66:67]
	v_cndmask_b32_dpp v100, v36, v32, vcc quad_perm:[1,0,3,2] row_mask:0xf bank_mask:0xf
	v_cndmask_b32_dpp v101, v37, v33, vcc quad_perm:[1,0,3,2] row_mask:0xf bank_mask:0xf
	v_cndmask_b32_dpp v102, v38, v34, vcc quad_perm:[1,0,3,2] row_mask:0xf bank_mask:0xf
	v_cndmask_b32_dpp v103, v39, v35, vcc quad_perm:[1,0,3,2] row_mask:0xf bank_mask:0xf
	s_mov_b64 vcc, s[62:63]
	v_cndmask_b32_dpp v36, v32, v36, vcc quad_perm:[1,0,3,2] row_mask:0xf bank_mask:0xf
	v_cndmask_b32_dpp v37, v33, v37, vcc quad_perm:[1,0,3,2] row_mask:0xf bank_mask:0xf
	v_cndmask_b32_dpp v38, v34, v38, vcc quad_perm:[1,0,3,2] row_mask:0xf bank_mask:0xf
	v_cndmask_b32_dpp v39, v35, v39, vcc quad_perm:[1,0,3,2] row_mask:0xf bank_mask:0xf
	s_mov_b64 vcc, s[66:67]
	v_cndmask_b32_dpp v106, v146, v40, vcc quad_perm:[1,0,3,2] row_mask:0xf bank_mask:0xf
	v_cndmask_b32_dpp v107, v147, v41, vcc quad_perm:[1,0,3,2] row_mask:0xf bank_mask:0xf
	s_mov_b64 vcc, s[62:63]
	v_cndmask_b32_dpp v146, v40, v146, vcc quad_perm:[1,0,3,2] row_mask:0xf bank_mask:0xf
	v_cndmask_b32_dpp v147, v41, v147, vcc quad_perm:[1,0,3,2] row_mask:0xf bank_mask:0xf
	s_add_u32 s88, s58, 0x40000
	s_addc_u32 s89, s59, 0
	s_add_u32 s90, s74, 0x20000
	s_addc_u32 s91, s75, 0
	global_store_dwordx4 v149, v[100:103], s[88:89]
	global_store_dwordx4 v149, v[36:39], s[88:89] offset:2048
	global_store_dwordx2 v148, v[106:107], s[90:91]
	global_store_dwordx2 v148, v[146:147], s[90:91] offset:1024
	s_add_u32 s92, s96, 0x40000
	s_addc_u32 s93, s97, 0
	v_pk_mul_f32 v[78:79], v[210:211], v[78:79]
	v_pk_mul_f32 v[80:81], v[212:213], v[80:81]
	v_pk_mul_f32 v[74:75], v[214:215], v[74:75]
	v_pk_mul_f32 v[76:77], v[216:217], v[76:77]
	v_cvt_pk_bf16_f32 v32, v78, v79
	v_cvt_pk_bf16_f32 v33, v80, v81
	v_cvt_pk_bf16_f32 v34, v74, v75
	v_cvt_pk_bf16_f32 v35, v76, v77
	v_pk_mul_f32 v[70:71], v[218:219], v[70:71]
	v_pk_mul_f32 v[72:73], v[220:221], v[72:73]
	v_pk_mul_f32 v[66:67], v[222:223], v[66:67]
	v_pk_mul_f32 v[68:69], v[224:225], v[68:69]
	v_cvt_pk_bf16_f32 v36, v70, v71
	v_cvt_pk_bf16_f32 v37, v72, v73
	v_cvt_pk_bf16_f32 v38, v66, v67
	v_cvt_pk_bf16_f32 v39, v68, v69
	s_mov_b64 vcc, s[66:67]
	v_cndmask_b32_dpp v100, v36, v32, vcc quad_perm:[1,0,3,2] row_mask:0xf bank_mask:0xf
	v_cndmask_b32_dpp v101, v37, v33, vcc quad_perm:[1,0,3,2] row_mask:0xf bank_mask:0xf
	v_cndmask_b32_dpp v102, v38, v34, vcc quad_perm:[1,0,3,2] row_mask:0xf bank_mask:0xf
	v_cndmask_b32_dpp v103, v39, v35, vcc quad_perm:[1,0,3,2] row_mask:0xf bank_mask:0xf
	s_mov_b64 vcc, s[62:63]
	v_cndmask_b32_dpp v36, v32, v36, vcc quad_perm:[1,0,3,2] row_mask:0xf bank_mask:0xf
	v_cndmask_b32_dpp v37, v33, v37, vcc quad_perm:[1,0,3,2] row_mask:0xf bank_mask:0xf
	v_cndmask_b32_dpp v38, v34, v38, vcc quad_perm:[1,0,3,2] row_mask:0xf bank_mask:0xf
	v_cndmask_b32_dpp v39, v35, v39, vcc quad_perm:[1,0,3,2] row_mask:0xf bank_mask:0xf
	global_store_dwordx4 v149, v[100:103], s[92:93]
	global_store_dwordx4 v149, v[36:39], s[92:93] offset:2048
	v_mov_b32_e32 v66, v151
	s_add_u32 s84, s58, 0x50000
	s_addc_u32 s85, s59, 0
	s_add_u32 s86, s74, 0x28000
	s_addc_u32 s87, s75, 0
	global_load_dwordx4 v[68:71], v149, s[84:85]
	global_load_dwordx2 v[72:73], v148, s[86:87]
	global_load_dwordx4 v[74:77], v149, s[84:85] offset:2048
	global_load_dwordx2 v[78:79], v148, s[86:87] offset:1024
	s_waitcnt vmcnt(10)
	s_mov_b64 vcc, s[66:67]
	v_cndmask_b32_dpp v32, v90, v84, vcc quad_perm:[1,0,3,2] row_mask:0xf bank_mask:0xf
	v_cndmask_b32_dpp v33, v91, v85, vcc quad_perm:[1,0,3,2] row_mask:0xf bank_mask:0xf
	v_cndmask_b32_dpp v34, v92, v86, vcc quad_perm:[1,0,3,2] row_mask:0xf bank_mask:0xf
	v_cndmask_b32_dpp v35, v93, v87, vcc quad_perm:[1,0,3,2] row_mask:0xf bank_mask:0xf
	s_mov_b64 vcc, s[62:63]
	v_cndmask_b32_dpp v90, v84, v90, vcc quad_perm:[1,0,3,2] row_mask:0xf bank_mask:0xf
	v_cndmask_b32_dpp v91, v85, v91, vcc quad_perm:[1,0,3,2] row_mask:0xf bank_mask:0xf
	v_cndmask_b32_dpp v92, v86, v92, vcc quad_perm:[1,0,3,2] row_mask:0xf bank_mask:0xf
	v_cndmask_b32_dpp v93, v87, v93, vcc quad_perm:[1,0,3,2] row_mask:0xf bank_mask:0xf
	s_mov_b64 vcc, s[66:67]
	v_cndmask_b32_dpp v36, v94, v88, vcc quad_perm:[1,0,3,2] row_mask:0xf bank_mask:0xf
	v_cndmask_b32_dpp v37, v95, v89, vcc quad_perm:[1,0,3,2] row_mask:0xf bank_mask:0xf
	s_mov_b64 vcc, s[62:63]
	v_cndmask_b32_dpp v94, v88, v94, vcc quad_perm:[1,0,3,2] row_mask:0xf bank_mask:0xf
	v_cndmask_b32_dpp v95, v89, v95, vcc quad_perm:[1,0,3,2] row_mask:0xf bank_mask:0xf
	v_perm_b32 v28, v32, v36, s32
	v_perm_b32 v29, v32, v36, s8
	v_perm_b32 v30, v33, v36, s61
	v_perm_b32 v31, v33, v36, s98
	v_pk_fma_f32 v[62:63], v[62:63], v[176:177], v[28:29]
	v_pk_fma_f32 v[64:65], v[64:65], v[178:179], v[30:31]
	v_perm_b32 v28, v34, v37, s32
	v_perm_b32 v29, v34, v37, s8
	v_perm_b32 v30, v35, v37, s61
	v_perm_b32 v31, v35, v37, s98
	v_pk_fma_f32 v[58:59], v[58:59], v[180:181], v[28:29]
	v_pk_fma_f32 v[60:61], v[60:61], v[182:183], v[30:31]
	v_perm_b32 v28, v90, v94, s32
	v_perm_b32 v29, v90, v94, s8
	v_perm_b32 v30, v91, v94, s61
	v_perm_b32 v31, v91, v94, s98
	v_pk_fma_f32 v[54:55], v[54:55], v[184:185], v[28:29]
	v_pk_fma_f32 v[56:57], v[56:57], v[186:187], v[30:31]
	v_perm_b32 v28, v92, v95, s32
	v_perm_b32 v29, v92, v95, s8
	v_perm_b32 v30, v93, v95, s61
	v_perm_b32 v31, v93, v95, s98
	v_pk_fma_f32 v[50:51], v[50:51], v[188:189], v[28:29]
	v_pk_fma_f32 v[52:53], v[52:53], v[190:191], v[30:31]
	v_mul_f32_e32 v28, v63, v63
	v_mul_f32_e32 v29, v65, v65
	v_mul_f32_e32 v30, v59, v59
	v_mul_f32_e32 v31, v61, v61
	v_fmac_f32_e32 v28, v62, v62
	v_fmac_f32_e32 v29, v64, v64
	v_fmac_f32_e32 v30, v58, v58
	v_fmac_f32_e32 v31, v60, v60
	v_add_f32_e32 v28, v28, v29
	v_add_f32_e32 v30, v30, v31
	v_add_f32_e32 v151, v28, v30
	v_add_u32_e32 v28, 0x80, v62
	v_add_u32_e32 v29, 0x80, v63
	v_add_u32_e32 v30, 0x80, v64
	v_add_u32_e32 v31, 0x80, v65
	v_perm_b32 v32, v29, v28, s78
	v_perm_b32 v33, v31, v30, s78
	v_perm_b32 v26, v29, v28, s79
	v_perm_b32 v27, v31, v30, s79
	v_perm_b32 v40, v27, v26, s60
	v_add_u32_e32 v28, 0x80, v58
	v_add_u32_e32 v29, 0x80, v59
	v_add_u32_e32 v30, 0x80, v60
	v_add_u32_e32 v31, 0x80, v61
	v_perm_b32 v34, v29, v28, s78
	v_perm_b32 v35, v31, v30, s78
	v_perm_b32 v26, v29, v28, s79
	v_perm_b32 v27, v31, v30, s79
	v_perm_b32 v41, v27, v26, s60
	v_mul_f32_e32 v28, v55, v55
	v_mul_f32_e32 v29, v57, v57
	v_mul_f32_e32 v30, v51, v51
	v_mul_f32_e32 v31, v53, v53
	v_fmac_f32_e32 v28, v54, v54
	v_fmac_f32_e32 v29, v56, v56
	v_fmac_f32_e32 v30, v50, v50
	v_fmac_f32_e32 v31, v52, v52
	v_add_f32_e32 v28, v28, v29
	v_add_f32_e32 v30, v30, v31
	v_add_f32_e32 v28, v28, v30
	v_add_f32_e32 v151, v151, v28
	v_add_u32_e32 v28, 0x80, v54
	v_add_u32_e32 v29, 0x80, v55
	v_add_u32_e32 v30, 0x80, v56
	v_add_u32_e32 v31, 0x80, v57
	v_perm_b32 v36, v29, v28, s78
	v_perm_b32 v37, v31, v30, s78
	v_perm_b32 v26, v29, v28, s79
	v_perm_b32 v27, v31, v30, s79
	v_perm_b32 v146, v27, v26, s60
	v_add_u32_e32 v28, 0x80, v50
	v_add_u32_e32 v29, 0x80, v51
	v_add_u32_e32 v30, 0x80, v52
	v_add_u32_e32 v31, 0x80, v53
	v_perm_b32 v38, v29, v28, s78
	v_perm_b32 v39, v31, v30, s78
	v_perm_b32 v26, v29, v28, s79
	v_perm_b32 v27, v31, v30, s79
	v_perm_b32 v147, v27, v26, s60
	s_mov_b64 vcc, s[66:67]
	v_cndmask_b32_dpp v84, v36, v32, vcc quad_perm:[1,0,3,2] row_mask:0xf bank_mask:0xf
	v_cndmask_b32_dpp v85, v37, v33, vcc quad_perm:[1,0,3,2] row_mask:0xf bank_mask:0xf
	v_cndmask_b32_dpp v86, v38, v34, vcc quad_perm:[1,0,3,2] row_mask:0xf bank_mask:0xf
	v_cndmask_b32_dpp v87, v39, v35, vcc quad_perm:[1,0,3,2] row_mask:0xf bank_mask:0xf
	s_mov_b64 vcc, s[62:63]
	v_cndmask_b32_dpp v36, v32, v36, vcc quad_perm:[1,0,3,2] row_mask:0xf bank_mask:0xf
	v_cndmask_b32_dpp v37, v33, v37, vcc quad_perm:[1,0,3,2] row_mask:0xf bank_mask:0xf
	v_cndmask_b32_dpp v38, v34, v38, vcc quad_perm:[1,0,3,2] row_mask:0xf bank_mask:0xf
	v_cndmask_b32_dpp v39, v35, v39, vcc quad_perm:[1,0,3,2] row_mask:0xf bank_mask:0xf
	s_mov_b64 vcc, s[66:67]
	v_cndmask_b32_dpp v90, v146, v40, vcc quad_perm:[1,0,3,2] row_mask:0xf bank_mask:0xf
	v_cndmask_b32_dpp v91, v147, v41, vcc quad_perm:[1,0,3,2] row_mask:0xf bank_mask:0xf
	s_mov_b64 vcc, s[62:63]
	v_cndmask_b32_dpp v146, v40, v146, vcc quad_perm:[1,0,3,2] row_mask:0xf bank_mask:0xf
	v_cndmask_b32_dpp v147, v41, v147, vcc quad_perm:[1,0,3,2] row_mask:0xf bank_mask:0xf
	s_add_u32 s88, s58, 0x48000
	s_addc_u32 s89, s59, 0
	s_add_u32 s90, s74, 0x24000
	s_addc_u32 s91, s75, 0
	global_store_dwordx4 v149, v[84:87], s[88:89]
	global_store_dwordx4 v149, v[36:39], s[88:89] offset:2048
	global_store_dwordx2 v148, v[90:91], s[90:91]
	global_store_dwordx2 v148, v[146:147], s[90:91] offset:1024
	s_add_u32 s92, s96, 0x48000
	s_addc_u32 s93, s97, 0
	v_pk_mul_f32 v[62:63], v[210:211], v[62:63]
	v_pk_mul_f32 v[64:65], v[212:213], v[64:65]
	v_pk_mul_f32 v[58:59], v[214:215], v[58:59]
	v_pk_mul_f32 v[60:61], v[216:217], v[60:61]
	v_cvt_pk_bf16_f32 v32, v62, v63
	v_cvt_pk_bf16_f32 v33, v64, v65
	v_cvt_pk_bf16_f32 v34, v58, v59
	v_cvt_pk_bf16_f32 v35, v60, v61
	v_pk_mul_f32 v[54:55], v[218:219], v[54:55]
	v_pk_mul_f32 v[56:57], v[220:221], v[56:57]
	v_pk_mul_f32 v[50:51], v[222:223], v[50:51]
	v_pk_mul_f32 v[52:53], v[224:225], v[52:53]
	v_cvt_pk_bf16_f32 v36, v54, v55
	v_cvt_pk_bf16_f32 v37, v56, v57
	v_cvt_pk_bf16_f32 v38, v50, v51
	v_cvt_pk_bf16_f32 v39, v52, v53
	s_mov_b64 vcc, s[66:67]
	v_cndmask_b32_dpp v84, v36, v32, vcc quad_perm:[1,0,3,2] row_mask:0xf bank_mask:0xf
	v_cndmask_b32_dpp v85, v37, v33, vcc quad_perm:[1,0,3,2] row_mask:0xf bank_mask:0xf
	v_cndmask_b32_dpp v86, v38, v34, vcc quad_perm:[1,0,3,2] row_mask:0xf bank_mask:0xf
	v_cndmask_b32_dpp v87, v39, v35, vcc quad_perm:[1,0,3,2] row_mask:0xf bank_mask:0xf
	s_mov_b64 vcc, s[62:63]
	v_cndmask_b32_dpp v36, v32, v36, vcc quad_perm:[1,0,3,2] row_mask:0xf bank_mask:0xf
	v_cndmask_b32_dpp v37, v33, v37, vcc quad_perm:[1,0,3,2] row_mask:0xf bank_mask:0xf
	v_cndmask_b32_dpp v38, v34, v38, vcc quad_perm:[1,0,3,2] row_mask:0xf bank_mask:0xf
	v_cndmask_b32_dpp v39, v35, v39, vcc quad_perm:[1,0,3,2] row_mask:0xf bank_mask:0xf
	global_store_dwordx4 v149, v[84:87], s[92:93]
	global_store_dwordx4 v149, v[36:39], s[92:93] offset:2048
	v_mov_b32_e32 v50, v151
	s_add_u32 s84, s58, 0x58000
	s_addc_u32 s85, s59, 0
	s_add_u32 s86, s74, 0x2c000
	s_addc_u32 s87, s75, 0
	global_load_dwordx4 v[52:55], v149, s[84:85]
	global_load_dwordx2 v[56:57], v148, s[86:87]
	global_load_dwordx4 v[58:61], v149, s[84:85] offset:2048
	global_load_dwordx2 v[62:63], v148, s[86:87] offset:1024
	s_waitcnt vmcnt(10)
	s_mov_b64 vcc, s[66:67]
	v_cndmask_b32_dpp v32, v74, v68, vcc quad_perm:[1,0,3,2] row_mask:0xf bank_mask:0xf
	v_cndmask_b32_dpp v33, v75, v69, vcc quad_perm:[1,0,3,2] row_mask:0xf bank_mask:0xf
	v_cndmask_b32_dpp v34, v76, v70, vcc quad_perm:[1,0,3,2] row_mask:0xf bank_mask:0xf
	v_cndmask_b32_dpp v35, v77, v71, vcc quad_perm:[1,0,3,2] row_mask:0xf bank_mask:0xf
	s_mov_b64 vcc, s[62:63]
	v_cndmask_b32_dpp v74, v68, v74, vcc quad_perm:[1,0,3,2] row_mask:0xf bank_mask:0xf
	v_cndmask_b32_dpp v75, v69, v75, vcc quad_perm:[1,0,3,2] row_mask:0xf bank_mask:0xf
	v_cndmask_b32_dpp v76, v70, v76, vcc quad_perm:[1,0,3,2] row_mask:0xf bank_mask:0xf
	v_cndmask_b32_dpp v77, v71, v77, vcc quad_perm:[1,0,3,2] row_mask:0xf bank_mask:0xf
	s_mov_b64 vcc, s[66:67]
	v_cndmask_b32_dpp v36, v78, v72, vcc quad_perm:[1,0,3,2] row_mask:0xf bank_mask:0xf
	v_cndmask_b32_dpp v37, v79, v73, vcc quad_perm:[1,0,3,2] row_mask:0xf bank_mask:0xf
	s_mov_b64 vcc, s[62:63]
	v_cndmask_b32_dpp v78, v72, v78, vcc quad_perm:[1,0,3,2] row_mask:0xf bank_mask:0xf
	v_cndmask_b32_dpp v79, v73, v79, vcc quad_perm:[1,0,3,2] row_mask:0xf bank_mask:0xf
	v_perm_b32 v28, v32, v36, s32
	v_perm_b32 v29, v32, v36, s8
	v_perm_b32 v30, v33, v36, s61
	v_perm_b32 v31, v33, v36, s98
	v_pk_fma_f32 v[46:47], v[46:47], v[176:177], v[28:29]
	v_pk_fma_f32 v[48:49], v[48:49], v[178:179], v[30:31]
	v_perm_b32 v28, v34, v37, s32
	v_perm_b32 v29, v34, v37, s8
	v_perm_b32 v30, v35, v37, s61
	v_perm_b32 v31, v35, v37, s98
	v_pk_fma_f32 v[42:43], v[42:43], v[180:181], v[28:29]
	v_pk_fma_f32 v[44:45], v[44:45], v[182:183], v[30:31]
	v_perm_b32 v28, v74, v78, s32
	v_perm_b32 v29, v74, v78, s8
	v_perm_b32 v30, v75, v78, s61
	v_perm_b32 v31, v75, v78, s98
	v_pk_fma_f32 v[22:23], v[22:23], v[184:185], v[28:29]
	v_pk_fma_f32 v[24:25], v[24:25], v[186:187], v[30:31]
	v_perm_b32 v28, v76, v79, s32
	v_perm_b32 v29, v76, v79, s8
	v_perm_b32 v30, v77, v79, s61
	v_perm_b32 v31, v77, v79, s98
	v_pk_fma_f32 v[18:19], v[18:19], v[188:189], v[28:29]
	v_pk_fma_f32 v[20:21], v[20:21], v[190:191], v[30:31]
	v_mul_f32_e32 v28, v47, v47
	v_mul_f32_e32 v29, v49, v49
	v_mul_f32_e32 v30, v43, v43
	v_mul_f32_e32 v31, v45, v45
	v_fmac_f32_e32 v28, v46, v46
	v_fmac_f32_e32 v29, v48, v48
	v_fmac_f32_e32 v30, v42, v42
	v_fmac_f32_e32 v31, v44, v44
	v_add_f32_e32 v28, v28, v29
	v_add_f32_e32 v30, v30, v31
	v_add_f32_e32 v151, v28, v30
	v_add_u32_e32 v28, 0x80, v46
	v_add_u32_e32 v29, 0x80, v47
	v_add_u32_e32 v30, 0x80, v48
	v_add_u32_e32 v31, 0x80, v49
	v_perm_b32 v32, v29, v28, s78
	v_perm_b32 v33, v31, v30, s78
	v_perm_b32 v26, v29, v28, s79
	v_perm_b32 v27, v31, v30, s79
	v_perm_b32 v40, v27, v26, s60
	v_add_u32_e32 v28, 0x80, v42
	v_add_u32_e32 v29, 0x80, v43
	v_add_u32_e32 v30, 0x80, v44
	v_add_u32_e32 v31, 0x80, v45
	v_perm_b32 v34, v29, v28, s78
	v_perm_b32 v35, v31, v30, s78
	v_perm_b32 v26, v29, v28, s79
	v_perm_b32 v27, v31, v30, s79
	v_perm_b32 v41, v27, v26, s60
	v_mul_f32_e32 v28, v23, v23
	v_mul_f32_e32 v29, v25, v25
	v_mul_f32_e32 v30, v19, v19
	v_mul_f32_e32 v31, v21, v21
	v_fmac_f32_e32 v28, v22, v22
	v_fmac_f32_e32 v29, v24, v24
	v_fmac_f32_e32 v30, v18, v18
	v_fmac_f32_e32 v31, v20, v20
	v_add_f32_e32 v28, v28, v29
	v_add_f32_e32 v30, v30, v31
	v_add_f32_e32 v28, v28, v30
	v_add_f32_e32 v151, v151, v28
	v_add_u32_e32 v28, 0x80, v22
	v_add_u32_e32 v29, 0x80, v23
	v_add_u32_e32 v30, 0x80, v24
	v_add_u32_e32 v31, 0x80, v25
	v_perm_b32 v36, v29, v28, s78
	v_perm_b32 v37, v31, v30, s78
	v_perm_b32 v26, v29, v28, s79
	v_perm_b32 v27, v31, v30, s79
	v_perm_b32 v146, v27, v26, s60
	v_add_u32_e32 v28, 0x80, v18
	v_add_u32_e32 v29, 0x80, v19
	v_add_u32_e32 v30, 0x80, v20
	v_add_u32_e32 v31, 0x80, v21
	v_perm_b32 v38, v29, v28, s78
	v_perm_b32 v39, v31, v30, s78
	v_perm_b32 v26, v29, v28, s79
	v_perm_b32 v27, v31, v30, s79
	v_perm_b32 v147, v27, v26, s60
	s_mov_b64 vcc, s[66:67]
	v_cndmask_b32_dpp v68, v36, v32, vcc quad_perm:[1,0,3,2] row_mask:0xf bank_mask:0xf
	v_cndmask_b32_dpp v69, v37, v33, vcc quad_perm:[1,0,3,2] row_mask:0xf bank_mask:0xf
	v_cndmask_b32_dpp v70, v38, v34, vcc quad_perm:[1,0,3,2] row_mask:0xf bank_mask:0xf
	v_cndmask_b32_dpp v71, v39, v35, vcc quad_perm:[1,0,3,2] row_mask:0xf bank_mask:0xf
	s_mov_b64 vcc, s[62:63]
	v_cndmask_b32_dpp v36, v32, v36, vcc quad_perm:[1,0,3,2] row_mask:0xf bank_mask:0xf
	v_cndmask_b32_dpp v37, v33, v37, vcc quad_perm:[1,0,3,2] row_mask:0xf bank_mask:0xf
	v_cndmask_b32_dpp v38, v34, v38, vcc quad_perm:[1,0,3,2] row_mask:0xf bank_mask:0xf
	v_cndmask_b32_dpp v39, v35, v39, vcc quad_perm:[1,0,3,2] row_mask:0xf bank_mask:0xf
	s_mov_b64 vcc, s[66:67]
	v_cndmask_b32_dpp v74, v146, v40, vcc quad_perm:[1,0,3,2] row_mask:0xf bank_mask:0xf
	v_cndmask_b32_dpp v75, v147, v41, vcc quad_perm:[1,0,3,2] row_mask:0xf bank_mask:0xf
	s_mov_b64 vcc, s[62:63]
	v_cndmask_b32_dpp v146, v40, v146, vcc quad_perm:[1,0,3,2] row_mask:0xf bank_mask:0xf
	v_cndmask_b32_dpp v147, v41, v147, vcc quad_perm:[1,0,3,2] row_mask:0xf bank_mask:0xf
	s_add_u32 s88, s58, 0x50000
	s_addc_u32 s89, s59, 0
	s_add_u32 s90, s74, 0x28000
	s_addc_u32 s91, s75, 0
	global_store_dwordx4 v149, v[68:71], s[88:89]
	global_store_dwordx4 v149, v[36:39], s[88:89] offset:2048
	global_store_dwordx2 v148, v[74:75], s[90:91]
	global_store_dwordx2 v148, v[146:147], s[90:91] offset:1024
	s_add_u32 s92, s96, 0x50000
	s_addc_u32 s93, s97, 0
	v_pk_mul_f32 v[46:47], v[210:211], v[46:47]
	v_pk_mul_f32 v[48:49], v[212:213], v[48:49]
	v_pk_mul_f32 v[42:43], v[214:215], v[42:43]
	v_pk_mul_f32 v[44:45], v[216:217], v[44:45]
	v_cvt_pk_bf16_f32 v32, v46, v47
	v_cvt_pk_bf16_f32 v33, v48, v49
	v_cvt_pk_bf16_f32 v34, v42, v43
	v_cvt_pk_bf16_f32 v35, v44, v45
	v_pk_mul_f32 v[22:23], v[218:219], v[22:23]
	v_pk_mul_f32 v[24:25], v[220:221], v[24:25]
	v_pk_mul_f32 v[18:19], v[222:223], v[18:19]
	v_pk_mul_f32 v[20:21], v[224:225], v[20:21]
	v_cvt_pk_bf16_f32 v36, v22, v23
	v_cvt_pk_bf16_f32 v37, v24, v25
	v_cvt_pk_bf16_f32 v38, v18, v19
	v_cvt_pk_bf16_f32 v39, v20, v21
	s_mov_b64 vcc, s[66:67]
	v_cndmask_b32_dpp v68, v36, v32, vcc quad_perm:[1,0,3,2] row_mask:0xf bank_mask:0xf
	v_cndmask_b32_dpp v69, v37, v33, vcc quad_perm:[1,0,3,2] row_mask:0xf bank_mask:0xf
	v_cndmask_b32_dpp v70, v38, v34, vcc quad_perm:[1,0,3,2] row_mask:0xf bank_mask:0xf
	v_cndmask_b32_dpp v71, v39, v35, vcc quad_perm:[1,0,3,2] row_mask:0xf bank_mask:0xf
	s_mov_b64 vcc, s[62:63]
	v_cndmask_b32_dpp v36, v32, v36, vcc quad_perm:[1,0,3,2] row_mask:0xf bank_mask:0xf
	v_cndmask_b32_dpp v37, v33, v37, vcc quad_perm:[1,0,3,2] row_mask:0xf bank_mask:0xf
	v_cndmask_b32_dpp v38, v34, v38, vcc quad_perm:[1,0,3,2] row_mask:0xf bank_mask:0xf
	v_cndmask_b32_dpp v39, v35, v39, vcc quad_perm:[1,0,3,2] row_mask:0xf bank_mask:0xf
	global_store_dwordx4 v149, v[68:71], s[92:93]
	global_store_dwordx4 v149, v[36:39], s[92:93] offset:2048
	v_mov_b32_e32 v18, v151
	s_waitcnt vmcnt(6)
	s_mov_b64 vcc, s[66:67]
	v_cndmask_b32_dpp v32, v58, v52, vcc quad_perm:[1,0,3,2] row_mask:0xf bank_mask:0xf
	v_cndmask_b32_dpp v33, v59, v53, vcc quad_perm:[1,0,3,2] row_mask:0xf bank_mask:0xf
	v_cndmask_b32_dpp v34, v60, v54, vcc quad_perm:[1,0,3,2] row_mask:0xf bank_mask:0xf
	v_cndmask_b32_dpp v35, v61, v55, vcc quad_perm:[1,0,3,2] row_mask:0xf bank_mask:0xf
	s_mov_b64 vcc, s[62:63]
	v_cndmask_b32_dpp v58, v52, v58, vcc quad_perm:[1,0,3,2] row_mask:0xf bank_mask:0xf
	v_cndmask_b32_dpp v59, v53, v59, vcc quad_perm:[1,0,3,2] row_mask:0xf bank_mask:0xf
	v_cndmask_b32_dpp v60, v54, v60, vcc quad_perm:[1,0,3,2] row_mask:0xf bank_mask:0xf
	v_cndmask_b32_dpp v61, v55, v61, vcc quad_perm:[1,0,3,2] row_mask:0xf bank_mask:0xf
	s_mov_b64 vcc, s[66:67]
	v_cndmask_b32_dpp v36, v62, v56, vcc quad_perm:[1,0,3,2] row_mask:0xf bank_mask:0xf
	v_cndmask_b32_dpp v37, v63, v57, vcc quad_perm:[1,0,3,2] row_mask:0xf bank_mask:0xf
	s_mov_b64 vcc, s[62:63]
	v_cndmask_b32_dpp v62, v56, v62, vcc quad_perm:[1,0,3,2] row_mask:0xf bank_mask:0xf
	v_cndmask_b32_dpp v63, v57, v63, vcc quad_perm:[1,0,3,2] row_mask:0xf bank_mask:0xf
	v_perm_b32 v28, v32, v36, s32
	v_perm_b32 v29, v32, v36, s8
	v_perm_b32 v30, v33, v36, s61
	v_perm_b32 v31, v33, v36, s98
	v_pk_fma_f32 v[14:15], v[14:15], v[176:177], v[28:29]
	v_pk_fma_f32 v[16:17], v[16:17], v[178:179], v[30:31]
	v_perm_b32 v28, v34, v37, s32
	v_perm_b32 v29, v34, v37, s8
	v_perm_b32 v30, v35, v37, s61
	v_perm_b32 v31, v35, v37, s98
	v_pk_fma_f32 v[10:11], v[10:11], v[180:181], v[28:29]
	v_pk_fma_f32 v[12:13], v[12:13], v[182:183], v[30:31]
	v_perm_b32 v28, v58, v62, s32
	v_perm_b32 v29, v58, v62, s8
	v_perm_b32 v30, v59, v62, s61
	v_perm_b32 v31, v59, v62, s98
	v_pk_fma_f32 v[6:7], v[6:7], v[184:185], v[28:29]
	v_pk_fma_f32 v[8:9], v[8:9], v[186:187], v[30:31]
	v_perm_b32 v28, v60, v63, s32
	v_perm_b32 v29, v60, v63, s8
	v_perm_b32 v30, v61, v63, s61
	v_perm_b32 v31, v61, v63, s98
	v_pk_fma_f32 v[2:3], v[2:3], v[188:189], v[28:29]
	v_pk_fma_f32 v[4:5], v[4:5], v[190:191], v[30:31]
	v_mul_f32_e32 v28, v15, v15
	v_mul_f32_e32 v29, v17, v17
	v_mul_f32_e32 v30, v11, v11
	v_mul_f32_e32 v31, v13, v13
	v_fmac_f32_e32 v28, v14, v14
	v_fmac_f32_e32 v29, v16, v16
	v_fmac_f32_e32 v30, v10, v10
	v_fmac_f32_e32 v31, v12, v12
	v_add_f32_e32 v28, v28, v29
	v_add_f32_e32 v30, v30, v31
	v_add_f32_e32 v151, v28, v30
	v_add_u32_e32 v28, 0x80, v14
	v_add_u32_e32 v29, 0x80, v15
	v_add_u32_e32 v30, 0x80, v16
	v_add_u32_e32 v31, 0x80, v17
	v_perm_b32 v32, v29, v28, s78
	v_perm_b32 v33, v31, v30, s78
	v_perm_b32 v26, v29, v28, s79
	v_perm_b32 v27, v31, v30, s79
	v_perm_b32 v40, v27, v26, s60
	v_add_u32_e32 v28, 0x80, v10
	v_add_u32_e32 v29, 0x80, v11
	v_add_u32_e32 v30, 0x80, v12
	v_add_u32_e32 v31, 0x80, v13
	v_perm_b32 v34, v29, v28, s78
	v_perm_b32 v35, v31, v30, s78
	v_perm_b32 v26, v29, v28, s79
	v_perm_b32 v27, v31, v30, s79
	v_perm_b32 v41, v27, v26, s60
	v_mul_f32_e32 v28, v7, v7
	v_mul_f32_e32 v29, v9, v9
	v_mul_f32_e32 v30, v3, v3
	v_mul_f32_e32 v31, v5, v5
	v_fmac_f32_e32 v28, v6, v6
	v_fmac_f32_e32 v29, v8, v8
	v_fmac_f32_e32 v30, v2, v2
	v_fmac_f32_e32 v31, v4, v4
	v_add_f32_e32 v28, v28, v29
	v_add_f32_e32 v30, v30, v31
	v_add_f32_e32 v28, v28, v30
	v_add_f32_e32 v151, v151, v28
	v_add_u32_e32 v28, 0x80, v6
	v_add_u32_e32 v29, 0x80, v7
	v_add_u32_e32 v30, 0x80, v8
	v_add_u32_e32 v31, 0x80, v9
	v_perm_b32 v36, v29, v28, s78
	v_perm_b32 v37, v31, v30, s78
	v_perm_b32 v26, v29, v28, s79
	v_perm_b32 v27, v31, v30, s79
	v_perm_b32 v146, v27, v26, s60
	v_add_u32_e32 v28, 0x80, v2
	v_add_u32_e32 v29, 0x80, v3
	v_add_u32_e32 v30, 0x80, v4
	v_add_u32_e32 v31, 0x80, v5
	v_perm_b32 v38, v29, v28, s78
	v_perm_b32 v39, v31, v30, s78
	v_perm_b32 v26, v29, v28, s79
	v_perm_b32 v27, v31, v30, s79
	v_perm_b32 v147, v27, v26, s60
	s_mov_b64 vcc, s[66:67]
	v_cndmask_b32_dpp v52, v36, v32, vcc quad_perm:[1,0,3,2] row_mask:0xf bank_mask:0xf
	v_cndmask_b32_dpp v53, v37, v33, vcc quad_perm:[1,0,3,2] row_mask:0xf bank_mask:0xf
	v_cndmask_b32_dpp v54, v38, v34, vcc quad_perm:[1,0,3,2] row_mask:0xf bank_mask:0xf
	v_cndmask_b32_dpp v55, v39, v35, vcc quad_perm:[1,0,3,2] row_mask:0xf bank_mask:0xf
	s_mov_b64 vcc, s[62:63]
	v_cndmask_b32_dpp v36, v32, v36, vcc quad_perm:[1,0,3,2] row_mask:0xf bank_mask:0xf
	v_cndmask_b32_dpp v37, v33, v37, vcc quad_perm:[1,0,3,2] row_mask:0xf bank_mask:0xf
	v_cndmask_b32_dpp v38, v34, v38, vcc quad_perm:[1,0,3,2] row_mask:0xf bank_mask:0xf
	v_cndmask_b32_dpp v39, v35, v39, vcc quad_perm:[1,0,3,2] row_mask:0xf bank_mask:0xf
	s_mov_b64 vcc, s[66:67]
	v_cndmask_b32_dpp v58, v146, v40, vcc quad_perm:[1,0,3,2] row_mask:0xf bank_mask:0xf
	v_cndmask_b32_dpp v59, v147, v41, vcc quad_perm:[1,0,3,2] row_mask:0xf bank_mask:0xf
	s_mov_b64 vcc, s[62:63]
	v_cndmask_b32_dpp v146, v40, v146, vcc quad_perm:[1,0,3,2] row_mask:0xf bank_mask:0xf
	v_cndmask_b32_dpp v147, v41, v147, vcc quad_perm:[1,0,3,2] row_mask:0xf bank_mask:0xf
	s_add_u32 s88, s58, 0x58000
	s_addc_u32 s89, s59, 0
	s_add_u32 s90, s74, 0x2c000
	s_addc_u32 s91, s75, 0
	global_store_dwordx4 v149, v[52:55], s[88:89]
	global_store_dwordx4 v149, v[36:39], s[88:89] offset:2048
	global_store_dwordx2 v148, v[58:59], s[90:91]
	global_store_dwordx2 v148, v[146:147], s[90:91] offset:1024
	s_add_u32 s92, s96, 0x58000
	s_addc_u32 s93, s97, 0
	v_pk_mul_f32 v[14:15], v[210:211], v[14:15]
	v_pk_mul_f32 v[16:17], v[212:213], v[16:17]
	v_pk_mul_f32 v[10:11], v[214:215], v[10:11]
	v_pk_mul_f32 v[12:13], v[216:217], v[12:13]
	v_cvt_pk_bf16_f32 v32, v14, v15
	v_cvt_pk_bf16_f32 v33, v16, v17
	v_cvt_pk_bf16_f32 v34, v10, v11
	v_cvt_pk_bf16_f32 v35, v12, v13
	v_pk_mul_f32 v[6:7], v[218:219], v[6:7]
	v_pk_mul_f32 v[8:9], v[220:221], v[8:9]
	v_pk_mul_f32 v[2:3], v[222:223], v[2:3]
	v_pk_mul_f32 v[4:5], v[224:225], v[4:5]
	v_cvt_pk_bf16_f32 v36, v6, v7
	v_cvt_pk_bf16_f32 v37, v8, v9
	v_cvt_pk_bf16_f32 v38, v2, v3
	v_cvt_pk_bf16_f32 v39, v4, v5
	s_mov_b64 vcc, s[66:67]
	v_cndmask_b32_dpp v52, v36, v32, vcc quad_perm:[1,0,3,2] row_mask:0xf bank_mask:0xf
	v_cndmask_b32_dpp v53, v37, v33, vcc quad_perm:[1,0,3,2] row_mask:0xf bank_mask:0xf
	v_cndmask_b32_dpp v54, v38, v34, vcc quad_perm:[1,0,3,2] row_mask:0xf bank_mask:0xf
	v_cndmask_b32_dpp v55, v39, v35, vcc quad_perm:[1,0,3,2] row_mask:0xf bank_mask:0xf
	s_mov_b64 vcc, s[62:63]
	v_cndmask_b32_dpp v36, v32, v36, vcc quad_perm:[1,0,3,2] row_mask:0xf bank_mask:0xf
	v_cndmask_b32_dpp v37, v33, v37, vcc quad_perm:[1,0,3,2] row_mask:0xf bank_mask:0xf
	v_cndmask_b32_dpp v38, v34, v38, vcc quad_perm:[1,0,3,2] row_mask:0xf bank_mask:0xf
	v_cndmask_b32_dpp v39, v35, v39, vcc quad_perm:[1,0,3,2] row_mask:0xf bank_mask:0xf
	global_store_dwordx4 v149, v[52:55], s[92:93]
	global_store_dwordx4 v149, v[36:39], s[92:93] offset:2048
	v_mov_b32_e32 v2, v151
	v_mbcnt_lo_u32_b32 v3, -1, 0
	v_mbcnt_hi_u32_b32 v3, -1, v3
	v_xor_b32_e32 v4, 16, v3
	v_xor_b32_e32 v5, 32, v3
	v_lshlrev_b32_e32 v4, 2, v4
	v_lshlrev_b32_e32 v5, 2, v5
	v_cmp_gt_u32_e64 s[34:35], 16, v3
	ds_bpermute_b32 v6, v4, v130
	ds_bpermute_b32 v7, v4, v114
	ds_bpermute_b32 v8, v4, v98
	ds_bpermute_b32 v9, v4, v82
	ds_bpermute_b32 v10, v4, v66
	ds_bpermute_b32 v11, v4, v50
	ds_bpermute_b32 v12, v4, v18
	ds_bpermute_b32 v13, v4, v2
	s_waitcnt lgkmcnt(0)
	v_add_f32_e32 v130, v130, v6
	v_add_f32_e32 v114, v114, v7
	v_add_f32_e32 v98, v98, v8
	v_add_f32_e32 v82, v82, v9
	v_add_f32_e32 v66, v66, v10
	v_add_f32_e32 v50, v50, v11
	v_add_f32_e32 v18, v18, v12
	v_add_f32_e32 v2, v2, v13
	ds_bpermute_b32 v6, v5, v130
	ds_bpermute_b32 v7, v5, v114
	ds_bpermute_b32 v8, v5, v98
	ds_bpermute_b32 v9, v5, v82
	ds_bpermute_b32 v10, v5, v66
	ds_bpermute_b32 v11, v5, v50
	ds_bpermute_b32 v12, v5, v18
	ds_bpermute_b32 v13, v5, v2
	s_waitcnt lgkmcnt(0)
	v_add_f32_e32 v130, v130, v6
	v_add_f32_e32 v114, v114, v7
	v_add_f32_e32 v98, v98, v8
	v_add_f32_e32 v82, v82, v9
	v_add_f32_e32 v66, v66, v10
	v_add_f32_e32 v50, v50, v11
	v_add_f32_e32 v18, v18, v12
	v_add_f32_e32 v2, v2, v13
	v_readlane_b32 s70, v244, 53
	v_readlane_b32 s71, v244, 54
	v_lshlrev_b32_e32 v3, 6, v192
	s_lshl_b32 s94, s55, 14
	s_lshl_b32 s95, s4, 4
	s_add_u32 s94, s94, s95
	s_lshl_b32 s95, s49, 2
	s_add_u32 s94, s94, s95
	s_add_u32 s94, s70, s94
	s_addc_u32 s95, s71, 0
	s_and_saveexec_b64 s[36:37], s[34:35]
	global_store_dword v3, v130, s[94:95]
	s_add_u32 s84, s94, 0x400
	s_addc_u32 s85, s95, 0
	global_store_dword v3, v114, s[84:85]
	s_add_u32 s84, s94, 0x800
	s_addc_u32 s85, s95, 0
	global_store_dword v3, v98, s[84:85]
	s_add_u32 s84, s94, 0xc00
	s_addc_u32 s85, s95, 0
	global_store_dword v3, v82, s[84:85]
	s_add_u32 s84, s94, 0x2000
	s_addc_u32 s85, s95, 0
	global_store_dword v3, v66, s[84:85]
	s_add_u32 s84, s94, 0x2400
	s_addc_u32 s85, s95, 0
	global_store_dword v3, v50, s[84:85]
	s_add_u32 s84, s94, 0x2800
	s_addc_u32 s85, s95, 0
	global_store_dword v3, v18, s[84:85]
	s_add_u32 s84, s94, 0x2c00
	s_addc_u32 s85, s95, 0
	global_store_dword v3, v2, s[84:85]
	s_or_b64 exec, exec, s[36:37]
	v_readlane_b32 s56, v246, 3
	v_readlane_b32 s57, v246, 4
	s_andn2_b64 vcc, exec, s[18:19]
	s_mov_b64 s[12:13], -1
	s_cbranch_vccnz .LBB0_1180
	s_andn2_b64 vcc, exec, s[0:1]
	s_cbranch_vccnz .LBB0_1179
	s_barrier
	s_branch .LBB0_1179

.LBB0_1512:
	s_and_b64 vcc, exec, s[18:19]
	s_cbranch_vccz .Lepi3_nulla1
	s_ashr_i32 s16, s54, 31
	s_lshr_b32 s16, s16, 29
	s_add_i32 s16, s54, s16
	s_ashr_i32 s16, s16, 3
	s_mul_i32 s27, s16, 0x6000
	s_mul_hi_i32 s25, s16, 0x6000
	s_add_u32 s80, s45, s27
	s_addc_u32 s81, s47, s25
	s_add_u32 s82, s49, s27
	s_addc_u32 s83, s50, s25
	s_mov_b32 s62, 0xaaaaaaaa
	s_mov_b32 s63, 0xaaaaaaaa
	s_mov_b32 s66, 0x55555555
	s_mov_b32 s67, 0x55555555
	s_mov_b32 s32, 0x0504000c
	s_mov_b32 s61, 0x0504020c
	s_mov_b32 s98, 0x0706030c
	v_mbcnt_lo_u32_b32 v172, -1, 0
	v_mbcnt_hi_u32_b32 v172, -1, v172
	v_and_b32_e32 v172, 1, v172
	v_and_b32_e32 v171, 0x60, v196
	v_add_u32_e32 v171, v171, v196
	v_lshl_or_b32 v171, s4, 8, v171
	v_lshlrev_b32_e32 v44, 2, v171
	v_lshl_add_u32 v171, v172, 5, v171
	v_lshl_add_u32 v170, s54, 8, v194
	v_sub_u32_e32 v170, v170, v172
	v_lshl_add_u32 v170, v170, 10, v171
	v_lshlrev_b32_e32 v171, 1, v170
	global_load_dwordx4 v[174:177], v44, s[80:81] offset:0
	global_load_dwordx4 v[178:181], v44, s[80:81] offset:16
	global_load_dwordx4 v[190:193], v44, s[20:21] offset:0
	global_load_dwordx4 v[210:213], v44, s[20:21] offset:16
	global_load_dwordx4 v[182:185], v44, s[80:81] offset:128
	global_load_dwordx4 v[186:189], v44, s[80:81] offset:144
	global_load_dwordx4 v[214:217], v44, s[20:21] offset:128
	global_load_dwordx4 v[218:221], v44, s[20:21] offset:144
	global_load_dwordx4 v[222:225], v44, s[82:83] offset:0
	global_load_dwordx4 v[226:229], v44, s[82:83] offset:16
	s_waitcnt vmcnt(0)
	v_pk_add_f32 v[222:223], v[222:223], 1.0 op_sel_hi:[1,0]
	v_pk_add_f32 v[224:225], v[224:225], 1.0 op_sel_hi:[1,0]
	v_pk_add_f32 v[226:227], v[226:227], 1.0 op_sel_hi:[1,0]
	v_pk_add_f32 v[228:229], v[228:229], 1.0 op_sel_hi:[1,0]
	v_pk_mul_f32 v[190:191], v[190:191], v[222:223]
	v_pk_mul_f32 v[192:193], v[192:193], v[224:225]
	v_pk_mul_f32 v[210:211], v[210:211], v[226:227]
	v_pk_mul_f32 v[212:213], v[212:213], v[228:229]
	s_nop 1
	global_load_dwordx4 v[222:225], v44, s[82:83] offset:128
	global_load_dwordx4 v[226:229], v44, s[82:83] offset:144
	s_waitcnt vmcnt(0)
	v_pk_add_f32 v[222:223], v[222:223], 1.0 op_sel_hi:[1,0]
	v_pk_add_f32 v[224:225], v[224:225], 1.0 op_sel_hi:[1,0]
	v_pk_add_f32 v[226:227], v[226:227], 1.0 op_sel_hi:[1,0]
	v_pk_add_f32 v[228:229], v[228:229], 1.0 op_sel_hi:[1,0]
	v_pk_mul_f32 v[214:215], v[214:215], v[222:223]
	v_pk_mul_f32 v[216:217], v[216:217], v[224:225]
	v_pk_mul_f32 v[218:219], v[218:219], v[226:227]
	v_pk_mul_f32 v[220:221], v[220:221], v[228:229]
	s_add_u32 s84, s58, 0x0
	s_addc_u32 s85, s59, 0
	s_add_u32 s86, s74, 0x0
	s_addc_u32 s87, s75, 0
	global_load_dwordx4 v[222:225], v171, s[84:85]
	global_load_dwordx2 v[226:227], v170, s[86:87]
	global_load_dwordx4 v[228:231], v171, s[84:85] offset:2048
	global_load_dwordx2 v[232:233], v170, s[86:87] offset:1024
	s_waitcnt vmcnt(0)
	s_mov_b64 vcc, s[66:67]
	v_cndmask_b32_dpp v48, v228, v222, vcc quad_perm:[1,0,3,2] row_mask:0xf bank_mask:0xf
	v_cndmask_b32_dpp v49, v229, v223, vcc quad_perm:[1,0,3,2] row_mask:0xf bank_mask:0xf
	v_cndmask_b32_dpp v50, v230, v224, vcc quad_perm:[1,0,3,2] row_mask:0xf bank_mask:0xf
	v_cndmask_b32_dpp v51, v231, v225, vcc quad_perm:[1,0,3,2] row_mask:0xf bank_mask:0xf
	s_mov_b64 vcc, s[62:63]
	v_cndmask_b32_dpp v228, v222, v228, vcc quad_perm:[1,0,3,2] row_mask:0xf bank_mask:0xf
	v_cndmask_b32_dpp v229, v223, v229, vcc quad_perm:[1,0,3,2] row_mask:0xf bank_mask:0xf
	v_cndmask_b32_dpp v230, v224, v230, vcc quad_perm:[1,0,3,2] row_mask:0xf bank_mask:0xf
	v_cndmask_b32_dpp v231, v225, v231, vcc quad_perm:[1,0,3,2] row_mask:0xf bank_mask:0xf
	s_mov_b64 vcc, s[66:67]
	v_cndmask_b32_dpp v52, v232, v226, vcc quad_perm:[1,0,3,2] row_mask:0xf bank_mask:0xf
	v_cndmask_b32_dpp v53, v233, v227, vcc quad_perm:[1,0,3,2] row_mask:0xf bank_mask:0xf
	s_mov_b64 vcc, s[62:63]
	v_cndmask_b32_dpp v232, v226, v232, vcc quad_perm:[1,0,3,2] row_mask:0xf bank_mask:0xf
	v_cndmask_b32_dpp v233, v227, v233, vcc quad_perm:[1,0,3,2] row_mask:0xf bank_mask:0xf
	v_perm_b32 v44, v48, v52, s32
	v_perm_b32 v45, v48, v52, s8
	v_perm_b32 v46, v49, v52, s61
	v_perm_b32 v47, v49, v52, s98
	v_pk_fma_f32 v[142:143], v[142:143], v[174:175], v[44:45]
	v_pk_fma_f32 v[144:145], v[144:145], v[176:177], v[46:47]
	v_perm_b32 v44, v50, v53, s32
	v_perm_b32 v45, v50, v53, s8
	v_perm_b32 v46, v51, v53, s61
	v_perm_b32 v47, v51, v53, s98
	v_pk_fma_f32 v[138:139], v[138:139], v[178:179], v[44:45]
	v_pk_fma_f32 v[140:141], v[140:141], v[180:181], v[46:47]
	v_perm_b32 v44, v228, v232, s32
	v_perm_b32 v45, v228, v232, s8
	v_perm_b32 v46, v229, v232, s61
	v_perm_b32 v47, v229, v232, s98
	v_pk_fma_f32 v[134:135], v[134:135], v[182:183], v[44:45]
	v_pk_fma_f32 v[136:137], v[136:137], v[184:185], v[46:47]
	v_perm_b32 v44, v230, v233, s32
	v_perm_b32 v45, v230, v233, s8
	v_perm_b32 v46, v231, v233, s61
	v_perm_b32 v47, v231, v233, s98
	v_pk_fma_f32 v[130:131], v[130:131], v[186:187], v[44:45]
	v_pk_fma_f32 v[132:133], v[132:133], v[188:189], v[46:47]
	v_mul_f32_e32 v44, v143, v143
	v_mul_f32_e32 v45, v145, v145
	v_mul_f32_e32 v46, v139, v139
	v_mul_f32_e32 v47, v141, v141
	v_fmac_f32_e32 v44, v142, v142
	v_fmac_f32_e32 v45, v144, v144
	v_fmac_f32_e32 v46, v138, v138
	v_fmac_f32_e32 v47, v140, v140
	v_add_f32_e32 v44, v44, v45
	v_add_f32_e32 v46, v46, v47
	v_add_f32_e32 v173, v44, v46
	v_add_u32_e32 v44, 0x80, v142
	v_add_u32_e32 v45, 0x80, v143
	v_add_u32_e32 v46, 0x80, v144
	v_add_u32_e32 v47, 0x80, v145
	v_perm_b32 v48, v45, v44, s78
	v_perm_b32 v49, v47, v46, s78
	v_perm_b32 v42, v45, v44, s79
	v_perm_b32 v43, v47, v46, s79
	v_perm_b32 v56, v43, v42, s60
	v_add_u32_e32 v44, 0x80, v138
	v_add_u32_e32 v45, 0x80, v139
	v_add_u32_e32 v46, 0x80, v140
	v_add_u32_e32 v47, 0x80, v141
	v_perm_b32 v50, v45, v44, s78
	v_perm_b32 v51, v47, v46, s78
	v_perm_b32 v42, v45, v44, s79
	v_perm_b32 v43, v47, v46, s79
	v_perm_b32 v57, v43, v42, s60
	v_mul_f32_e32 v44, v135, v135
	v_mul_f32_e32 v45, v137, v137
	v_mul_f32_e32 v46, v131, v131
	v_mul_f32_e32 v47, v133, v133
	v_fmac_f32_e32 v44, v134, v134
	v_fmac_f32_e32 v45, v136, v136
	v_fmac_f32_e32 v46, v130, v130
	v_fmac_f32_e32 v47, v132, v132
	v_add_f32_e32 v44, v44, v45
	v_add_f32_e32 v46, v46, v47
	v_add_f32_e32 v44, v44, v46
	v_add_f32_e32 v173, v173, v44
	v_add_u32_e32 v44, 0x80, v134
	v_add_u32_e32 v45, 0x80, v135
	v_add_u32_e32 v46, 0x80, v136
	v_add_u32_e32 v47, 0x80, v137
	v_perm_b32 v52, v45, v44, s78
	v_perm_b32 v53, v47, v46, s78
	v_perm_b32 v42, v45, v44, s79
	v_perm_b32 v43, v47, v46, s79
	v_perm_b32 v168, v43, v42, s60
	v_add_u32_e32 v44, 0x80, v130
	v_add_u32_e32 v45, 0x80, v131
	v_add_u32_e32 v46, 0x80, v132
	v_add_u32_e32 v47, 0x80, v133
	v_perm_b32 v54, v45, v44, s78
	v_perm_b32 v55, v47, v46, s78
	v_perm_b32 v42, v45, v44, s79
	v_perm_b32 v43, v47, v46, s79
	v_perm_b32 v169, v43, v42, s60
	s_mov_b64 vcc, s[66:67]
	v_cndmask_b32_dpp v222, v52, v48, vcc quad_perm:[1,0,3,2] row_mask:0xf bank_mask:0xf
	v_cndmask_b32_dpp v223, v53, v49, vcc quad_perm:[1,0,3,2] row_mask:0xf bank_mask:0xf
	v_cndmask_b32_dpp v224, v54, v50, vcc quad_perm:[1,0,3,2] row_mask:0xf bank_mask:0xf
	v_cndmask_b32_dpp v225, v55, v51, vcc quad_perm:[1,0,3,2] row_mask:0xf bank_mask:0xf
	s_mov_b64 vcc, s[62:63]
	v_cndmask_b32_dpp v52, v48, v52, vcc quad_perm:[1,0,3,2] row_mask:0xf bank_mask:0xf
	v_cndmask_b32_dpp v53, v49, v53, vcc quad_perm:[1,0,3,2] row_mask:0xf bank_mask:0xf
	v_cndmask_b32_dpp v54, v50, v54, vcc quad_perm:[1,0,3,2] row_mask:0xf bank_mask:0xf
	v_cndmask_b32_dpp v55, v51, v55, vcc quad_perm:[1,0,3,2] row_mask:0xf bank_mask:0xf
	s_mov_b64 vcc, s[66:67]
	v_cndmask_b32_dpp v228, v168, v56, vcc quad_perm:[1,0,3,2] row_mask:0xf bank_mask:0xf
	v_cndmask_b32_dpp v229, v169, v57, vcc quad_perm:[1,0,3,2] row_mask:0xf bank_mask:0xf
	s_mov_b64 vcc, s[62:63]
	v_cndmask_b32_dpp v168, v56, v168, vcc quad_perm:[1,0,3,2] row_mask:0xf bank_mask:0xf
	v_cndmask_b32_dpp v169, v57, v169, vcc quad_perm:[1,0,3,2] row_mask:0xf bank_mask:0xf
	s_add_u32 s88, s58, 0x0
	s_addc_u32 s89, s59, 0
	s_add_u32 s90, s74, 0x0
	s_addc_u32 s91, s75, 0
	global_store_dwordx4 v171, v[222:225], s[88:89]
	global_store_dwordx4 v171, v[52:55], s[88:89] offset:2048
	global_store_dwordx2 v170, v[228:229], s[90:91]
	global_store_dwordx2 v170, v[168:169], s[90:91] offset:1024
	s_add_u32 s92, s96, 0x0
	s_addc_u32 s93, s97, 0
	v_pk_mul_f32 v[142:143], v[190:191], v[142:143]
	v_pk_mul_f32 v[144:145], v[192:193], v[144:145]
	v_pk_mul_f32 v[138:139], v[210:211], v[138:139]
	v_pk_mul_f32 v[140:141], v[212:213], v[140:141]
	v_cvt_pk_bf16_f32 v48, v142, v143
	v_cvt_pk_bf16_f32 v49, v144, v145
	v_cvt_pk_bf16_f32 v50, v138, v139
	v_cvt_pk_bf16_f32 v51, v140, v141
	v_pk_mul_f32 v[134:135], v[214:215], v[134:135]
	v_pk_mul_f32 v[136:137], v[216:217], v[136:137]
	v_pk_mul_f32 v[130:131], v[218:219], v[130:131]
	v_pk_mul_f32 v[132:133], v[220:221], v[132:133]
	v_cvt_pk_bf16_f32 v52, v134, v135
	v_cvt_pk_bf16_f32 v53, v136, v137
	v_cvt_pk_bf16_f32 v54, v130, v131
	v_cvt_pk_bf16_f32 v55, v132, v133
	s_mov_b64 vcc, s[66:67]
	v_cndmask_b32_dpp v222, v52, v48, vcc quad_perm:[1,0,3,2] row_mask:0xf bank_mask:0xf
	v_cndmask_b32_dpp v223, v53, v49, vcc quad_perm:[1,0,3,2] row_mask:0xf bank_mask:0xf
	v_cndmask_b32_dpp v224, v54, v50, vcc quad_perm:[1,0,3,2] row_mask:0xf bank_mask:0xf
	v_cndmask_b32_dpp v225, v55, v51, vcc quad_perm:[1,0,3,2] row_mask:0xf bank_mask:0xf
	s_mov_b64 vcc, s[62:63]
	v_cndmask_b32_dpp v52, v48, v52, vcc quad_perm:[1,0,3,2] row_mask:0xf bank_mask:0xf
	v_cndmask_b32_dpp v53, v49, v53, vcc quad_perm:[1,0,3,2] row_mask:0xf bank_mask:0xf
	v_cndmask_b32_dpp v54, v50, v54, vcc quad_perm:[1,0,3,2] row_mask:0xf bank_mask:0xf
	v_cndmask_b32_dpp v55, v51, v55, vcc quad_perm:[1,0,3,2] row_mask:0xf bank_mask:0xf
	global_store_dwordx4 v171, v[222:225], s[92:93]
	global_store_dwordx4 v171, v[52:55], s[92:93] offset:2048
	v_mov_b32_e32 v130, v173
	s_add_u32 s84, s58, 0x8000
	s_addc_u32 s85, s59, 0
	s_add_u32 s86, s74, 0x4000
	s_addc_u32 s87, s75, 0
	global_load_dwordx4 v[132:135], v171, s[84:85]
	global_load_dwordx2 v[136:137], v170, s[86:87]
	global_load_dwordx4 v[138:141], v171, s[84:85] offset:2048
	global_load_dwordx2 v[142:143], v170, s[86:87] offset:1024
	s_add_u32 s84, s58, 0x10000
	s_addc_u32 s85, s59, 0
	s_add_u32 s86, s74, 0x8000
	s_addc_u32 s87, s75, 0
	global_load_dwordx4 v[222:225], v171, s[84:85]
	global_load_dwordx2 v[144:145], v170, s[86:87]
	global_load_dwordx4 v[226:229], v171, s[84:85] offset:2048
	global_load_dwordx2 v[230:231], v170, s[86:87] offset:1024
	s_waitcnt vmcnt(4)
	s_mov_b64 vcc, s[66:67]
	v_cndmask_b32_dpp v48, v138, v132, vcc quad_perm:[1,0,3,2] row_mask:0xf bank_mask:0xf
	v_cndmask_b32_dpp v49, v139, v133, vcc quad_perm:[1,0,3,2] row_mask:0xf bank_mask:0xf
	v_cndmask_b32_dpp v50, v140, v134, vcc quad_perm:[1,0,3,2] row_mask:0xf bank_mask:0xf
	v_cndmask_b32_dpp v51, v141, v135, vcc quad_perm:[1,0,3,2] row_mask:0xf bank_mask:0xf
	s_mov_b64 vcc, s[62:63]
	v_cndmask_b32_dpp v138, v132, v138, vcc quad_perm:[1,0,3,2] row_mask:0xf bank_mask:0xf
	v_cndmask_b32_dpp v139, v133, v139, vcc quad_perm:[1,0,3,2] row_mask:0xf bank_mask:0xf
	v_cndmask_b32_dpp v140, v134, v140, vcc quad_perm:[1,0,3,2] row_mask:0xf bank_mask:0xf
	v_cndmask_b32_dpp v141, v135, v141, vcc quad_perm:[1,0,3,2] row_mask:0xf bank_mask:0xf
	s_mov_b64 vcc, s[66:67]
	v_cndmask_b32_dpp v52, v142, v136, vcc quad_perm:[1,0,3,2] row_mask:0xf bank_mask:0xf
	v_cndmask_b32_dpp v53, v143, v137, vcc quad_perm:[1,0,3,2] row_mask:0xf bank_mask:0xf
	s_mov_b64 vcc, s[62:63]
	v_cndmask_b32_dpp v142, v136, v142, vcc quad_perm:[1,0,3,2] row_mask:0xf bank_mask:0xf
	v_cndmask_b32_dpp v143, v137, v143, vcc quad_perm:[1,0,3,2] row_mask:0xf bank_mask:0xf
	v_perm_b32 v44, v48, v52, s32
	v_perm_b32 v45, v48, v52, s8
	v_perm_b32 v46, v49, v52, s61
	v_perm_b32 v47, v49, v52, s98
	v_pk_fma_f32 v[126:127], v[126:127], v[174:175], v[44:45]
	v_pk_fma_f32 v[128:129], v[128:129], v[176:177], v[46:47]
	v_perm_b32 v44, v50, v53, s32
	v_perm_b32 v45, v50, v53, s8
	v_perm_b32 v46, v51, v53, s61
	v_perm_b32 v47, v51, v53, s98
	v_pk_fma_f32 v[122:123], v[122:123], v[178:179], v[44:45]
	v_pk_fma_f32 v[124:125], v[124:125], v[180:181], v[46:47]
	v_perm_b32 v44, v138, v142, s32
	v_perm_b32 v45, v138, v142, s8
	v_perm_b32 v46, v139, v142, s61
	v_perm_b32 v47, v139, v142, s98
	v_pk_fma_f32 v[118:119], v[118:119], v[182:183], v[44:45]
	v_pk_fma_f32 v[120:121], v[120:121], v[184:185], v[46:47]
	v_perm_b32 v44, v140, v143, s32
	v_perm_b32 v45, v140, v143, s8
	v_perm_b32 v46, v141, v143, s61
	v_perm_b32 v47, v141, v143, s98
	v_pk_fma_f32 v[114:115], v[114:115], v[186:187], v[44:45]
	v_pk_fma_f32 v[116:117], v[116:117], v[188:189], v[46:47]
	v_mul_f32_e32 v44, v127, v127
	v_mul_f32_e32 v45, v129, v129
	v_mul_f32_e32 v46, v123, v123
	v_mul_f32_e32 v47, v125, v125
	v_fmac_f32_e32 v44, v126, v126
	v_fmac_f32_e32 v45, v128, v128
	v_fmac_f32_e32 v46, v122, v122
	v_fmac_f32_e32 v47, v124, v124
	v_add_f32_e32 v44, v44, v45
	v_add_f32_e32 v46, v46, v47
	v_add_f32_e32 v173, v44, v46
	v_add_u32_e32 v44, 0x80, v126
	v_add_u32_e32 v45, 0x80, v127
	v_add_u32_e32 v46, 0x80, v128
	v_add_u32_e32 v47, 0x80, v129
	v_perm_b32 v48, v45, v44, s78
	v_perm_b32 v49, v47, v46, s78
	v_perm_b32 v42, v45, v44, s79
	v_perm_b32 v43, v47, v46, s79
	v_perm_b32 v56, v43, v42, s60
	v_add_u32_e32 v44, 0x80, v122
	v_add_u32_e32 v45, 0x80, v123
	v_add_u32_e32 v46, 0x80, v124
	v_add_u32_e32 v47, 0x80, v125
	v_perm_b32 v50, v45, v44, s78
	v_perm_b32 v51, v47, v46, s78
	v_perm_b32 v42, v45, v44, s79
	v_perm_b32 v43, v47, v46, s79
	v_perm_b32 v57, v43, v42, s60
	v_mul_f32_e32 v44, v119, v119
	v_mul_f32_e32 v45, v121, v121
	v_mul_f32_e32 v46, v115, v115
	v_mul_f32_e32 v47, v117, v117
	v_fmac_f32_e32 v44, v118, v118
	v_fmac_f32_e32 v45, v120, v120
	v_fmac_f32_e32 v46, v114, v114
	v_fmac_f32_e32 v47, v116, v116
	v_add_f32_e32 v44, v44, v45
	v_add_f32_e32 v46, v46, v47
	v_add_f32_e32 v44, v44, v46
	v_add_f32_e32 v173, v173, v44
	v_add_u32_e32 v44, 0x80, v118
	v_add_u32_e32 v45, 0x80, v119
	v_add_u32_e32 v46, 0x80, v120
	v_add_u32_e32 v47, 0x80, v121
	v_perm_b32 v52, v45, v44, s78
	v_perm_b32 v53, v47, v46, s78
	v_perm_b32 v42, v45, v44, s79
	v_perm_b32 v43, v47, v46, s79
	v_perm_b32 v168, v43, v42, s60
	v_add_u32_e32 v44, 0x80, v114
	v_add_u32_e32 v45, 0x80, v115
	v_add_u32_e32 v46, 0x80, v116
	v_add_u32_e32 v47, 0x80, v117
	v_perm_b32 v54, v45, v44, s78
	v_perm_b32 v55, v47, v46, s78
	v_perm_b32 v42, v45, v44, s79
	v_perm_b32 v43, v47, v46, s79
	v_perm_b32 v169, v43, v42, s60
	s_mov_b64 vcc, s[66:67]
	v_cndmask_b32_dpp v132, v52, v48, vcc quad_perm:[1,0,3,2] row_mask:0xf bank_mask:0xf
	v_cndmask_b32_dpp v133, v53, v49, vcc quad_perm:[1,0,3,2] row_mask:0xf bank_mask:0xf
	v_cndmask_b32_dpp v134, v54, v50, vcc quad_perm:[1,0,3,2] row_mask:0xf bank_mask:0xf
	v_cndmask_b32_dpp v135, v55, v51, vcc quad_perm:[1,0,3,2] row_mask:0xf bank_mask:0xf
	s_mov_b64 vcc, s[62:63]
	v_cndmask_b32_dpp v52, v48, v52, vcc quad_perm:[1,0,3,2] row_mask:0xf bank_mask:0xf
	v_cndmask_b32_dpp v53, v49, v53, vcc quad_perm:[1,0,3,2] row_mask:0xf bank_mask:0xf
	v_cndmask_b32_dpp v54, v50, v54, vcc quad_perm:[1,0,3,2] row_mask:0xf bank_mask:0xf
	v_cndmask_b32_dpp v55, v51, v55, vcc quad_perm:[1,0,3,2] row_mask:0xf bank_mask:0xf
	s_mov_b64 vcc, s[66:67]
	v_cndmask_b32_dpp v138, v168, v56, vcc quad_perm:[1,0,3,2] row_mask:0xf bank_mask:0xf
	v_cndmask_b32_dpp v139, v169, v57, vcc quad_perm:[1,0,3,2] row_mask:0xf bank_mask:0xf
	s_mov_b64 vcc, s[62:63]
	v_cndmask_b32_dpp v168, v56, v168, vcc quad_perm:[1,0,3,2] row_mask:0xf bank_mask:0xf
	v_cndmask_b32_dpp v169, v57, v169, vcc quad_perm:[1,0,3,2] row_mask:0xf bank_mask:0xf
	s_add_u32 s88, s58, 0x8000
	s_addc_u32 s89, s59, 0
	s_add_u32 s90, s74, 0x4000
	s_addc_u32 s91, s75, 0
	global_store_dwordx4 v171, v[132:135], s[88:89]
	global_store_dwordx4 v171, v[52:55], s[88:89] offset:2048
	global_store_dwordx2 v170, v[138:139], s[90:91]
	global_store_dwordx2 v170, v[168:169], s[90:91] offset:1024
	s_add_u32 s92, s96, 0x8000
	s_addc_u32 s93, s97, 0
	v_pk_mul_f32 v[126:127], v[190:191], v[126:127]
	v_pk_mul_f32 v[128:129], v[192:193], v[128:129]
	v_pk_mul_f32 v[122:123], v[210:211], v[122:123]
	v_pk_mul_f32 v[124:125], v[212:213], v[124:125]
	v_cvt_pk_bf16_f32 v48, v126, v127
	v_cvt_pk_bf16_f32 v49, v128, v129
	v_cvt_pk_bf16_f32 v50, v122, v123
	v_cvt_pk_bf16_f32 v51, v124, v125
	v_pk_mul_f32 v[118:119], v[214:215], v[118:119]
	v_pk_mul_f32 v[120:121], v[216:217], v[120:121]
	v_pk_mul_f32 v[114:115], v[218:219], v[114:115]
	v_pk_mul_f32 v[116:117], v[220:221], v[116:117]
	v_cvt_pk_bf16_f32 v52, v118, v119
	v_cvt_pk_bf16_f32 v53, v120, v121
	v_cvt_pk_bf16_f32 v54, v114, v115
	v_cvt_pk_bf16_f32 v55, v116, v117
	s_mov_b64 vcc, s[66:67]
	v_cndmask_b32_dpp v132, v52, v48, vcc quad_perm:[1,0,3,2] row_mask:0xf bank_mask:0xf
	v_cndmask_b32_dpp v133, v53, v49, vcc quad_perm:[1,0,3,2] row_mask:0xf bank_mask:0xf
	v_cndmask_b32_dpp v134, v54, v50, vcc quad_perm:[1,0,3,2] row_mask:0xf bank_mask:0xf
	v_cndmask_b32_dpp v135, v55, v51, vcc quad_perm:[1,0,3,2] row_mask:0xf bank_mask:0xf
	s_mov_b64 vcc, s[62:63]
	v_cndmask_b32_dpp v52, v48, v52, vcc quad_perm:[1,0,3,2] row_mask:0xf bank_mask:0xf
	v_cndmask_b32_dpp v53, v49, v53, vcc quad_perm:[1,0,3,2] row_mask:0xf bank_mask:0xf
	v_cndmask_b32_dpp v54, v50, v54, vcc quad_perm:[1,0,3,2] row_mask:0xf bank_mask:0xf
	v_cndmask_b32_dpp v55, v51, v55, vcc quad_perm:[1,0,3,2] row_mask:0xf bank_mask:0xf
	global_store_dwordx4 v171, v[132:135], s[92:93]
	global_store_dwordx4 v171, v[52:55], s[92:93] offset:2048
	v_mov_b32_e32 v114, v173
	s_add_u32 s84, s58, 0x18000
	s_addc_u32 s85, s59, 0
	s_add_u32 s86, s74, 0xc000
	s_addc_u32 s87, s75, 0
	global_load_dwordx4 v[116:119], v171, s[84:85]
	global_load_dwordx2 v[120:121], v170, s[86:87]
	global_load_dwordx4 v[122:125], v171, s[84:85] offset:2048
	global_load_dwordx2 v[126:127], v170, s[86:87] offset:1024
	s_waitcnt vmcnt(10)
	s_mov_b64 vcc, s[66:67]
	v_cndmask_b32_dpp v48, v226, v222, vcc quad_perm:[1,0,3,2] row_mask:0xf bank_mask:0xf
	v_cndmask_b32_dpp v49, v227, v223, vcc quad_perm:[1,0,3,2] row_mask:0xf bank_mask:0xf
	v_cndmask_b32_dpp v50, v228, v224, vcc quad_perm:[1,0,3,2] row_mask:0xf bank_mask:0xf
	v_cndmask_b32_dpp v51, v229, v225, vcc quad_perm:[1,0,3,2] row_mask:0xf bank_mask:0xf
	s_mov_b64 vcc, s[62:63]
	v_cndmask_b32_dpp v226, v222, v226, vcc quad_perm:[1,0,3,2] row_mask:0xf bank_mask:0xf
	v_cndmask_b32_dpp v227, v223, v227, vcc quad_perm:[1,0,3,2] row_mask:0xf bank_mask:0xf
	v_cndmask_b32_dpp v228, v224, v228, vcc quad_perm:[1,0,3,2] row_mask:0xf bank_mask:0xf
	v_cndmask_b32_dpp v229, v225, v229, vcc quad_perm:[1,0,3,2] row_mask:0xf bank_mask:0xf
	s_mov_b64 vcc, s[66:67]
	v_cndmask_b32_dpp v52, v230, v144, vcc quad_perm:[1,0,3,2] row_mask:0xf bank_mask:0xf
	v_cndmask_b32_dpp v53, v231, v145, vcc quad_perm:[1,0,3,2] row_mask:0xf bank_mask:0xf
	s_mov_b64 vcc, s[62:63]
	v_cndmask_b32_dpp v230, v144, v230, vcc quad_perm:[1,0,3,2] row_mask:0xf bank_mask:0xf
	v_cndmask_b32_dpp v231, v145, v231, vcc quad_perm:[1,0,3,2] row_mask:0xf bank_mask:0xf
	v_perm_b32 v44, v48, v52, s32
	v_perm_b32 v45, v48, v52, s8
	v_perm_b32 v46, v49, v52, s61
	v_perm_b32 v47, v49, v52, s98
	v_pk_fma_f32 v[110:111], v[110:111], v[174:175], v[44:45]
	v_pk_fma_f32 v[112:113], v[112:113], v[176:177], v[46:47]
	v_perm_b32 v44, v50, v53, s32
	v_perm_b32 v45, v50, v53, s8
	v_perm_b32 v46, v51, v53, s61
	v_perm_b32 v47, v51, v53, s98
	v_pk_fma_f32 v[106:107], v[106:107], v[178:179], v[44:45]
	v_pk_fma_f32 v[108:109], v[108:109], v[180:181], v[46:47]
	v_perm_b32 v44, v226, v230, s32
	v_perm_b32 v45, v226, v230, s8
	v_perm_b32 v46, v227, v230, s61
	v_perm_b32 v47, v227, v230, s98
	v_pk_fma_f32 v[102:103], v[102:103], v[182:183], v[44:45]
	v_pk_fma_f32 v[104:105], v[104:105], v[184:185], v[46:47]
	v_perm_b32 v44, v228, v231, s32
	v_perm_b32 v45, v228, v231, s8
	v_perm_b32 v46, v229, v231, s61
	v_perm_b32 v47, v229, v231, s98
	v_pk_fma_f32 v[98:99], v[98:99], v[186:187], v[44:45]
	v_pk_fma_f32 v[100:101], v[100:101], v[188:189], v[46:47]
	v_mul_f32_e32 v44, v111, v111
	v_mul_f32_e32 v45, v113, v113
	v_mul_f32_e32 v46, v107, v107
	v_mul_f32_e32 v47, v109, v109
	v_fmac_f32_e32 v44, v110, v110
	v_fmac_f32_e32 v45, v112, v112
	v_fmac_f32_e32 v46, v106, v106
	v_fmac_f32_e32 v47, v108, v108
	v_add_f32_e32 v44, v44, v45
	v_add_f32_e32 v46, v46, v47
	v_add_f32_e32 v173, v44, v46
	v_add_u32_e32 v44, 0x80, v110
	v_add_u32_e32 v45, 0x80, v111
	v_add_u32_e32 v46, 0x80, v112
	v_add_u32_e32 v47, 0x80, v113
	v_perm_b32 v48, v45, v44, s78
	v_perm_b32 v49, v47, v46, s78
	v_perm_b32 v42, v45, v44, s79
	v_perm_b32 v43, v47, v46, s79
	v_perm_b32 v56, v43, v42, s60
	v_add_u32_e32 v44, 0x80, v106
	v_add_u32_e32 v45, 0x80, v107
	v_add_u32_e32 v46, 0x80, v108
	v_add_u32_e32 v47, 0x80, v109
	v_perm_b32 v50, v45, v44, s78
	v_perm_b32 v51, v47, v46, s78
	v_perm_b32 v42, v45, v44, s79
	v_perm_b32 v43, v47, v46, s79
	v_perm_b32 v57, v43, v42, s60
	v_mul_f32_e32 v44, v103, v103
	v_mul_f32_e32 v45, v105, v105
	v_mul_f32_e32 v46, v99, v99
	v_mul_f32_e32 v47, v101, v101
	v_fmac_f32_e32 v44, v102, v102
	v_fmac_f32_e32 v45, v104, v104
	v_fmac_f32_e32 v46, v98, v98
	v_fmac_f32_e32 v47, v100, v100
	v_add_f32_e32 v44, v44, v45
	v_add_f32_e32 v46, v46, v47
	v_add_f32_e32 v44, v44, v46
	v_add_f32_e32 v173, v173, v44
	v_add_u32_e32 v44, 0x80, v102
	v_add_u32_e32 v45, 0x80, v103
	v_add_u32_e32 v46, 0x80, v104
	v_add_u32_e32 v47, 0x80, v105
	v_perm_b32 v52, v45, v44, s78
	v_perm_b32 v53, v47, v46, s78
	v_perm_b32 v42, v45, v44, s79
	v_perm_b32 v43, v47, v46, s79
	v_perm_b32 v168, v43, v42, s60
	v_add_u32_e32 v44, 0x80, v98
	v_add_u32_e32 v45, 0x80, v99
	v_add_u32_e32 v46, 0x80, v100
	v_add_u32_e32 v47, 0x80, v101
	v_perm_b32 v54, v45, v44, s78
	v_perm_b32 v55, v47, v46, s78
	v_perm_b32 v42, v45, v44, s79
	v_perm_b32 v43, v47, v46, s79
	v_perm_b32 v169, v43, v42, s60
	s_mov_b64 vcc, s[66:67]
	v_cndmask_b32_dpp v222, v52, v48, vcc quad_perm:[1,0,3,2] row_mask:0xf bank_mask:0xf
	v_cndmask_b32_dpp v223, v53, v49, vcc quad_perm:[1,0,3,2] row_mask:0xf bank_mask:0xf
	v_cndmask_b32_dpp v224, v54, v50, vcc quad_perm:[1,0,3,2] row_mask:0xf bank_mask:0xf
	v_cndmask_b32_dpp v225, v55, v51, vcc quad_perm:[1,0,3,2] row_mask:0xf bank_mask:0xf
	s_mov_b64 vcc, s[62:63]
	v_cndmask_b32_dpp v52, v48, v52, vcc quad_perm:[1,0,3,2] row_mask:0xf bank_mask:0xf
	v_cndmask_b32_dpp v53, v49, v53, vcc quad_perm:[1,0,3,2] row_mask:0xf bank_mask:0xf
	v_cndmask_b32_dpp v54, v50, v54, vcc quad_perm:[1,0,3,2] row_mask:0xf bank_mask:0xf
	v_cndmask_b32_dpp v55, v51, v55, vcc quad_perm:[1,0,3,2] row_mask:0xf bank_mask:0xf
	s_mov_b64 vcc, s[66:67]
	v_cndmask_b32_dpp v226, v168, v56, vcc quad_perm:[1,0,3,2] row_mask:0xf bank_mask:0xf
	v_cndmask_b32_dpp v227, v169, v57, vcc quad_perm:[1,0,3,2] row_mask:0xf bank_mask:0xf
	s_mov_b64 vcc, s[62:63]
	v_cndmask_b32_dpp v168, v56, v168, vcc quad_perm:[1,0,3,2] row_mask:0xf bank_mask:0xf
	v_cndmask_b32_dpp v169, v57, v169, vcc quad_perm:[1,0,3,2] row_mask:0xf bank_mask:0xf
	s_add_u32 s88, s58, 0x10000
	s_addc_u32 s89, s59, 0
	s_add_u32 s90, s74, 0x8000
	s_addc_u32 s91, s75, 0
	global_store_dwordx4 v171, v[222:225], s[88:89]
	global_store_dwordx4 v171, v[52:55], s[88:89] offset:2048
	global_store_dwordx2 v170, v[226:227], s[90:91]
	global_store_dwordx2 v170, v[168:169], s[90:91] offset:1024
	s_add_u32 s92, s96, 0x10000
	s_addc_u32 s93, s97, 0
	v_pk_mul_f32 v[110:111], v[190:191], v[110:111]
	v_pk_mul_f32 v[112:113], v[192:193], v[112:113]
	v_pk_mul_f32 v[106:107], v[210:211], v[106:107]
	v_pk_mul_f32 v[108:109], v[212:213], v[108:109]
	v_cvt_pk_bf16_f32 v48, v110, v111
	v_cvt_pk_bf16_f32 v49, v112, v113
	v_cvt_pk_bf16_f32 v50, v106, v107
	v_cvt_pk_bf16_f32 v51, v108, v109
	v_pk_mul_f32 v[102:103], v[214:215], v[102:103]
	v_pk_mul_f32 v[104:105], v[216:217], v[104:105]
	v_pk_mul_f32 v[98:99], v[218:219], v[98:99]
	v_pk_mul_f32 v[100:101], v[220:221], v[100:101]
	v_cvt_pk_bf16_f32 v52, v102, v103
	v_cvt_pk_bf16_f32 v53, v104, v105
	v_cvt_pk_bf16_f32 v54, v98, v99
	v_cvt_pk_bf16_f32 v55, v100, v101
	s_mov_b64 vcc, s[66:67]
	v_cndmask_b32_dpp v222, v52, v48, vcc quad_perm:[1,0,3,2] row_mask:0xf bank_mask:0xf
	v_cndmask_b32_dpp v223, v53, v49, vcc quad_perm:[1,0,3,2] row_mask:0xf bank_mask:0xf
	v_cndmask_b32_dpp v224, v54, v50, vcc quad_perm:[1,0,3,2] row_mask:0xf bank_mask:0xf
	v_cndmask_b32_dpp v225, v55, v51, vcc quad_perm:[1,0,3,2] row_mask:0xf bank_mask:0xf
	s_mov_b64 vcc, s[62:63]
	v_cndmask_b32_dpp v52, v48, v52, vcc quad_perm:[1,0,3,2] row_mask:0xf bank_mask:0xf
	v_cndmask_b32_dpp v53, v49, v53, vcc quad_perm:[1,0,3,2] row_mask:0xf bank_mask:0xf
	v_cndmask_b32_dpp v54, v50, v54, vcc quad_perm:[1,0,3,2] row_mask:0xf bank_mask:0xf
	v_cndmask_b32_dpp v55, v51, v55, vcc quad_perm:[1,0,3,2] row_mask:0xf bank_mask:0xf
	global_store_dwordx4 v171, v[222:225], s[92:93]
	global_store_dwordx4 v171, v[52:55], s[92:93] offset:2048
	v_mov_b32_e32 v98, v173
	s_add_u32 s84, s58, 0x40000
	s_addc_u32 s85, s59, 0
	s_add_u32 s86, s74, 0x20000
	s_addc_u32 s87, s75, 0
	global_load_dwordx4 v[100:103], v171, s[84:85]
	global_load_dwordx2 v[104:105], v170, s[86:87]
	global_load_dwordx4 v[106:109], v171, s[84:85] offset:2048
	global_load_dwordx2 v[110:111], v170, s[86:87] offset:1024
	s_waitcnt vmcnt(10)
	s_mov_b64 vcc, s[66:67]
	v_cndmask_b32_dpp v48, v122, v116, vcc quad_perm:[1,0,3,2] row_mask:0xf bank_mask:0xf
	v_cndmask_b32_dpp v49, v123, v117, vcc quad_perm:[1,0,3,2] row_mask:0xf bank_mask:0xf
	v_cndmask_b32_dpp v50, v124, v118, vcc quad_perm:[1,0,3,2] row_mask:0xf bank_mask:0xf
	v_cndmask_b32_dpp v51, v125, v119, vcc quad_perm:[1,0,3,2] row_mask:0xf bank_mask:0xf
	s_mov_b64 vcc, s[62:63]
	v_cndmask_b32_dpp v122, v116, v122, vcc quad_perm:[1,0,3,2] row_mask:0xf bank_mask:0xf
	v_cndmask_b32_dpp v123, v117, v123, vcc quad_perm:[1,0,3,2] row_mask:0xf bank_mask:0xf
	v_cndmask_b32_dpp v124, v118, v124, vcc quad_perm:[1,0,3,2] row_mask:0xf bank_mask:0xf
	v_cndmask_b32_dpp v125, v119, v125, vcc quad_perm:[1,0,3,2] row_mask:0xf bank_mask:0xf
	s_mov_b64 vcc, s[66:67]
	v_cndmask_b32_dpp v52, v126, v120, vcc quad_perm:[1,0,3,2] row_mask:0xf bank_mask:0xf
	v_cndmask_b32_dpp v53, v127, v121, vcc quad_perm:[1,0,3,2] row_mask:0xf bank_mask:0xf
	s_mov_b64 vcc, s[62:63]
	v_cndmask_b32_dpp v126, v120, v126, vcc quad_perm:[1,0,3,2] row_mask:0xf bank_mask:0xf
	v_cndmask_b32_dpp v127, v121, v127, vcc quad_perm:[1,0,3,2] row_mask:0xf bank_mask:0xf
	v_perm_b32 v44, v48, v52, s32
	v_perm_b32 v45, v48, v52, s8
	v_perm_b32 v46, v49, v52, s61
	v_perm_b32 v47, v49, v52, s98
	v_pk_fma_f32 v[94:95], v[94:95], v[174:175], v[44:45]
	v_pk_fma_f32 v[96:97], v[96:97], v[176:177], v[46:47]
	v_perm_b32 v44, v50, v53, s32
	v_perm_b32 v45, v50, v53, s8
	v_perm_b32 v46, v51, v53, s61
	v_perm_b32 v47, v51, v53, s98
	v_pk_fma_f32 v[90:91], v[90:91], v[178:179], v[44:45]
	v_pk_fma_f32 v[92:93], v[92:93], v[180:181], v[46:47]
	v_perm_b32 v44, v122, v126, s32
	v_perm_b32 v45, v122, v126, s8
	v_perm_b32 v46, v123, v126, s61
	v_perm_b32 v47, v123, v126, s98
	v_pk_fma_f32 v[86:87], v[86:87], v[182:183], v[44:45]
	v_pk_fma_f32 v[88:89], v[88:89], v[184:185], v[46:47]
	v_perm_b32 v44, v124, v127, s32
	v_perm_b32 v45, v124, v127, s8
	v_perm_b32 v46, v125, v127, s61
	v_perm_b32 v47, v125, v127, s98
	v_pk_fma_f32 v[82:83], v[82:83], v[186:187], v[44:45]
	v_pk_fma_f32 v[84:85], v[84:85], v[188:189], v[46:47]
	v_mul_f32_e32 v44, v95, v95
	v_mul_f32_e32 v45, v97, v97
	v_mul_f32_e32 v46, v91, v91
	v_mul_f32_e32 v47, v93, v93
	v_fmac_f32_e32 v44, v94, v94
	v_fmac_f32_e32 v45, v96, v96
	v_fmac_f32_e32 v46, v90, v90
	v_fmac_f32_e32 v47, v92, v92
	v_add_f32_e32 v44, v44, v45
	v_add_f32_e32 v46, v46, v47
	v_add_f32_e32 v173, v44, v46
	v_add_u32_e32 v44, 0x80, v94
	v_add_u32_e32 v45, 0x80, v95
	v_add_u32_e32 v46, 0x80, v96
	v_add_u32_e32 v47, 0x80, v97
	v_perm_b32 v48, v45, v44, s78
	v_perm_b32 v49, v47, v46, s78
	v_perm_b32 v42, v45, v44, s79
	v_perm_b32 v43, v47, v46, s79
	v_perm_b32 v56, v43, v42, s60
	v_add_u32_e32 v44, 0x80, v90
	v_add_u32_e32 v45, 0x80, v91
	v_add_u32_e32 v46, 0x80, v92
	v_add_u32_e32 v47, 0x80, v93
	v_perm_b32 v50, v45, v44, s78
	v_perm_b32 v51, v47, v46, s78
	v_perm_b32 v42, v45, v44, s79
	v_perm_b32 v43, v47, v46, s79
	v_perm_b32 v57, v43, v42, s60
	v_mul_f32_e32 v44, v87, v87
	v_mul_f32_e32 v45, v89, v89
	v_mul_f32_e32 v46, v83, v83
	v_mul_f32_e32 v47, v85, v85
	v_fmac_f32_e32 v44, v86, v86
	v_fmac_f32_e32 v45, v88, v88
	v_fmac_f32_e32 v46, v82, v82
	v_fmac_f32_e32 v47, v84, v84
	v_add_f32_e32 v44, v44, v45
	v_add_f32_e32 v46, v46, v47
	v_add_f32_e32 v44, v44, v46
	v_add_f32_e32 v173, v173, v44
	v_add_u32_e32 v44, 0x80, v86
	v_add_u32_e32 v45, 0x80, v87
	v_add_u32_e32 v46, 0x80, v88
	v_add_u32_e32 v47, 0x80, v89
	v_perm_b32 v52, v45, v44, s78
	v_perm_b32 v53, v47, v46, s78
	v_perm_b32 v42, v45, v44, s79
	v_perm_b32 v43, v47, v46, s79
	v_perm_b32 v168, v43, v42, s60
	v_add_u32_e32 v44, 0x80, v82
	v_add_u32_e32 v45, 0x80, v83
	v_add_u32_e32 v46, 0x80, v84
	v_add_u32_e32 v47, 0x80, v85
	v_perm_b32 v54, v45, v44, s78
	v_perm_b32 v55, v47, v46, s78
	v_perm_b32 v42, v45, v44, s79
	v_perm_b32 v43, v47, v46, s79
	v_perm_b32 v169, v43, v42, s60
	s_mov_b64 vcc, s[66:67]
	v_cndmask_b32_dpp v116, v52, v48, vcc quad_perm:[1,0,3,2] row_mask:0xf bank_mask:0xf
	v_cndmask_b32_dpp v117, v53, v49, vcc quad_perm:[1,0,3,2] row_mask:0xf bank_mask:0xf
	v_cndmask_b32_dpp v118, v54, v50, vcc quad_perm:[1,0,3,2] row_mask:0xf bank_mask:0xf
	v_cndmask_b32_dpp v119, v55, v51, vcc quad_perm:[1,0,3,2] row_mask:0xf bank_mask:0xf
	s_mov_b64 vcc, s[62:63]
	v_cndmask_b32_dpp v52, v48, v52, vcc quad_perm:[1,0,3,2] row_mask:0xf bank_mask:0xf
	v_cndmask_b32_dpp v53, v49, v53, vcc quad_perm:[1,0,3,2] row_mask:0xf bank_mask:0xf
	v_cndmask_b32_dpp v54, v50, v54, vcc quad_perm:[1,0,3,2] row_mask:0xf bank_mask:0xf
	v_cndmask_b32_dpp v55, v51, v55, vcc quad_perm:[1,0,3,2] row_mask:0xf bank_mask:0xf
	s_mov_b64 vcc, s[66:67]
	v_cndmask_b32_dpp v122, v168, v56, vcc quad_perm:[1,0,3,2] row_mask:0xf bank_mask:0xf
	v_cndmask_b32_dpp v123, v169, v57, vcc quad_perm:[1,0,3,2] row_mask:0xf bank_mask:0xf
	s_mov_b64 vcc, s[62:63]
	v_cndmask_b32_dpp v168, v56, v168, vcc quad_perm:[1,0,3,2] row_mask:0xf bank_mask:0xf
	v_cndmask_b32_dpp v169, v57, v169, vcc quad_perm:[1,0,3,2] row_mask:0xf bank_mask:0xf
	s_add_u32 s88, s58, 0x18000
	s_addc_u32 s89, s59, 0
	s_add_u32 s90, s74, 0xc000
	s_addc_u32 s91, s75, 0
	global_store_dwordx4 v171, v[116:119], s[88:89]
	global_store_dwordx4 v171, v[52:55], s[88:89] offset:2048
	global_store_dwordx2 v170, v[122:123], s[90:91]
	global_store_dwordx2 v170, v[168:169], s[90:91] offset:1024
	s_add_u32 s92, s96, 0x18000
	s_addc_u32 s93, s97, 0
	v_pk_mul_f32 v[94:95], v[190:191], v[94:95]
	v_pk_mul_f32 v[96:97], v[192:193], v[96:97]
	v_pk_mul_f32 v[90:91], v[210:211], v[90:91]
	v_pk_mul_f32 v[92:93], v[212:213], v[92:93]
	v_cvt_pk_bf16_f32 v48, v94, v95
	v_cvt_pk_bf16_f32 v49, v96, v97
	v_cvt_pk_bf16_f32 v50, v90, v91
	v_cvt_pk_bf16_f32 v51, v92, v93
	v_pk_mul_f32 v[86:87], v[214:215], v[86:87]
	v_pk_mul_f32 v[88:89], v[216:217], v[88:89]
	v_pk_mul_f32 v[82:83], v[218:219], v[82:83]
	v_pk_mul_f32 v[84:85], v[220:221], v[84:85]
	v_cvt_pk_bf16_f32 v52, v86, v87
	v_cvt_pk_bf16_f32 v53, v88, v89
	v_cvt_pk_bf16_f32 v54, v82, v83
	v_cvt_pk_bf16_f32 v55, v84, v85
	s_mov_b64 vcc, s[66:67]
	v_cndmask_b32_dpp v116, v52, v48, vcc quad_perm:[1,0,3,2] row_mask:0xf bank_mask:0xf
	v_cndmask_b32_dpp v117, v53, v49, vcc quad_perm:[1,0,3,2] row_mask:0xf bank_mask:0xf
	v_cndmask_b32_dpp v118, v54, v50, vcc quad_perm:[1,0,3,2] row_mask:0xf bank_mask:0xf
	v_cndmask_b32_dpp v119, v55, v51, vcc quad_perm:[1,0,3,2] row_mask:0xf bank_mask:0xf
	s_mov_b64 vcc, s[62:63]
	v_cndmask_b32_dpp v52, v48, v52, vcc quad_perm:[1,0,3,2] row_mask:0xf bank_mask:0xf
	v_cndmask_b32_dpp v53, v49, v53, vcc quad_perm:[1,0,3,2] row_mask:0xf bank_mask:0xf
	v_cndmask_b32_dpp v54, v50, v54, vcc quad_perm:[1,0,3,2] row_mask:0xf bank_mask:0xf
	v_cndmask_b32_dpp v55, v51, v55, vcc quad_perm:[1,0,3,2] row_mask:0xf bank_mask:0xf
	global_store_dwordx4 v171, v[116:119], s[92:93]
	global_store_dwordx4 v171, v[52:55], s[92:93] offset:2048
	v_mov_b32_e32 v82, v173
	s_add_u32 s84, s58, 0x48000
	s_addc_u32 s85, s59, 0
	s_add_u32 s86, s74, 0x24000
	s_addc_u32 s87, s75, 0
	global_load_dwordx4 v[84:87], v171, s[84:85]
	global_load_dwordx2 v[88:89], v170, s[86:87]
	global_load_dwordx4 v[90:93], v171, s[84:85] offset:2048
	global_load_dwordx2 v[94:95], v170, s[86:87] offset:1024
	s_waitcnt vmcnt(10)
	s_mov_b64 vcc, s[66:67]
	v_cndmask_b32_dpp v48, v106, v100, vcc quad_perm:[1,0,3,2] row_mask:0xf bank_mask:0xf
	v_cndmask_b32_dpp v49, v107, v101, vcc quad_perm:[1,0,3,2] row_mask:0xf bank_mask:0xf
	v_cndmask_b32_dpp v50, v108, v102, vcc quad_perm:[1,0,3,2] row_mask:0xf bank_mask:0xf
	v_cndmask_b32_dpp v51, v109, v103, vcc quad_perm:[1,0,3,2] row_mask:0xf bank_mask:0xf
	s_mov_b64 vcc, s[62:63]
	v_cndmask_b32_dpp v106, v100, v106, vcc quad_perm:[1,0,3,2] row_mask:0xf bank_mask:0xf
	v_cndmask_b32_dpp v107, v101, v107, vcc quad_perm:[1,0,3,2] row_mask:0xf bank_mask:0xf
	v_cndmask_b32_dpp v108, v102, v108, vcc quad_perm:[1,0,3,2] row_mask:0xf bank_mask:0xf
	v_cndmask_b32_dpp v109, v103, v109, vcc quad_perm:[1,0,3,2] row_mask:0xf bank_mask:0xf
	s_mov_b64 vcc, s[66:67]
	v_cndmask_b32_dpp v52, v110, v104, vcc quad_perm:[1,0,3,2] row_mask:0xf bank_mask:0xf
	v_cndmask_b32_dpp v53, v111, v105, vcc quad_perm:[1,0,3,2] row_mask:0xf bank_mask:0xf
	s_mov_b64 vcc, s[62:63]
	v_cndmask_b32_dpp v110, v104, v110, vcc quad_perm:[1,0,3,2] row_mask:0xf bank_mask:0xf
	v_cndmask_b32_dpp v111, v105, v111, vcc quad_perm:[1,0,3,2] row_mask:0xf bank_mask:0xf
	v_perm_b32 v44, v48, v52, s32
	v_perm_b32 v45, v48, v52, s8
	v_perm_b32 v46, v49, v52, s61
	v_perm_b32 v47, v49, v52, s98
	v_pk_fma_f32 v[78:79], v[78:79], v[174:175], v[44:45]
	v_pk_fma_f32 v[80:81], v[80:81], v[176:177], v[46:47]
	v_perm_b32 v44, v50, v53, s32
	v_perm_b32 v45, v50, v53, s8
	v_perm_b32 v46, v51, v53, s61
	v_perm_b32 v47, v51, v53, s98
	v_pk_fma_f32 v[74:75], v[74:75], v[178:179], v[44:45]
	v_pk_fma_f32 v[76:77], v[76:77], v[180:181], v[46:47]
	v_perm_b32 v44, v106, v110, s32
	v_perm_b32 v45, v106, v110, s8
	v_perm_b32 v46, v107, v110, s61
	v_perm_b32 v47, v107, v110, s98
	v_pk_fma_f32 v[70:71], v[70:71], v[182:183], v[44:45]
	v_pk_fma_f32 v[72:73], v[72:73], v[184:185], v[46:47]
	v_perm_b32 v44, v108, v111, s32
	v_perm_b32 v45, v108, v111, s8
	v_perm_b32 v46, v109, v111, s61
	v_perm_b32 v47, v109, v111, s98
	v_pk_fma_f32 v[66:67], v[66:67], v[186:187], v[44:45]
	v_pk_fma_f32 v[68:69], v[68:69], v[188:189], v[46:47]
	v_mul_f32_e32 v44, v79, v79
	v_mul_f32_e32 v45, v81, v81
	v_mul_f32_e32 v46, v75, v75
	v_mul_f32_e32 v47, v77, v77
	v_fmac_f32_e32 v44, v78, v78
	v_fmac_f32_e32 v45, v80, v80
	v_fmac_f32_e32 v46, v74, v74
	v_fmac_f32_e32 v47, v76, v76
	v_add_f32_e32 v44, v44, v45
	v_add_f32_e32 v46, v46, v47
	v_add_f32_e32 v173, v44, v46
	v_add_u32_e32 v44, 0x80, v78
	v_add_u32_e32 v45, 0x80, v79
	v_add_u32_e32 v46, 0x80, v80
	v_add_u32_e32 v47, 0x80, v81
	v_perm_b32 v48, v45, v44, s78
	v_perm_b32 v49, v47, v46, s78
	v_perm_b32 v42, v45, v44, s79
	v_perm_b32 v43, v47, v46, s79
	v_perm_b32 v56, v43, v42, s60
	v_add_u32_e32 v44, 0x80, v74
	v_add_u32_e32 v45, 0x80, v75
	v_add_u32_e32 v46, 0x80, v76
	v_add_u32_e32 v47, 0x80, v77
	v_perm_b32 v50, v45, v44, s78
	v_perm_b32 v51, v47, v46, s78
	v_perm_b32 v42, v45, v44, s79
	v_perm_b32 v43, v47, v46, s79
	v_perm_b32 v57, v43, v42, s60
	v_mul_f32_e32 v44, v71, v71
	v_mul_f32_e32 v45, v73, v73
	v_mul_f32_e32 v46, v67, v67
	v_mul_f32_e32 v47, v69, v69
	v_fmac_f32_e32 v44, v70, v70
	v_fmac_f32_e32 v45, v72, v72
	v_fmac_f32_e32 v46, v66, v66
	v_fmac_f32_e32 v47, v68, v68
	v_add_f32_e32 v44, v44, v45
	v_add_f32_e32 v46, v46, v47
	v_add_f32_e32 v44, v44, v46
	v_add_f32_e32 v173, v173, v44
	v_add_u32_e32 v44, 0x80, v70
	v_add_u32_e32 v45, 0x80, v71
	v_add_u32_e32 v46, 0x80, v72
	v_add_u32_e32 v47, 0x80, v73
	v_perm_b32 v52, v45, v44, s78
	v_perm_b32 v53, v47, v46, s78
	v_perm_b32 v42, v45, v44, s79
	v_perm_b32 v43, v47, v46, s79
	v_perm_b32 v168, v43, v42, s60
	v_add_u32_e32 v44, 0x80, v66
	v_add_u32_e32 v45, 0x80, v67
	v_add_u32_e32 v46, 0x80, v68
	v_add_u32_e32 v47, 0x80, v69
	v_perm_b32 v54, v45, v44, s78
	v_perm_b32 v55, v47, v46, s78
	v_perm_b32 v42, v45, v44, s79
	v_perm_b32 v43, v47, v46, s79
	v_perm_b32 v169, v43, v42, s60
	s_mov_b64 vcc, s[66:67]
	v_cndmask_b32_dpp v100, v52, v48, vcc quad_perm:[1,0,3,2] row_mask:0xf bank_mask:0xf
	v_cndmask_b32_dpp v101, v53, v49, vcc quad_perm:[1,0,3,2] row_mask:0xf bank_mask:0xf
	v_cndmask_b32_dpp v102, v54, v50, vcc quad_perm:[1,0,3,2] row_mask:0xf bank_mask:0xf
	v_cndmask_b32_dpp v103, v55, v51, vcc quad_perm:[1,0,3,2] row_mask:0xf bank_mask:0xf
	s_mov_b64 vcc, s[62:63]
	v_cndmask_b32_dpp v52, v48, v52, vcc quad_perm:[1,0,3,2] row_mask:0xf bank_mask:0xf
	v_cndmask_b32_dpp v53, v49, v53, vcc quad_perm:[1,0,3,2] row_mask:0xf bank_mask:0xf
	v_cndmask_b32_dpp v54, v50, v54, vcc quad_perm:[1,0,3,2] row_mask:0xf bank_mask:0xf
	v_cndmask_b32_dpp v55, v51, v55, vcc quad_perm:[1,0,3,2] row_mask:0xf bank_mask:0xf
	s_mov_b64 vcc, s[66:67]
	v_cndmask_b32_dpp v106, v168, v56, vcc quad_perm:[1,0,3,2] row_mask:0xf bank_mask:0xf
	v_cndmask_b32_dpp v107, v169, v57, vcc quad_perm:[1,0,3,2] row_mask:0xf bank_mask:0xf
	s_mov_b64 vcc, s[62:63]
	v_cndmask_b32_dpp v168, v56, v168, vcc quad_perm:[1,0,3,2] row_mask:0xf bank_mask:0xf
	v_cndmask_b32_dpp v169, v57, v169, vcc quad_perm:[1,0,3,2] row_mask:0xf bank_mask:0xf
	s_add_u32 s88, s58, 0x40000
	s_addc_u32 s89, s59, 0
	s_add_u32 s90, s74, 0x20000
	s_addc_u32 s91, s75, 0
	global_store_dwordx4 v171, v[100:103], s[88:89]
	global_store_dwordx4 v171, v[52:55], s[88:89] offset:2048
	global_store_dwordx2 v170, v[106:107], s[90:91]
	global_store_dwordx2 v170, v[168:169], s[90:91] offset:1024
	s_add_u32 s92, s96, 0x40000
	s_addc_u32 s93, s97, 0
	v_pk_mul_f32 v[78:79], v[190:191], v[78:79]
	v_pk_mul_f32 v[80:81], v[192:193], v[80:81]
	v_pk_mul_f32 v[74:75], v[210:211], v[74:75]
	v_pk_mul_f32 v[76:77], v[212:213], v[76:77]
	v_cvt_pk_bf16_f32 v48, v78, v79
	v_cvt_pk_bf16_f32 v49, v80, v81
	v_cvt_pk_bf16_f32 v50, v74, v75
	v_cvt_pk_bf16_f32 v51, v76, v77
	v_pk_mul_f32 v[70:71], v[214:215], v[70:71]
	v_pk_mul_f32 v[72:73], v[216:217], v[72:73]
	v_pk_mul_f32 v[66:67], v[218:219], v[66:67]
	v_pk_mul_f32 v[68:69], v[220:221], v[68:69]
	v_cvt_pk_bf16_f32 v52, v70, v71
	v_cvt_pk_bf16_f32 v53, v72, v73
	v_cvt_pk_bf16_f32 v54, v66, v67
	v_cvt_pk_bf16_f32 v55, v68, v69
	s_mov_b64 vcc, s[66:67]
	v_cndmask_b32_dpp v100, v52, v48, vcc quad_perm:[1,0,3,2] row_mask:0xf bank_mask:0xf
	v_cndmask_b32_dpp v101, v53, v49, vcc quad_perm:[1,0,3,2] row_mask:0xf bank_mask:0xf
	v_cndmask_b32_dpp v102, v54, v50, vcc quad_perm:[1,0,3,2] row_mask:0xf bank_mask:0xf
	v_cndmask_b32_dpp v103, v55, v51, vcc quad_perm:[1,0,3,2] row_mask:0xf bank_mask:0xf
	s_mov_b64 vcc, s[62:63]
	v_cndmask_b32_dpp v52, v48, v52, vcc quad_perm:[1,0,3,2] row_mask:0xf bank_mask:0xf
	v_cndmask_b32_dpp v53, v49, v53, vcc quad_perm:[1,0,3,2] row_mask:0xf bank_mask:0xf
	v_cndmask_b32_dpp v54, v50, v54, vcc quad_perm:[1,0,3,2] row_mask:0xf bank_mask:0xf
	v_cndmask_b32_dpp v55, v51, v55, vcc quad_perm:[1,0,3,2] row_mask:0xf bank_mask:0xf
	global_store_dwordx4 v171, v[100:103], s[92:93]
	global_store_dwordx4 v171, v[52:55], s[92:93] offset:2048
	v_mov_b32_e32 v66, v173
	s_add_u32 s84, s58, 0x50000
	s_addc_u32 s85, s59, 0
	s_add_u32 s86, s74, 0x28000
	s_addc_u32 s87, s75, 0
	global_load_dwordx4 v[68:71], v171, s[84:85]
	global_load_dwordx2 v[72:73], v170, s[86:87]
	global_load_dwordx4 v[74:77], v171, s[84:85] offset:2048
	global_load_dwordx2 v[78:79], v170, s[86:87] offset:1024
	s_waitcnt vmcnt(10)
	s_mov_b64 vcc, s[66:67]
	v_cndmask_b32_dpp v48, v90, v84, vcc quad_perm:[1,0,3,2] row_mask:0xf bank_mask:0xf
	v_cndmask_b32_dpp v49, v91, v85, vcc quad_perm:[1,0,3,2] row_mask:0xf bank_mask:0xf
	v_cndmask_b32_dpp v50, v92, v86, vcc quad_perm:[1,0,3,2] row_mask:0xf bank_mask:0xf
	v_cndmask_b32_dpp v51, v93, v87, vcc quad_perm:[1,0,3,2] row_mask:0xf bank_mask:0xf
	s_mov_b64 vcc, s[62:63]
	v_cndmask_b32_dpp v90, v84, v90, vcc quad_perm:[1,0,3,2] row_mask:0xf bank_mask:0xf
	v_cndmask_b32_dpp v91, v85, v91, vcc quad_perm:[1,0,3,2] row_mask:0xf bank_mask:0xf
	v_cndmask_b32_dpp v92, v86, v92, vcc quad_perm:[1,0,3,2] row_mask:0xf bank_mask:0xf
	v_cndmask_b32_dpp v93, v87, v93, vcc quad_perm:[1,0,3,2] row_mask:0xf bank_mask:0xf
	s_mov_b64 vcc, s[66:67]
	v_cndmask_b32_dpp v52, v94, v88, vcc quad_perm:[1,0,3,2] row_mask:0xf bank_mask:0xf
	v_cndmask_b32_dpp v53, v95, v89, vcc quad_perm:[1,0,3,2] row_mask:0xf bank_mask:0xf
	s_mov_b64 vcc, s[62:63]
	v_cndmask_b32_dpp v94, v88, v94, vcc quad_perm:[1,0,3,2] row_mask:0xf bank_mask:0xf
	v_cndmask_b32_dpp v95, v89, v95, vcc quad_perm:[1,0,3,2] row_mask:0xf bank_mask:0xf
	v_perm_b32 v44, v48, v52, s32
	v_perm_b32 v45, v48, v52, s8
	v_perm_b32 v46, v49, v52, s61
	v_perm_b32 v47, v49, v52, s98
	v_pk_fma_f32 v[62:63], v[62:63], v[174:175], v[44:45]
	v_pk_fma_f32 v[64:65], v[64:65], v[176:177], v[46:47]
	v_perm_b32 v44, v50, v53, s32
	v_perm_b32 v45, v50, v53, s8
	v_perm_b32 v46, v51, v53, s61
	v_perm_b32 v47, v51, v53, s98
	v_pk_fma_f32 v[58:59], v[58:59], v[178:179], v[44:45]
	v_pk_fma_f32 v[60:61], v[60:61], v[180:181], v[46:47]
	v_perm_b32 v44, v90, v94, s32
	v_perm_b32 v45, v90, v94, s8
	v_perm_b32 v46, v91, v94, s61
	v_perm_b32 v47, v91, v94, s98
	v_pk_fma_f32 v[38:39], v[38:39], v[182:183], v[44:45]
	v_pk_fma_f32 v[40:41], v[40:41], v[184:185], v[46:47]
	v_perm_b32 v44, v92, v95, s32
	v_perm_b32 v45, v92, v95, s8
	v_perm_b32 v46, v93, v95, s61
	v_perm_b32 v47, v93, v95, s98
	v_pk_fma_f32 v[34:35], v[34:35], v[186:187], v[44:45]
	v_pk_fma_f32 v[36:37], v[36:37], v[188:189], v[46:47]
	v_mul_f32_e32 v44, v63, v63
	v_mul_f32_e32 v45, v65, v65
	v_mul_f32_e32 v46, v59, v59
	v_mul_f32_e32 v47, v61, v61
	v_fmac_f32_e32 v44, v62, v62
	v_fmac_f32_e32 v45, v64, v64
	v_fmac_f32_e32 v46, v58, v58
	v_fmac_f32_e32 v47, v60, v60
	v_add_f32_e32 v44, v44, v45
	v_add_f32_e32 v46, v46, v47
	v_add_f32_e32 v173, v44, v46
	v_add_u32_e32 v44, 0x80, v62
	v_add_u32_e32 v45, 0x80, v63
	v_add_u32_e32 v46, 0x80, v64
	v_add_u32_e32 v47, 0x80, v65
	v_perm_b32 v48, v45, v44, s78
	v_perm_b32 v49, v47, v46, s78
	v_perm_b32 v42, v45, v44, s79
	v_perm_b32 v43, v47, v46, s79
	v_perm_b32 v56, v43, v42, s60
	v_add_u32_e32 v44, 0x80, v58
	v_add_u32_e32 v45, 0x80, v59
	v_add_u32_e32 v46, 0x80, v60
	v_add_u32_e32 v47, 0x80, v61
	v_perm_b32 v50, v45, v44, s78
	v_perm_b32 v51, v47, v46, s78
	v_perm_b32 v42, v45, v44, s79
	v_perm_b32 v43, v47, v46, s79
	v_perm_b32 v57, v43, v42, s60
	v_mul_f32_e32 v44, v39, v39
	v_mul_f32_e32 v45, v41, v41
	v_mul_f32_e32 v46, v35, v35
	v_mul_f32_e32 v47, v37, v37
	v_fmac_f32_e32 v44, v38, v38
	v_fmac_f32_e32 v45, v40, v40
	v_fmac_f32_e32 v46, v34, v34
	v_fmac_f32_e32 v47, v36, v36
	v_add_f32_e32 v44, v44, v45
	v_add_f32_e32 v46, v46, v47
	v_add_f32_e32 v44, v44, v46
	v_add_f32_e32 v173, v173, v44
	v_add_u32_e32 v44, 0x80, v38
	v_add_u32_e32 v45, 0x80, v39
	v_add_u32_e32 v46, 0x80, v40
	v_add_u32_e32 v47, 0x80, v41
	v_perm_b32 v52, v45, v44, s78
	v_perm_b32 v53, v47, v46, s78
	v_perm_b32 v42, v45, v44, s79
	v_perm_b32 v43, v47, v46, s79
	v_perm_b32 v168, v43, v42, s60
	v_add_u32_e32 v44, 0x80, v34
	v_add_u32_e32 v45, 0x80, v35
	v_add_u32_e32 v46, 0x80, v36
	v_add_u32_e32 v47, 0x80, v37
	v_perm_b32 v54, v45, v44, s78
	v_perm_b32 v55, v47, v46, s78
	v_perm_b32 v42, v45, v44, s79
	v_perm_b32 v43, v47, v46, s79
	v_perm_b32 v169, v43, v42, s60
	s_mov_b64 vcc, s[66:67]
	v_cndmask_b32_dpp v84, v52, v48, vcc quad_perm:[1,0,3,2] row_mask:0xf bank_mask:0xf
	v_cndmask_b32_dpp v85, v53, v49, vcc quad_perm:[1,0,3,2] row_mask:0xf bank_mask:0xf
	v_cndmask_b32_dpp v86, v54, v50, vcc quad_perm:[1,0,3,2] row_mask:0xf bank_mask:0xf
	v_cndmask_b32_dpp v87, v55, v51, vcc quad_perm:[1,0,3,2] row_mask:0xf bank_mask:0xf
	s_mov_b64 vcc, s[62:63]
	v_cndmask_b32_dpp v52, v48, v52, vcc quad_perm:[1,0,3,2] row_mask:0xf bank_mask:0xf
	v_cndmask_b32_dpp v53, v49, v53, vcc quad_perm:[1,0,3,2] row_mask:0xf bank_mask:0xf
	v_cndmask_b32_dpp v54, v50, v54, vcc quad_perm:[1,0,3,2] row_mask:0xf bank_mask:0xf
	v_cndmask_b32_dpp v55, v51, v55, vcc quad_perm:[1,0,3,2] row_mask:0xf bank_mask:0xf
	s_mov_b64 vcc, s[66:67]
	v_cndmask_b32_dpp v90, v168, v56, vcc quad_perm:[1,0,3,2] row_mask:0xf bank_mask:0xf
	v_cndmask_b32_dpp v91, v169, v57, vcc quad_perm:[1,0,3,2] row_mask:0xf bank_mask:0xf
	s_mov_b64 vcc, s[62:63]
	v_cndmask_b32_dpp v168, v56, v168, vcc quad_perm:[1,0,3,2] row_mask:0xf bank_mask:0xf
	v_cndmask_b32_dpp v169, v57, v169, vcc quad_perm:[1,0,3,2] row_mask:0xf bank_mask:0xf
	s_add_u32 s88, s58, 0x48000
	s_addc_u32 s89, s59, 0
	s_add_u32 s90, s74, 0x24000
	s_addc_u32 s91, s75, 0
	global_store_dwordx4 v171, v[84:87], s[88:89]
	global_store_dwordx4 v171, v[52:55], s[88:89] offset:2048
	global_store_dwordx2 v170, v[90:91], s[90:91]
	global_store_dwordx2 v170, v[168:169], s[90:91] offset:1024
	s_add_u32 s92, s96, 0x48000
	s_addc_u32 s93, s97, 0
	v_pk_mul_f32 v[62:63], v[190:191], v[62:63]
	v_pk_mul_f32 v[64:65], v[192:193], v[64:65]
	v_pk_mul_f32 v[58:59], v[210:211], v[58:59]
	v_pk_mul_f32 v[60:61], v[212:213], v[60:61]
	v_cvt_pk_bf16_f32 v48, v62, v63
	v_cvt_pk_bf16_f32 v49, v64, v65
	v_cvt_pk_bf16_f32 v50, v58, v59
	v_cvt_pk_bf16_f32 v51, v60, v61
	v_pk_mul_f32 v[38:39], v[214:215], v[38:39]
	v_pk_mul_f32 v[40:41], v[216:217], v[40:41]
	v_pk_mul_f32 v[34:35], v[218:219], v[34:35]
	v_pk_mul_f32 v[36:37], v[220:221], v[36:37]
	v_cvt_pk_bf16_f32 v52, v38, v39
	v_cvt_pk_bf16_f32 v53, v40, v41
	v_cvt_pk_bf16_f32 v54, v34, v35
	v_cvt_pk_bf16_f32 v55, v36, v37
	s_mov_b64 vcc, s[66:67]
	v_cndmask_b32_dpp v84, v52, v48, vcc quad_perm:[1,0,3,2] row_mask:0xf bank_mask:0xf
	v_cndmask_b32_dpp v85, v53, v49, vcc quad_perm:[1,0,3,2] row_mask:0xf bank_mask:0xf
	v_cndmask_b32_dpp v86, v54, v50, vcc quad_perm:[1,0,3,2] row_mask:0xf bank_mask:0xf
	v_cndmask_b32_dpp v87, v55, v51, vcc quad_perm:[1,0,3,2] row_mask:0xf bank_mask:0xf
	s_mov_b64 vcc, s[62:63]
	v_cndmask_b32_dpp v52, v48, v52, vcc quad_perm:[1,0,3,2] row_mask:0xf bank_mask:0xf
	v_cndmask_b32_dpp v53, v49, v53, vcc quad_perm:[1,0,3,2] row_mask:0xf bank_mask:0xf
	v_cndmask_b32_dpp v54, v50, v54, vcc quad_perm:[1,0,3,2] row_mask:0xf bank_mask:0xf
	v_cndmask_b32_dpp v55, v51, v55, vcc quad_perm:[1,0,3,2] row_mask:0xf bank_mask:0xf
	global_store_dwordx4 v171, v[84:87], s[92:93]
	global_store_dwordx4 v171, v[52:55], s[92:93] offset:2048
	v_mov_b32_e32 v34, v173
	s_add_u32 s84, s58, 0x58000
	s_addc_u32 s85, s59, 0
	s_add_u32 s86, s74, 0x2c000
	s_addc_u32 s87, s75, 0
	global_load_dwordx4 v[36:39], v171, s[84:85]
	global_load_dwordx2 v[40:41], v170, s[86:87]
	global_load_dwordx4 v[58:61], v171, s[84:85] offset:2048
	global_load_dwordx2 v[62:63], v170, s[86:87] offset:1024
	s_waitcnt vmcnt(10)
	s_mov_b64 vcc, s[66:67]
	v_cndmask_b32_dpp v48, v74, v68, vcc quad_perm:[1,0,3,2] row_mask:0xf bank_mask:0xf
	v_cndmask_b32_dpp v49, v75, v69, vcc quad_perm:[1,0,3,2] row_mask:0xf bank_mask:0xf
	v_cndmask_b32_dpp v50, v76, v70, vcc quad_perm:[1,0,3,2] row_mask:0xf bank_mask:0xf
	v_cndmask_b32_dpp v51, v77, v71, vcc quad_perm:[1,0,3,2] row_mask:0xf bank_mask:0xf
	s_mov_b64 vcc, s[62:63]
	v_cndmask_b32_dpp v74, v68, v74, vcc quad_perm:[1,0,3,2] row_mask:0xf bank_mask:0xf
	v_cndmask_b32_dpp v75, v69, v75, vcc quad_perm:[1,0,3,2] row_mask:0xf bank_mask:0xf
	v_cndmask_b32_dpp v76, v70, v76, vcc quad_perm:[1,0,3,2] row_mask:0xf bank_mask:0xf
	v_cndmask_b32_dpp v77, v71, v77, vcc quad_perm:[1,0,3,2] row_mask:0xf bank_mask:0xf
	s_mov_b64 vcc, s[66:67]
	v_cndmask_b32_dpp v52, v78, v72, vcc quad_perm:[1,0,3,2] row_mask:0xf bank_mask:0xf
	v_cndmask_b32_dpp v53, v79, v73, vcc quad_perm:[1,0,3,2] row_mask:0xf bank_mask:0xf
	s_mov_b64 vcc, s[62:63]
	v_cndmask_b32_dpp v78, v72, v78, vcc quad_perm:[1,0,3,2] row_mask:0xf bank_mask:0xf
	v_cndmask_b32_dpp v79, v73, v79, vcc quad_perm:[1,0,3,2] row_mask:0xf bank_mask:0xf
	v_perm_b32 v44, v48, v52, s32
	v_perm_b32 v45, v48, v52, s8
	v_perm_b32 v46, v49, v52, s61
	v_perm_b32 v47, v49, v52, s98
	v_pk_fma_f32 v[30:31], v[30:31], v[174:175], v[44:45]
	v_pk_fma_f32 v[32:33], v[32:33], v[176:177], v[46:47]
	v_perm_b32 v44, v50, v53, s32
	v_perm_b32 v45, v50, v53, s8
	v_perm_b32 v46, v51, v53, s61
	v_perm_b32 v47, v51, v53, s98
	v_pk_fma_f32 v[26:27], v[26:27], v[178:179], v[44:45]
	v_pk_fma_f32 v[28:29], v[28:29], v[180:181], v[46:47]
	v_perm_b32 v44, v74, v78, s32
	v_perm_b32 v45, v74, v78, s8
	v_perm_b32 v46, v75, v78, s61
	v_perm_b32 v47, v75, v78, s98
	v_pk_fma_f32 v[22:23], v[22:23], v[182:183], v[44:45]
	v_pk_fma_f32 v[24:25], v[24:25], v[184:185], v[46:47]
	v_perm_b32 v44, v76, v79, s32
	v_perm_b32 v45, v76, v79, s8
	v_perm_b32 v46, v77, v79, s61
	v_perm_b32 v47, v77, v79, s98
	v_pk_fma_f32 v[18:19], v[18:19], v[186:187], v[44:45]
	v_pk_fma_f32 v[20:21], v[20:21], v[188:189], v[46:47]
	v_mul_f32_e32 v44, v31, v31
	v_mul_f32_e32 v45, v33, v33
	v_mul_f32_e32 v46, v27, v27
	v_mul_f32_e32 v47, v29, v29
	v_fmac_f32_e32 v44, v30, v30
	v_fmac_f32_e32 v45, v32, v32
	v_fmac_f32_e32 v46, v26, v26
	v_fmac_f32_e32 v47, v28, v28
	v_add_f32_e32 v44, v44, v45
	v_add_f32_e32 v46, v46, v47
	v_add_f32_e32 v173, v44, v46
	v_add_u32_e32 v44, 0x80, v30
	v_add_u32_e32 v45, 0x80, v31
	v_add_u32_e32 v46, 0x80, v32
	v_add_u32_e32 v47, 0x80, v33
	v_perm_b32 v48, v45, v44, s78
	v_perm_b32 v49, v47, v46, s78
	v_perm_b32 v42, v45, v44, s79
	v_perm_b32 v43, v47, v46, s79
	v_perm_b32 v56, v43, v42, s60
	v_add_u32_e32 v44, 0x80, v26
	v_add_u32_e32 v45, 0x80, v27
	v_add_u32_e32 v46, 0x80, v28
	v_add_u32_e32 v47, 0x80, v29
	v_perm_b32 v50, v45, v44, s78
	v_perm_b32 v51, v47, v46, s78
	v_perm_b32 v42, v45, v44, s79
	v_perm_b32 v43, v47, v46, s79
	v_perm_b32 v57, v43, v42, s60
	v_mul_f32_e32 v44, v23, v23
	v_mul_f32_e32 v45, v25, v25
	v_mul_f32_e32 v46, v19, v19
	v_mul_f32_e32 v47, v21, v21
	v_fmac_f32_e32 v44, v22, v22
	v_fmac_f32_e32 v45, v24, v24
	v_fmac_f32_e32 v46, v18, v18
	v_fmac_f32_e32 v47, v20, v20
	v_add_f32_e32 v44, v44, v45
	v_add_f32_e32 v46, v46, v47
	v_add_f32_e32 v44, v44, v46
	v_add_f32_e32 v173, v173, v44
	v_add_u32_e32 v44, 0x80, v22
	v_add_u32_e32 v45, 0x80, v23
	v_add_u32_e32 v46, 0x80, v24
	v_add_u32_e32 v47, 0x80, v25
	v_perm_b32 v52, v45, v44, s78
	v_perm_b32 v53, v47, v46, s78
	v_perm_b32 v42, v45, v44, s79
	v_perm_b32 v43, v47, v46, s79
	v_perm_b32 v168, v43, v42, s60
	v_add_u32_e32 v44, 0x80, v18
	v_add_u32_e32 v45, 0x80, v19
	v_add_u32_e32 v46, 0x80, v20
	v_add_u32_e32 v47, 0x80, v21
	v_perm_b32 v54, v45, v44, s78
	v_perm_b32 v55, v47, v46, s78
	v_perm_b32 v42, v45, v44, s79
	v_perm_b32 v43, v47, v46, s79
	v_perm_b32 v169, v43, v42, s60
	s_mov_b64 vcc, s[66:67]
	v_cndmask_b32_dpp v68, v52, v48, vcc quad_perm:[1,0,3,2] row_mask:0xf bank_mask:0xf
	v_cndmask_b32_dpp v69, v53, v49, vcc quad_perm:[1,0,3,2] row_mask:0xf bank_mask:0xf
	v_cndmask_b32_dpp v70, v54, v50, vcc quad_perm:[1,0,3,2] row_mask:0xf bank_mask:0xf
	v_cndmask_b32_dpp v71, v55, v51, vcc quad_perm:[1,0,3,2] row_mask:0xf bank_mask:0xf
	s_mov_b64 vcc, s[62:63]
	v_cndmask_b32_dpp v52, v48, v52, vcc quad_perm:[1,0,3,2] row_mask:0xf bank_mask:0xf
	v_cndmask_b32_dpp v53, v49, v53, vcc quad_perm:[1,0,3,2] row_mask:0xf bank_mask:0xf
	v_cndmask_b32_dpp v54, v50, v54, vcc quad_perm:[1,0,3,2] row_mask:0xf bank_mask:0xf
	v_cndmask_b32_dpp v55, v51, v55, vcc quad_perm:[1,0,3,2] row_mask:0xf bank_mask:0xf
	s_mov_b64 vcc, s[66:67]
	v_cndmask_b32_dpp v74, v168, v56, vcc quad_perm:[1,0,3,2] row_mask:0xf bank_mask:0xf
	v_cndmask_b32_dpp v75, v169, v57, vcc quad_perm:[1,0,3,2] row_mask:0xf bank_mask:0xf
	s_mov_b64 vcc, s[62:63]
	v_cndmask_b32_dpp v168, v56, v168, vcc quad_perm:[1,0,3,2] row_mask:0xf bank_mask:0xf
	v_cndmask_b32_dpp v169, v57, v169, vcc quad_perm:[1,0,3,2] row_mask:0xf bank_mask:0xf
	s_add_u32 s88, s58, 0x50000
	s_addc_u32 s89, s59, 0
	s_add_u32 s90, s74, 0x28000
	s_addc_u32 s91, s75, 0
	global_store_dwordx4 v171, v[68:71], s[88:89]
	global_store_dwordx4 v171, v[52:55], s[88:89] offset:2048
	global_store_dwordx2 v170, v[74:75], s[90:91]
	global_store_dwordx2 v170, v[168:169], s[90:91] offset:1024
	s_add_u32 s92, s96, 0x50000
	s_addc_u32 s93, s97, 0
	v_pk_mul_f32 v[30:31], v[190:191], v[30:31]
	v_pk_mul_f32 v[32:33], v[192:193], v[32:33]
	v_pk_mul_f32 v[26:27], v[210:211], v[26:27]
	v_pk_mul_f32 v[28:29], v[212:213], v[28:29]
	v_cvt_pk_bf16_f32 v48, v30, v31
	v_cvt_pk_bf16_f32 v49, v32, v33
	v_cvt_pk_bf16_f32 v50, v26, v27
	v_cvt_pk_bf16_f32 v51, v28, v29
	v_pk_mul_f32 v[22:23], v[214:215], v[22:23]
	v_pk_mul_f32 v[24:25], v[216:217], v[24:25]
	v_pk_mul_f32 v[18:19], v[218:219], v[18:19]
	v_pk_mul_f32 v[20:21], v[220:221], v[20:21]
	v_cvt_pk_bf16_f32 v52, v22, v23
	v_cvt_pk_bf16_f32 v53, v24, v25
	v_cvt_pk_bf16_f32 v54, v18, v19
	v_cvt_pk_bf16_f32 v55, v20, v21
	s_mov_b64 vcc, s[66:67]
	v_cndmask_b32_dpp v68, v52, v48, vcc quad_perm:[1,0,3,2] row_mask:0xf bank_mask:0xf
	v_cndmask_b32_dpp v69, v53, v49, vcc quad_perm:[1,0,3,2] row_mask:0xf bank_mask:0xf
	v_cndmask_b32_dpp v70, v54, v50, vcc quad_perm:[1,0,3,2] row_mask:0xf bank_mask:0xf
	v_cndmask_b32_dpp v71, v55, v51, vcc quad_perm:[1,0,3,2] row_mask:0xf bank_mask:0xf
	s_mov_b64 vcc, s[62:63]
	v_cndmask_b32_dpp v52, v48, v52, vcc quad_perm:[1,0,3,2] row_mask:0xf bank_mask:0xf
	v_cndmask_b32_dpp v53, v49, v53, vcc quad_perm:[1,0,3,2] row_mask:0xf bank_mask:0xf
	v_cndmask_b32_dpp v54, v50, v54, vcc quad_perm:[1,0,3,2] row_mask:0xf bank_mask:0xf
	v_cndmask_b32_dpp v55, v51, v55, vcc quad_perm:[1,0,3,2] row_mask:0xf bank_mask:0xf
	global_store_dwordx4 v171, v[68:71], s[92:93]
	global_store_dwordx4 v171, v[52:55], s[92:93] offset:2048
	v_mov_b32_e32 v18, v173
	s_waitcnt vmcnt(6)
	s_mov_b64 vcc, s[66:67]
	v_cndmask_b32_dpp v48, v58, v36, vcc quad_perm:[1,0,3,2] row_mask:0xf bank_mask:0xf
	v_cndmask_b32_dpp v49, v59, v37, vcc quad_perm:[1,0,3,2] row_mask:0xf bank_mask:0xf
	v_cndmask_b32_dpp v50, v60, v38, vcc quad_perm:[1,0,3,2] row_mask:0xf bank_mask:0xf
	v_cndmask_b32_dpp v51, v61, v39, vcc quad_perm:[1,0,3,2] row_mask:0xf bank_mask:0xf
	s_mov_b64 vcc, s[62:63]
	v_cndmask_b32_dpp v58, v36, v58, vcc quad_perm:[1,0,3,2] row_mask:0xf bank_mask:0xf
	v_cndmask_b32_dpp v59, v37, v59, vcc quad_perm:[1,0,3,2] row_mask:0xf bank_mask:0xf
	v_cndmask_b32_dpp v60, v38, v60, vcc quad_perm:[1,0,3,2] row_mask:0xf bank_mask:0xf
	v_cndmask_b32_dpp v61, v39, v61, vcc quad_perm:[1,0,3,2] row_mask:0xf bank_mask:0xf
	s_mov_b64 vcc, s[66:67]
	v_cndmask_b32_dpp v52, v62, v40, vcc quad_perm:[1,0,3,2] row_mask:0xf bank_mask:0xf
	v_cndmask_b32_dpp v53, v63, v41, vcc quad_perm:[1,0,3,2] row_mask:0xf bank_mask:0xf
	s_mov_b64 vcc, s[62:63]
	v_cndmask_b32_dpp v62, v40, v62, vcc quad_perm:[1,0,3,2] row_mask:0xf bank_mask:0xf
	v_cndmask_b32_dpp v63, v41, v63, vcc quad_perm:[1,0,3,2] row_mask:0xf bank_mask:0xf
	v_perm_b32 v44, v48, v52, s32
	v_perm_b32 v45, v48, v52, s8
	v_perm_b32 v46, v49, v52, s61
	v_perm_b32 v47, v49, v52, s98
	v_pk_fma_f32 v[14:15], v[14:15], v[174:175], v[44:45]
	v_pk_fma_f32 v[16:17], v[16:17], v[176:177], v[46:47]
	v_perm_b32 v44, v50, v53, s32
	v_perm_b32 v45, v50, v53, s8
	v_perm_b32 v46, v51, v53, s61
	v_perm_b32 v47, v51, v53, s98
	v_pk_fma_f32 v[10:11], v[10:11], v[178:179], v[44:45]
	v_pk_fma_f32 v[12:13], v[12:13], v[180:181], v[46:47]
	v_perm_b32 v44, v58, v62, s32
	v_perm_b32 v45, v58, v62, s8
	v_perm_b32 v46, v59, v62, s61
	v_perm_b32 v47, v59, v62, s98
	v_pk_fma_f32 v[6:7], v[6:7], v[182:183], v[44:45]
	v_pk_fma_f32 v[8:9], v[8:9], v[184:185], v[46:47]
	v_perm_b32 v44, v60, v63, s32
	v_perm_b32 v45, v60, v63, s8
	v_perm_b32 v46, v61, v63, s61
	v_perm_b32 v47, v61, v63, s98
	v_pk_fma_f32 v[2:3], v[2:3], v[186:187], v[44:45]
	v_pk_fma_f32 v[4:5], v[4:5], v[188:189], v[46:47]
	v_mul_f32_e32 v44, v15, v15
	v_mul_f32_e32 v45, v17, v17
	v_mul_f32_e32 v46, v11, v11
	v_mul_f32_e32 v47, v13, v13
	v_fmac_f32_e32 v44, v14, v14
	v_fmac_f32_e32 v45, v16, v16
	v_fmac_f32_e32 v46, v10, v10
	v_fmac_f32_e32 v47, v12, v12
	v_add_f32_e32 v44, v44, v45
	v_add_f32_e32 v46, v46, v47
	v_add_f32_e32 v173, v44, v46
	v_add_u32_e32 v44, 0x80, v14
	v_add_u32_e32 v45, 0x80, v15
	v_add_u32_e32 v46, 0x80, v16
	v_add_u32_e32 v47, 0x80, v17
	v_perm_b32 v48, v45, v44, s78
	v_perm_b32 v49, v47, v46, s78
	v_perm_b32 v42, v45, v44, s79
	v_perm_b32 v43, v47, v46, s79
	v_perm_b32 v56, v43, v42, s60
	v_add_u32_e32 v44, 0x80, v10
	v_add_u32_e32 v45, 0x80, v11
	v_add_u32_e32 v46, 0x80, v12
	v_add_u32_e32 v47, 0x80, v13
	v_perm_b32 v50, v45, v44, s78
	v_perm_b32 v51, v47, v46, s78
	v_perm_b32 v42, v45, v44, s79
	v_perm_b32 v43, v47, v46, s79
	v_perm_b32 v57, v43, v42, s60
	v_mul_f32_e32 v44, v7, v7
	v_mul_f32_e32 v45, v9, v9
	v_mul_f32_e32 v46, v3, v3
	v_mul_f32_e32 v47, v5, v5
	v_fmac_f32_e32 v44, v6, v6
	v_fmac_f32_e32 v45, v8, v8
	v_fmac_f32_e32 v46, v2, v2
	v_fmac_f32_e32 v47, v4, v4
	v_add_f32_e32 v44, v44, v45
	v_add_f32_e32 v46, v46, v47
	v_add_f32_e32 v44, v44, v46
	v_add_f32_e32 v173, v173, v44
	v_add_u32_e32 v44, 0x80, v6
	v_add_u32_e32 v45, 0x80, v7
	v_add_u32_e32 v46, 0x80, v8
	v_add_u32_e32 v47, 0x80, v9
	v_perm_b32 v52, v45, v44, s78
	v_perm_b32 v53, v47, v46, s78
	v_perm_b32 v42, v45, v44, s79
	v_perm_b32 v43, v47, v46, s79
	v_perm_b32 v168, v43, v42, s60
	v_add_u32_e32 v44, 0x80, v2
	v_add_u32_e32 v45, 0x80, v3
	v_add_u32_e32 v46, 0x80, v4
	v_add_u32_e32 v47, 0x80, v5
	v_perm_b32 v54, v45, v44, s78
	v_perm_b32 v55, v47, v46, s78
	v_perm_b32 v42, v45, v44, s79
	v_perm_b32 v43, v47, v46, s79
	v_perm_b32 v169, v43, v42, s60
	s_mov_b64 vcc, s[66:67]
	v_cndmask_b32_dpp v36, v52, v48, vcc quad_perm:[1,0,3,2] row_mask:0xf bank_mask:0xf
	v_cndmask_b32_dpp v37, v53, v49, vcc quad_perm:[1,0,3,2] row_mask:0xf bank_mask:0xf
	v_cndmask_b32_dpp v38, v54, v50, vcc quad_perm:[1,0,3,2] row_mask:0xf bank_mask:0xf
	v_cndmask_b32_dpp v39, v55, v51, vcc quad_perm:[1,0,3,2] row_mask:0xf bank_mask:0xf
	s_mov_b64 vcc, s[62:63]
	v_cndmask_b32_dpp v52, v48, v52, vcc quad_perm:[1,0,3,2] row_mask:0xf bank_mask:0xf
	v_cndmask_b32_dpp v53, v49, v53, vcc quad_perm:[1,0,3,2] row_mask:0xf bank_mask:0xf
	v_cndmask_b32_dpp v54, v50, v54, vcc quad_perm:[1,0,3,2] row_mask:0xf bank_mask:0xf
	v_cndmask_b32_dpp v55, v51, v55, vcc quad_perm:[1,0,3,2] row_mask:0xf bank_mask:0xf
	s_mov_b64 vcc, s[66:67]
	v_cndmask_b32_dpp v58, v168, v56, vcc quad_perm:[1,0,3,2] row_mask:0xf bank_mask:0xf
	v_cndmask_b32_dpp v59, v169, v57, vcc quad_perm:[1,0,3,2] row_mask:0xf bank_mask:0xf
	s_mov_b64 vcc, s[62:63]
	v_cndmask_b32_dpp v168, v56, v168, vcc quad_perm:[1,0,3,2] row_mask:0xf bank_mask:0xf
	v_cndmask_b32_dpp v169, v57, v169, vcc quad_perm:[1,0,3,2] row_mask:0xf bank_mask:0xf
	s_add_u32 s88, s58, 0x58000
	s_addc_u32 s89, s59, 0
	s_add_u32 s90, s74, 0x2c000
	s_addc_u32 s91, s75, 0
	global_store_dwordx4 v171, v[36:39], s[88:89]
	global_store_dwordx4 v171, v[52:55], s[88:89] offset:2048
	global_store_dwordx2 v170, v[58:59], s[90:91]
	global_store_dwordx2 v170, v[168:169], s[90:91] offset:1024
	s_add_u32 s92, s96, 0x58000
	s_addc_u32 s93, s97, 0
	v_pk_mul_f32 v[14:15], v[190:191], v[14:15]
	v_pk_mul_f32 v[16:17], v[192:193], v[16:17]
	v_pk_mul_f32 v[10:11], v[210:211], v[10:11]
	v_pk_mul_f32 v[12:13], v[212:213], v[12:13]
	v_cvt_pk_bf16_f32 v48, v14, v15
	v_cvt_pk_bf16_f32 v49, v16, v17
	v_cvt_pk_bf16_f32 v50, v10, v11
	v_cvt_pk_bf16_f32 v51, v12, v13
	v_pk_mul_f32 v[6:7], v[214:215], v[6:7]
	v_pk_mul_f32 v[8:9], v[216:217], v[8:9]
	v_pk_mul_f32 v[2:3], v[218:219], v[2:3]
	v_pk_mul_f32 v[4:5], v[220:221], v[4:5]
	v_cvt_pk_bf16_f32 v52, v6, v7
	v_cvt_pk_bf16_f32 v53, v8, v9
	v_cvt_pk_bf16_f32 v54, v2, v3
	v_cvt_pk_bf16_f32 v55, v4, v5
	s_mov_b64 vcc, s[66:67]
	v_cndmask_b32_dpp v36, v52, v48, vcc quad_perm:[1,0,3,2] row_mask:0xf bank_mask:0xf
	v_cndmask_b32_dpp v37, v53, v49, vcc quad_perm:[1,0,3,2] row_mask:0xf bank_mask:0xf
	v_cndmask_b32_dpp v38, v54, v50, vcc quad_perm:[1,0,3,2] row_mask:0xf bank_mask:0xf
	v_cndmask_b32_dpp v39, v55, v51, vcc quad_perm:[1,0,3,2] row_mask:0xf bank_mask:0xf
	s_mov_b64 vcc, s[62:63]
	v_cndmask_b32_dpp v52, v48, v52, vcc quad_perm:[1,0,3,2] row_mask:0xf bank_mask:0xf
	v_cndmask_b32_dpp v53, v49, v53, vcc quad_perm:[1,0,3,2] row_mask:0xf bank_mask:0xf
	v_cndmask_b32_dpp v54, v50, v54, vcc quad_perm:[1,0,3,2] row_mask:0xf bank_mask:0xf
	v_cndmask_b32_dpp v55, v51, v55, vcc quad_perm:[1,0,3,2] row_mask:0xf bank_mask:0xf
	global_store_dwordx4 v171, v[36:39], s[92:93]
	global_store_dwordx4 v171, v[52:55], s[92:93] offset:2048
	v_mov_b32_e32 v2, v173
	v_mbcnt_lo_u32_b32 v3, -1, 0
	v_mbcnt_hi_u32_b32 v3, -1, v3
	v_xor_b32_e32 v4, 16, v3
	v_xor_b32_e32 v5, 32, v3
	v_lshlrev_b32_e32 v4, 2, v4
	v_lshlrev_b32_e32 v5, 2, v5
	v_cmp_gt_u32_e64 s[34:35], 16, v3
	ds_bpermute_b32 v6, v4, v130
	ds_bpermute_b32 v7, v4, v114
	ds_bpermute_b32 v8, v4, v98
	ds_bpermute_b32 v9, v4, v82
	ds_bpermute_b32 v10, v4, v66
	ds_bpermute_b32 v11, v4, v34
	ds_bpermute_b32 v12, v4, v18
	ds_bpermute_b32 v13, v4, v2
	s_waitcnt lgkmcnt(0)
	v_add_f32_e32 v130, v130, v6
	v_add_f32_e32 v114, v114, v7
	v_add_f32_e32 v98, v98, v8
	v_add_f32_e32 v82, v82, v9
	v_add_f32_e32 v66, v66, v10
	v_add_f32_e32 v34, v34, v11
	v_add_f32_e32 v18, v18, v12
	v_add_f32_e32 v2, v2, v13
	ds_bpermute_b32 v6, v5, v130
	ds_bpermute_b32 v7, v5, v114
	ds_bpermute_b32 v8, v5, v98
	ds_bpermute_b32 v9, v5, v82
	ds_bpermute_b32 v10, v5, v66
	ds_bpermute_b32 v11, v5, v34
	ds_bpermute_b32 v12, v5, v18
	ds_bpermute_b32 v13, v5, v2
	s_waitcnt lgkmcnt(0)
	v_add_f32_e32 v130, v130, v6
	v_add_f32_e32 v114, v114, v7
	v_add_f32_e32 v98, v98, v8
	v_add_f32_e32 v82, v82, v9
	v_add_f32_e32 v66, v66, v10
	v_add_f32_e32 v34, v34, v11
	v_add_f32_e32 v18, v18, v12
	v_add_f32_e32 v2, v2, v13
	v_readlane_b32 s70, v244, 53
	v_readlane_b32 s71, v244, 54
	v_lshlrev_b32_e32 v3, 6, v194
	s_lshl_b32 s94, s54, 14
	s_lshl_b32 s95, s4, 4
	s_add_u32 s94, s94, s95
	s_lshl_b32 s95, s51, 2
	s_add_u32 s94, s94, s95
	s_add_u32 s94, s70, s94
	s_addc_u32 s95, s71, 0
	s_and_saveexec_b64 s[36:37], s[34:35]
	global_store_dword v3, v130, s[94:95]
	s_add_u32 s84, s94, 0x400
	s_addc_u32 s85, s95, 0
	global_store_dword v3, v114, s[84:85]
	s_add_u32 s84, s94, 0x800
	s_addc_u32 s85, s95, 0
	global_store_dword v3, v98, s[84:85]
	s_add_u32 s84, s94, 0xc00
	s_addc_u32 s85, s95, 0
	global_store_dword v3, v82, s[84:85]
	s_add_u32 s84, s94, 0x2000
	s_addc_u32 s85, s95, 0
	global_store_dword v3, v66, s[84:85]
	s_add_u32 s84, s94, 0x2400
	s_addc_u32 s85, s95, 0
	global_store_dword v3, v34, s[84:85]
	s_add_u32 s84, s94, 0x2800
	s_addc_u32 s85, s95, 0
	global_store_dword v3, v18, s[84:85]
	s_add_u32 s84, s94, 0x2c00
	s_addc_u32 s85, s95, 0
	global_store_dword v3, v2, s[84:85]
	s_or_b64 exec, exec, s[36:37]
	v_readlane_b32 s56, v246, 3
	v_readlane_b32 s57, v246, 4
	s_branch .LBB0_1568
.Lepi3_nulla1:
	s_ashr_i32 s16, s54, 31
	s_lshr_b32 s16, s16, 29
	s_add_i32 s16, s54, s16
	s_ashr_i32 s16, s16, 3
	s_mul_i32 s27, s16, 0x6000
	s_mul_hi_i32 s25, s16, 0x6000
	s_add_u32 s80, s45, s27
	s_addc_u32 s81, s47, s25
	s_mov_b32 s62, 0xaaaaaaaa
	s_mov_b32 s63, 0xaaaaaaaa
	s_mov_b32 s66, 0x55555555
	s_mov_b32 s67, 0x55555555
	s_mov_b32 s32, 0x0504000c
	s_mov_b32 s61, 0x0504020c
	s_mov_b32 s98, 0x0706030c
	v_mbcnt_lo_u32_b32 v172, -1, 0
	v_mbcnt_hi_u32_b32 v172, -1, v172
	v_and_b32_e32 v172, 1, v172
	v_and_b32_e32 v171, 0x60, v196
	v_add_u32_e32 v171, v171, v196
	v_lshl_or_b32 v171, s4, 8, v171
	v_lshlrev_b32_e32 v44, 2, v171
	v_lshl_add_u32 v171, v172, 5, v171
	v_lshl_add_u32 v170, s54, 8, v194
	v_sub_u32_e32 v170, v170, v172
	v_lshl_add_u32 v170, v170, 10, v171
	v_lshlrev_b32_e32 v171, 1, v170
	global_load_dwordx4 v[174:177], v44, s[80:81] offset:0
	global_load_dwordx4 v[178:181], v44, s[80:81] offset:16
	global_load_dwordx4 v[182:185], v44, s[80:81] offset:128
	global_load_dwordx4 v[186:189], v44, s[80:81] offset:144
	s_waitcnt vmcnt(0)
	s_add_u32 s84, s58, 0x0
	s_addc_u32 s85, s59, 0
	s_add_u32 s86, s74, 0x0
	s_addc_u32 s87, s75, 0
	global_load_dwordx4 v[190:193], v171, s[84:85]
	global_load_dwordx2 v[210:211], v170, s[86:87]
	global_load_dwordx4 v[212:215], v171, s[84:85] offset:2048
	global_load_dwordx2 v[216:217], v170, s[86:87] offset:1024
	s_add_u32 s84, s58, 0x8000
	s_addc_u32 s85, s59, 0
	s_add_u32 s86, s74, 0x4000
	s_addc_u32 s87, s75, 0
	global_load_dwordx4 v[218:221], v171, s[84:85]
	global_load_dwordx2 v[222:223], v170, s[86:87]
	global_load_dwordx4 v[224:227], v171, s[84:85] offset:2048
	global_load_dwordx2 v[228:229], v170, s[86:87] offset:1024
	s_waitcnt vmcnt(4)
	s_mov_b64 vcc, s[66:67]
	v_cndmask_b32_dpp v48, v212, v190, vcc quad_perm:[1,0,3,2] row_mask:0xf bank_mask:0xf
	v_cndmask_b32_dpp v49, v213, v191, vcc quad_perm:[1,0,3,2] row_mask:0xf bank_mask:0xf
	v_cndmask_b32_dpp v50, v214, v192, vcc quad_perm:[1,0,3,2] row_mask:0xf bank_mask:0xf
	v_cndmask_b32_dpp v51, v215, v193, vcc quad_perm:[1,0,3,2] row_mask:0xf bank_mask:0xf
	s_mov_b64 vcc, s[62:63]
	v_cndmask_b32_dpp v212, v190, v212, vcc quad_perm:[1,0,3,2] row_mask:0xf bank_mask:0xf
	v_cndmask_b32_dpp v213, v191, v213, vcc quad_perm:[1,0,3,2] row_mask:0xf bank_mask:0xf
	v_cndmask_b32_dpp v214, v192, v214, vcc quad_perm:[1,0,3,2] row_mask:0xf bank_mask:0xf
	v_cndmask_b32_dpp v215, v193, v215, vcc quad_perm:[1,0,3,2] row_mask:0xf bank_mask:0xf
	s_mov_b64 vcc, s[66:67]
	v_cndmask_b32_dpp v52, v216, v210, vcc quad_perm:[1,0,3,2] row_mask:0xf bank_mask:0xf
	v_cndmask_b32_dpp v53, v217, v211, vcc quad_perm:[1,0,3,2] row_mask:0xf bank_mask:0xf
	s_mov_b64 vcc, s[62:63]
	v_cndmask_b32_dpp v216, v210, v216, vcc quad_perm:[1,0,3,2] row_mask:0xf bank_mask:0xf
	v_cndmask_b32_dpp v217, v211, v217, vcc quad_perm:[1,0,3,2] row_mask:0xf bank_mask:0xf
	v_perm_b32 v44, v48, v52, s32
	v_perm_b32 v45, v48, v52, s8
	v_perm_b32 v46, v49, v52, s61
	v_perm_b32 v47, v49, v52, s98
	v_pk_fma_f32 v[142:143], v[142:143], v[174:175], v[44:45]
	v_pk_fma_f32 v[144:145], v[144:145], v[176:177], v[46:47]
	v_perm_b32 v44, v50, v53, s32
	v_perm_b32 v45, v50, v53, s8
	v_perm_b32 v46, v51, v53, s61
	v_perm_b32 v47, v51, v53, s98
	v_pk_fma_f32 v[138:139], v[138:139], v[178:179], v[44:45]
	v_pk_fma_f32 v[140:141], v[140:141], v[180:181], v[46:47]
	v_perm_b32 v44, v212, v216, s32
	v_perm_b32 v45, v212, v216, s8
	v_perm_b32 v46, v213, v216, s61
	v_perm_b32 v47, v213, v216, s98
	v_pk_fma_f32 v[134:135], v[134:135], v[182:183], v[44:45]
	v_pk_fma_f32 v[136:137], v[136:137], v[184:185], v[46:47]
	v_perm_b32 v44, v214, v217, s32
	v_perm_b32 v45, v214, v217, s8
	v_perm_b32 v46, v215, v217, s61
	v_perm_b32 v47, v215, v217, s98
	v_pk_fma_f32 v[130:131], v[130:131], v[186:187], v[44:45]
	v_pk_fma_f32 v[132:133], v[132:133], v[188:189], v[46:47]
	v_add_u32_e32 v44, 0x80, v142
	v_add_u32_e32 v45, 0x80, v143
	v_add_u32_e32 v46, 0x80, v144
	v_add_u32_e32 v47, 0x80, v145
	v_perm_b32 v48, v45, v44, s78
	v_perm_b32 v49, v47, v46, s78
	v_perm_b32 v42, v45, v44, s79
	v_perm_b32 v43, v47, v46, s79
	v_perm_b32 v56, v43, v42, s60
	v_add_u32_e32 v44, 0x80, v138
	v_add_u32_e32 v45, 0x80, v139
	v_add_u32_e32 v46, 0x80, v140
	v_add_u32_e32 v47, 0x80, v141
	v_perm_b32 v50, v45, v44, s78
	v_perm_b32 v51, v47, v46, s78
	v_perm_b32 v42, v45, v44, s79
	v_perm_b32 v43, v47, v46, s79
	v_perm_b32 v57, v43, v42, s60
	v_add_u32_e32 v44, 0x80, v134
	v_add_u32_e32 v45, 0x80, v135
	v_add_u32_e32 v46, 0x80, v136
	v_add_u32_e32 v47, 0x80, v137
	v_perm_b32 v52, v45, v44, s78
	v_perm_b32 v53, v47, v46, s78
	v_perm_b32 v42, v45, v44, s79
	v_perm_b32 v43, v47, v46, s79
	v_perm_b32 v168, v43, v42, s60
	v_add_u32_e32 v44, 0x80, v130
	v_add_u32_e32 v45, 0x80, v131
	v_add_u32_e32 v46, 0x80, v132
	v_add_u32_e32 v47, 0x80, v133
	v_perm_b32 v54, v45, v44, s78
	v_perm_b32 v55, v47, v46, s78
	v_perm_b32 v42, v45, v44, s79
	v_perm_b32 v43, v47, v46, s79
	v_perm_b32 v169, v43, v42, s60
	s_mov_b64 vcc, s[66:67]
	v_cndmask_b32_dpp v190, v52, v48, vcc quad_perm:[1,0,3,2] row_mask:0xf bank_mask:0xf
	v_cndmask_b32_dpp v191, v53, v49, vcc quad_perm:[1,0,3,2] row_mask:0xf bank_mask:0xf
	v_cndmask_b32_dpp v192, v54, v50, vcc quad_perm:[1,0,3,2] row_mask:0xf bank_mask:0xf
	v_cndmask_b32_dpp v193, v55, v51, vcc quad_perm:[1,0,3,2] row_mask:0xf bank_mask:0xf
	s_mov_b64 vcc, s[62:63]
	v_cndmask_b32_dpp v52, v48, v52, vcc quad_perm:[1,0,3,2] row_mask:0xf bank_mask:0xf
	v_cndmask_b32_dpp v53, v49, v53, vcc quad_perm:[1,0,3,2] row_mask:0xf bank_mask:0xf
	v_cndmask_b32_dpp v54, v50, v54, vcc quad_perm:[1,0,3,2] row_mask:0xf bank_mask:0xf
	v_cndmask_b32_dpp v55, v51, v55, vcc quad_perm:[1,0,3,2] row_mask:0xf bank_mask:0xf
	s_mov_b64 vcc, s[66:67]
	v_cndmask_b32_dpp v212, v168, v56, vcc quad_perm:[1,0,3,2] row_mask:0xf bank_mask:0xf
	v_cndmask_b32_dpp v213, v169, v57, vcc quad_perm:[1,0,3,2] row_mask:0xf bank_mask:0xf
	s_mov_b64 vcc, s[62:63]
	v_cndmask_b32_dpp v168, v56, v168, vcc quad_perm:[1,0,3,2] row_mask:0xf bank_mask:0xf
	v_cndmask_b32_dpp v169, v57, v169, vcc quad_perm:[1,0,3,2] row_mask:0xf bank_mask:0xf
	s_add_u32 s88, s58, 0x0
	s_addc_u32 s89, s59, 0
	s_add_u32 s90, s74, 0x0
	s_addc_u32 s91, s75, 0
	global_store_dwordx4 v171, v[190:193], s[88:89]
	global_store_dwordx4 v171, v[52:55], s[88:89] offset:2048
	global_store_dwordx2 v170, v[212:213], s[90:91]
	global_store_dwordx2 v170, v[168:169], s[90:91] offset:1024
	s_add_u32 s84, s58, 0x10000
	s_addc_u32 s85, s59, 0
	s_add_u32 s86, s74, 0x8000
	s_addc_u32 s87, s75, 0
	global_load_dwordx4 v[130:133], v171, s[84:85]
	global_load_dwordx2 v[134:135], v170, s[86:87]
	global_load_dwordx4 v[136:139], v171, s[84:85] offset:2048
	global_load_dwordx2 v[140:141], v170, s[86:87] offset:1024
	s_waitcnt vmcnt(8)
	s_mov_b64 vcc, s[66:67]
	v_cndmask_b32_dpp v48, v224, v218, vcc quad_perm:[1,0,3,2] row_mask:0xf bank_mask:0xf
	v_cndmask_b32_dpp v49, v225, v219, vcc quad_perm:[1,0,3,2] row_mask:0xf bank_mask:0xf
	v_cndmask_b32_dpp v50, v226, v220, vcc quad_perm:[1,0,3,2] row_mask:0xf bank_mask:0xf
	v_cndmask_b32_dpp v51, v227, v221, vcc quad_perm:[1,0,3,2] row_mask:0xf bank_mask:0xf
	s_mov_b64 vcc, s[62:63]
	v_cndmask_b32_dpp v224, v218, v224, vcc quad_perm:[1,0,3,2] row_mask:0xf bank_mask:0xf
	v_cndmask_b32_dpp v225, v219, v225, vcc quad_perm:[1,0,3,2] row_mask:0xf bank_mask:0xf
	v_cndmask_b32_dpp v226, v220, v226, vcc quad_perm:[1,0,3,2] row_mask:0xf bank_mask:0xf
	v_cndmask_b32_dpp v227, v221, v227, vcc quad_perm:[1,0,3,2] row_mask:0xf bank_mask:0xf
	s_mov_b64 vcc, s[66:67]
	v_cndmask_b32_dpp v52, v228, v222, vcc quad_perm:[1,0,3,2] row_mask:0xf bank_mask:0xf
	v_cndmask_b32_dpp v53, v229, v223, vcc quad_perm:[1,0,3,2] row_mask:0xf bank_mask:0xf
	s_mov_b64 vcc, s[62:63]
	v_cndmask_b32_dpp v228, v222, v228, vcc quad_perm:[1,0,3,2] row_mask:0xf bank_mask:0xf
	v_cndmask_b32_dpp v229, v223, v229, vcc quad_perm:[1,0,3,2] row_mask:0xf bank_mask:0xf
	v_perm_b32 v44, v48, v52, s32
	v_perm_b32 v45, v48, v52, s8
	v_perm_b32 v46, v49, v52, s61
	v_perm_b32 v47, v49, v52, s98
	v_pk_fma_f32 v[126:127], v[126:127], v[174:175], v[44:45]
	v_pk_fma_f32 v[128:129], v[128:129], v[176:177], v[46:47]
	v_perm_b32 v44, v50, v53, s32
	v_perm_b32 v45, v50, v53, s8
	v_perm_b32 v46, v51, v53, s61
	v_perm_b32 v47, v51, v53, s98
	v_pk_fma_f32 v[122:123], v[122:123], v[178:179], v[44:45]
	v_pk_fma_f32 v[124:125], v[124:125], v[180:181], v[46:47]
	v_perm_b32 v44, v224, v228, s32
	v_perm_b32 v45, v224, v228, s8
	v_perm_b32 v46, v225, v228, s61
	v_perm_b32 v47, v225, v228, s98
	v_pk_fma_f32 v[118:119], v[118:119], v[182:183], v[44:45]
	v_pk_fma_f32 v[120:121], v[120:121], v[184:185], v[46:47]
	v_perm_b32 v44, v226, v229, s32
	v_perm_b32 v45, v226, v229, s8
	v_perm_b32 v46, v227, v229, s61
	v_perm_b32 v47, v227, v229, s98
	v_pk_fma_f32 v[114:115], v[114:115], v[186:187], v[44:45]
	v_pk_fma_f32 v[116:117], v[116:117], v[188:189], v[46:47]
	v_add_u32_e32 v44, 0x80, v126
	v_add_u32_e32 v45, 0x80, v127
	v_add_u32_e32 v46, 0x80, v128
	v_add_u32_e32 v47, 0x80, v129
	v_perm_b32 v48, v45, v44, s78
	v_perm_b32 v49, v47, v46, s78
	v_perm_b32 v42, v45, v44, s79
	v_perm_b32 v43, v47, v46, s79
	v_perm_b32 v56, v43, v42, s60
	v_add_u32_e32 v44, 0x80, v122
	v_add_u32_e32 v45, 0x80, v123
	v_add_u32_e32 v46, 0x80, v124
	v_add_u32_e32 v47, 0x80, v125
	v_perm_b32 v50, v45, v44, s78
	v_perm_b32 v51, v47, v46, s78
	v_perm_b32 v42, v45, v44, s79
	v_perm_b32 v43, v47, v46, s79
	v_perm_b32 v57, v43, v42, s60
	v_add_u32_e32 v44, 0x80, v118
	v_add_u32_e32 v45, 0x80, v119
	v_add_u32_e32 v46, 0x80, v120
	v_add_u32_e32 v47, 0x80, v121
	v_perm_b32 v52, v45, v44, s78
	v_perm_b32 v53, v47, v46, s78
	v_perm_b32 v42, v45, v44, s79
	v_perm_b32 v43, v47, v46, s79
	v_perm_b32 v168, v43, v42, s60
	v_add_u32_e32 v44, 0x80, v114
	v_add_u32_e32 v45, 0x80, v115
	v_add_u32_e32 v46, 0x80, v116
	v_add_u32_e32 v47, 0x80, v117
	v_perm_b32 v54, v45, v44, s78
	v_perm_b32 v55, v47, v46, s78
	v_perm_b32 v42, v45, v44, s79
	v_perm_b32 v43, v47, v46, s79
	v_perm_b32 v169, v43, v42, s60
	s_mov_b64 vcc, s[66:67]
	v_cndmask_b32_dpp v218, v52, v48, vcc quad_perm:[1,0,3,2] row_mask:0xf bank_mask:0xf
	v_cndmask_b32_dpp v219, v53, v49, vcc quad_perm:[1,0,3,2] row_mask:0xf bank_mask:0xf
	v_cndmask_b32_dpp v220, v54, v50, vcc quad_perm:[1,0,3,2] row_mask:0xf bank_mask:0xf
	v_cndmask_b32_dpp v221, v55, v51, vcc quad_perm:[1,0,3,2] row_mask:0xf bank_mask:0xf
	s_mov_b64 vcc, s[62:63]
	v_cndmask_b32_dpp v52, v48, v52, vcc quad_perm:[1,0,3,2] row_mask:0xf bank_mask:0xf
	v_cndmask_b32_dpp v53, v49, v53, vcc quad_perm:[1,0,3,2] row_mask:0xf bank_mask:0xf
	v_cndmask_b32_dpp v54, v50, v54, vcc quad_perm:[1,0,3,2] row_mask:0xf bank_mask:0xf
	v_cndmask_b32_dpp v55, v51, v55, vcc quad_perm:[1,0,3,2] row_mask:0xf bank_mask:0xf
	s_mov_b64 vcc, s[66:67]
	v_cndmask_b32_dpp v224, v168, v56, vcc quad_perm:[1,0,3,2] row_mask:0xf bank_mask:0xf
	v_cndmask_b32_dpp v225, v169, v57, vcc quad_perm:[1,0,3,2] row_mask:0xf bank_mask:0xf
	s_mov_b64 vcc, s[62:63]
	v_cndmask_b32_dpp v168, v56, v168, vcc quad_perm:[1,0,3,2] row_mask:0xf bank_mask:0xf
	v_cndmask_b32_dpp v169, v57, v169, vcc quad_perm:[1,0,3,2] row_mask:0xf bank_mask:0xf
	s_add_u32 s88, s58, 0x8000
	s_addc_u32 s89, s59, 0
	s_add_u32 s90, s74, 0x4000
	s_addc_u32 s91, s75, 0
	global_store_dwordx4 v171, v[218:221], s[88:89]
	global_store_dwordx4 v171, v[52:55], s[88:89] offset:2048
	global_store_dwordx2 v170, v[224:225], s[90:91]
	global_store_dwordx2 v170, v[168:169], s[90:91] offset:1024
	s_add_u32 s84, s58, 0x18000
	s_addc_u32 s85, s59, 0
	s_add_u32 s86, s74, 0xc000
	s_addc_u32 s87, s75, 0
	global_load_dwordx4 v[114:117], v171, s[84:85]
	global_load_dwordx2 v[118:119], v170, s[86:87]
	global_load_dwordx4 v[120:123], v171, s[84:85] offset:2048
	global_load_dwordx2 v[124:125], v170, s[86:87] offset:1024
	s_waitcnt vmcnt(8)
	s_mov_b64 vcc, s[66:67]
	v_cndmask_b32_dpp v48, v136, v130, vcc quad_perm:[1,0,3,2] row_mask:0xf bank_mask:0xf
	v_cndmask_b32_dpp v49, v137, v131, vcc quad_perm:[1,0,3,2] row_mask:0xf bank_mask:0xf
	v_cndmask_b32_dpp v50, v138, v132, vcc quad_perm:[1,0,3,2] row_mask:0xf bank_mask:0xf
	v_cndmask_b32_dpp v51, v139, v133, vcc quad_perm:[1,0,3,2] row_mask:0xf bank_mask:0xf
	s_mov_b64 vcc, s[62:63]
	v_cndmask_b32_dpp v136, v130, v136, vcc quad_perm:[1,0,3,2] row_mask:0xf bank_mask:0xf
	v_cndmask_b32_dpp v137, v131, v137, vcc quad_perm:[1,0,3,2] row_mask:0xf bank_mask:0xf
	v_cndmask_b32_dpp v138, v132, v138, vcc quad_perm:[1,0,3,2] row_mask:0xf bank_mask:0xf
	v_cndmask_b32_dpp v139, v133, v139, vcc quad_perm:[1,0,3,2] row_mask:0xf bank_mask:0xf
	s_mov_b64 vcc, s[66:67]
	v_cndmask_b32_dpp v52, v140, v134, vcc quad_perm:[1,0,3,2] row_mask:0xf bank_mask:0xf
	v_cndmask_b32_dpp v53, v141, v135, vcc quad_perm:[1,0,3,2] row_mask:0xf bank_mask:0xf
	s_mov_b64 vcc, s[62:63]
	v_cndmask_b32_dpp v140, v134, v140, vcc quad_perm:[1,0,3,2] row_mask:0xf bank_mask:0xf
	v_cndmask_b32_dpp v141, v135, v141, vcc quad_perm:[1,0,3,2] row_mask:0xf bank_mask:0xf
	v_perm_b32 v44, v48, v52, s32
	v_perm_b32 v45, v48, v52, s8
	v_perm_b32 v46, v49, v52, s61
	v_perm_b32 v47, v49, v52, s98
	v_pk_fma_f32 v[110:111], v[110:111], v[174:175], v[44:45]
	v_pk_fma_f32 v[112:113], v[112:113], v[176:177], v[46:47]
	v_perm_b32 v44, v50, v53, s32
	v_perm_b32 v45, v50, v53, s8
	v_perm_b32 v46, v51, v53, s61
	v_perm_b32 v47, v51, v53, s98
	v_pk_fma_f32 v[106:107], v[106:107], v[178:179], v[44:45]
	v_pk_fma_f32 v[108:109], v[108:109], v[180:181], v[46:47]
	v_perm_b32 v44, v136, v140, s32
	v_perm_b32 v45, v136, v140, s8
	v_perm_b32 v46, v137, v140, s61
	v_perm_b32 v47, v137, v140, s98
	v_pk_fma_f32 v[102:103], v[102:103], v[182:183], v[44:45]
	v_pk_fma_f32 v[104:105], v[104:105], v[184:185], v[46:47]
	v_perm_b32 v44, v138, v141, s32
	v_perm_b32 v45, v138, v141, s8
	v_perm_b32 v46, v139, v141, s61
	v_perm_b32 v47, v139, v141, s98
	v_pk_fma_f32 v[98:99], v[98:99], v[186:187], v[44:45]
	v_pk_fma_f32 v[100:101], v[100:101], v[188:189], v[46:47]
	v_add_u32_e32 v44, 0x80, v110
	v_add_u32_e32 v45, 0x80, v111
	v_add_u32_e32 v46, 0x80, v112
	v_add_u32_e32 v47, 0x80, v113
	v_perm_b32 v48, v45, v44, s78
	v_perm_b32 v49, v47, v46, s78
	v_perm_b32 v42, v45, v44, s79
	v_perm_b32 v43, v47, v46, s79
	v_perm_b32 v56, v43, v42, s60
	v_add_u32_e32 v44, 0x80, v106
	v_add_u32_e32 v45, 0x80, v107
	v_add_u32_e32 v46, 0x80, v108
	v_add_u32_e32 v47, 0x80, v109
	v_perm_b32 v50, v45, v44, s78
	v_perm_b32 v51, v47, v46, s78
	v_perm_b32 v42, v45, v44, s79
	v_perm_b32 v43, v47, v46, s79
	v_perm_b32 v57, v43, v42, s60
	v_add_u32_e32 v44, 0x80, v102
	v_add_u32_e32 v45, 0x80, v103
	v_add_u32_e32 v46, 0x80, v104
	v_add_u32_e32 v47, 0x80, v105
	v_perm_b32 v52, v45, v44, s78
	v_perm_b32 v53, v47, v46, s78
	v_perm_b32 v42, v45, v44, s79
	v_perm_b32 v43, v47, v46, s79
	v_perm_b32 v168, v43, v42, s60
	v_add_u32_e32 v44, 0x80, v98
	v_add_u32_e32 v45, 0x80, v99
	v_add_u32_e32 v46, 0x80, v100
	v_add_u32_e32 v47, 0x80, v101
	v_perm_b32 v54, v45, v44, s78
	v_perm_b32 v55, v47, v46, s78
	v_perm_b32 v42, v45, v44, s79
	v_perm_b32 v43, v47, v46, s79
	v_perm_b32 v169, v43, v42, s60
	s_mov_b64 vcc, s[66:67]
	v_cndmask_b32_dpp v130, v52, v48, vcc quad_perm:[1,0,3,2] row_mask:0xf bank_mask:0xf
	v_cndmask_b32_dpp v131, v53, v49, vcc quad_perm:[1,0,3,2] row_mask:0xf bank_mask:0xf
	v_cndmask_b32_dpp v132, v54, v50, vcc quad_perm:[1,0,3,2] row_mask:0xf bank_mask:0xf
	v_cndmask_b32_dpp v133, v55, v51, vcc quad_perm:[1,0,3,2] row_mask:0xf bank_mask:0xf
	s_mov_b64 vcc, s[62:63]
	v_cndmask_b32_dpp v52, v48, v52, vcc quad_perm:[1,0,3,2] row_mask:0xf bank_mask:0xf
	v_cndmask_b32_dpp v53, v49, v53, vcc quad_perm:[1,0,3,2] row_mask:0xf bank_mask:0xf
	v_cndmask_b32_dpp v54, v50, v54, vcc quad_perm:[1,0,3,2] row_mask:0xf bank_mask:0xf
	v_cndmask_b32_dpp v55, v51, v55, vcc quad_perm:[1,0,3,2] row_mask:0xf bank_mask:0xf
	s_mov_b64 vcc, s[66:67]
	v_cndmask_b32_dpp v136, v168, v56, vcc quad_perm:[1,0,3,2] row_mask:0xf bank_mask:0xf
	v_cndmask_b32_dpp v137, v169, v57, vcc quad_perm:[1,0,3,2] row_mask:0xf bank_mask:0xf
	s_mov_b64 vcc, s[62:63]
	v_cndmask_b32_dpp v168, v56, v168, vcc quad_perm:[1,0,3,2] row_mask:0xf bank_mask:0xf
	v_cndmask_b32_dpp v169, v57, v169, vcc quad_perm:[1,0,3,2] row_mask:0xf bank_mask:0xf
	s_add_u32 s88, s58, 0x10000
	s_addc_u32 s89, s59, 0
	s_add_u32 s90, s74, 0x8000
	s_addc_u32 s91, s75, 0
	global_store_dwordx4 v171, v[130:133], s[88:89]
	global_store_dwordx4 v171, v[52:55], s[88:89] offset:2048
	global_store_dwordx2 v170, v[136:137], s[90:91]
	global_store_dwordx2 v170, v[168:169], s[90:91] offset:1024
	s_add_u32 s84, s58, 0x40000
	s_addc_u32 s85, s59, 0
	s_add_u32 s86, s74, 0x20000
	s_addc_u32 s87, s75, 0
	global_load_dwordx4 v[98:101], v171, s[84:85]
	global_load_dwordx2 v[102:103], v170, s[86:87]
	global_load_dwordx4 v[104:107], v171, s[84:85] offset:2048
	global_load_dwordx2 v[108:109], v170, s[86:87] offset:1024
	s_waitcnt vmcnt(8)
	s_mov_b64 vcc, s[66:67]
	v_cndmask_b32_dpp v48, v120, v114, vcc quad_perm:[1,0,3,2] row_mask:0xf bank_mask:0xf
	v_cndmask_b32_dpp v49, v121, v115, vcc quad_perm:[1,0,3,2] row_mask:0xf bank_mask:0xf
	v_cndmask_b32_dpp v50, v122, v116, vcc quad_perm:[1,0,3,2] row_mask:0xf bank_mask:0xf
	v_cndmask_b32_dpp v51, v123, v117, vcc quad_perm:[1,0,3,2] row_mask:0xf bank_mask:0xf
	s_mov_b64 vcc, s[62:63]
	v_cndmask_b32_dpp v120, v114, v120, vcc quad_perm:[1,0,3,2] row_mask:0xf bank_mask:0xf
	v_cndmask_b32_dpp v121, v115, v121, vcc quad_perm:[1,0,3,2] row_mask:0xf bank_mask:0xf
	v_cndmask_b32_dpp v122, v116, v122, vcc quad_perm:[1,0,3,2] row_mask:0xf bank_mask:0xf
	v_cndmask_b32_dpp v123, v117, v123, vcc quad_perm:[1,0,3,2] row_mask:0xf bank_mask:0xf
	s_mov_b64 vcc, s[66:67]
	v_cndmask_b32_dpp v52, v124, v118, vcc quad_perm:[1,0,3,2] row_mask:0xf bank_mask:0xf
	v_cndmask_b32_dpp v53, v125, v119, vcc quad_perm:[1,0,3,2] row_mask:0xf bank_mask:0xf
	s_mov_b64 vcc, s[62:63]
	v_cndmask_b32_dpp v124, v118, v124, vcc quad_perm:[1,0,3,2] row_mask:0xf bank_mask:0xf
	v_cndmask_b32_dpp v125, v119, v125, vcc quad_perm:[1,0,3,2] row_mask:0xf bank_mask:0xf
	v_perm_b32 v44, v48, v52, s32
	v_perm_b32 v45, v48, v52, s8
	v_perm_b32 v46, v49, v52, s61
	v_perm_b32 v47, v49, v52, s98
	v_pk_fma_f32 v[94:95], v[94:95], v[174:175], v[44:45]
	v_pk_fma_f32 v[96:97], v[96:97], v[176:177], v[46:47]
	v_perm_b32 v44, v50, v53, s32
	v_perm_b32 v45, v50, v53, s8
	v_perm_b32 v46, v51, v53, s61
	v_perm_b32 v47, v51, v53, s98
	v_pk_fma_f32 v[90:91], v[90:91], v[178:179], v[44:45]
	v_pk_fma_f32 v[92:93], v[92:93], v[180:181], v[46:47]
	v_perm_b32 v44, v120, v124, s32
	v_perm_b32 v45, v120, v124, s8
	v_perm_b32 v46, v121, v124, s61
	v_perm_b32 v47, v121, v124, s98
	v_pk_fma_f32 v[86:87], v[86:87], v[182:183], v[44:45]
	v_pk_fma_f32 v[88:89], v[88:89], v[184:185], v[46:47]
	v_perm_b32 v44, v122, v125, s32
	v_perm_b32 v45, v122, v125, s8
	v_perm_b32 v46, v123, v125, s61
	v_perm_b32 v47, v123, v125, s98
	v_pk_fma_f32 v[82:83], v[82:83], v[186:187], v[44:45]
	v_pk_fma_f32 v[84:85], v[84:85], v[188:189], v[46:47]
	v_add_u32_e32 v44, 0x80, v94
	v_add_u32_e32 v45, 0x80, v95
	v_add_u32_e32 v46, 0x80, v96
	v_add_u32_e32 v47, 0x80, v97
	v_perm_b32 v48, v45, v44, s78
	v_perm_b32 v49, v47, v46, s78
	v_perm_b32 v42, v45, v44, s79
	v_perm_b32 v43, v47, v46, s79
	v_perm_b32 v56, v43, v42, s60
	v_add_u32_e32 v44, 0x80, v90
	v_add_u32_e32 v45, 0x80, v91
	v_add_u32_e32 v46, 0x80, v92
	v_add_u32_e32 v47, 0x80, v93
	v_perm_b32 v50, v45, v44, s78
	v_perm_b32 v51, v47, v46, s78
	v_perm_b32 v42, v45, v44, s79
	v_perm_b32 v43, v47, v46, s79
	v_perm_b32 v57, v43, v42, s60
	v_add_u32_e32 v44, 0x80, v86
	v_add_u32_e32 v45, 0x80, v87
	v_add_u32_e32 v46, 0x80, v88
	v_add_u32_e32 v47, 0x80, v89
	v_perm_b32 v52, v45, v44, s78
	v_perm_b32 v53, v47, v46, s78
	v_perm_b32 v42, v45, v44, s79
	v_perm_b32 v43, v47, v46, s79
	v_perm_b32 v168, v43, v42, s60
	v_add_u32_e32 v44, 0x80, v82
	v_add_u32_e32 v45, 0x80, v83
	v_add_u32_e32 v46, 0x80, v84
	v_add_u32_e32 v47, 0x80, v85
	v_perm_b32 v54, v45, v44, s78
	v_perm_b32 v55, v47, v46, s78
	v_perm_b32 v42, v45, v44, s79
	v_perm_b32 v43, v47, v46, s79
	v_perm_b32 v169, v43, v42, s60
	s_mov_b64 vcc, s[66:67]
	v_cndmask_b32_dpp v114, v52, v48, vcc quad_perm:[1,0,3,2] row_mask:0xf bank_mask:0xf
	v_cndmask_b32_dpp v115, v53, v49, vcc quad_perm:[1,0,3,2] row_mask:0xf bank_mask:0xf
	v_cndmask_b32_dpp v116, v54, v50, vcc quad_perm:[1,0,3,2] row_mask:0xf bank_mask:0xf
	v_cndmask_b32_dpp v117, v55, v51, vcc quad_perm:[1,0,3,2] row_mask:0xf bank_mask:0xf
	s_mov_b64 vcc, s[62:63]
	v_cndmask_b32_dpp v52, v48, v52, vcc quad_perm:[1,0,3,2] row_mask:0xf bank_mask:0xf
	v_cndmask_b32_dpp v53, v49, v53, vcc quad_perm:[1,0,3,2] row_mask:0xf bank_mask:0xf
	v_cndmask_b32_dpp v54, v50, v54, vcc quad_perm:[1,0,3,2] row_mask:0xf bank_mask:0xf
	v_cndmask_b32_dpp v55, v51, v55, vcc quad_perm:[1,0,3,2] row_mask:0xf bank_mask:0xf
	s_mov_b64 vcc, s[66:67]
	v_cndmask_b32_dpp v120, v168, v56, vcc quad_perm:[1,0,3,2] row_mask:0xf bank_mask:0xf
	v_cndmask_b32_dpp v121, v169, v57, vcc quad_perm:[1,0,3,2] row_mask:0xf bank_mask:0xf
	s_mov_b64 vcc, s[62:63]
	v_cndmask_b32_dpp v168, v56, v168, vcc quad_perm:[1,0,3,2] row_mask:0xf bank_mask:0xf
	v_cndmask_b32_dpp v169, v57, v169, vcc quad_perm:[1,0,3,2] row_mask:0xf bank_mask:0xf
	s_add_u32 s88, s58, 0x18000
	s_addc_u32 s89, s59, 0
	s_add_u32 s90, s74, 0xc000
	s_addc_u32 s91, s75, 0
	global_store_dwordx4 v171, v[114:117], s[88:89]
	global_store_dwordx4 v171, v[52:55], s[88:89] offset:2048
	global_store_dwordx2 v170, v[120:121], s[90:91]
	global_store_dwordx2 v170, v[168:169], s[90:91] offset:1024
	s_add_u32 s84, s58, 0x48000
	s_addc_u32 s85, s59, 0
	s_add_u32 s86, s74, 0x24000
	s_addc_u32 s87, s75, 0
	global_load_dwordx4 v[82:85], v171, s[84:85]
	global_load_dwordx2 v[86:87], v170, s[86:87]
	global_load_dwordx4 v[88:91], v171, s[84:85] offset:2048
	global_load_dwordx2 v[92:93], v170, s[86:87] offset:1024
	s_waitcnt vmcnt(8)
	s_mov_b64 vcc, s[66:67]
	v_cndmask_b32_dpp v48, v104, v98, vcc quad_perm:[1,0,3,2] row_mask:0xf bank_mask:0xf
	v_cndmask_b32_dpp v49, v105, v99, vcc quad_perm:[1,0,3,2] row_mask:0xf bank_mask:0xf
	v_cndmask_b32_dpp v50, v106, v100, vcc quad_perm:[1,0,3,2] row_mask:0xf bank_mask:0xf
	v_cndmask_b32_dpp v51, v107, v101, vcc quad_perm:[1,0,3,2] row_mask:0xf bank_mask:0xf
	s_mov_b64 vcc, s[62:63]
	v_cndmask_b32_dpp v104, v98, v104, vcc quad_perm:[1,0,3,2] row_mask:0xf bank_mask:0xf
	v_cndmask_b32_dpp v105, v99, v105, vcc quad_perm:[1,0,3,2] row_mask:0xf bank_mask:0xf
	v_cndmask_b32_dpp v106, v100, v106, vcc quad_perm:[1,0,3,2] row_mask:0xf bank_mask:0xf
	v_cndmask_b32_dpp v107, v101, v107, vcc quad_perm:[1,0,3,2] row_mask:0xf bank_mask:0xf
	s_mov_b64 vcc, s[66:67]
	v_cndmask_b32_dpp v52, v108, v102, vcc quad_perm:[1,0,3,2] row_mask:0xf bank_mask:0xf
	v_cndmask_b32_dpp v53, v109, v103, vcc quad_perm:[1,0,3,2] row_mask:0xf bank_mask:0xf
	s_mov_b64 vcc, s[62:63]
	v_cndmask_b32_dpp v108, v102, v108, vcc quad_perm:[1,0,3,2] row_mask:0xf bank_mask:0xf
	v_cndmask_b32_dpp v109, v103, v109, vcc quad_perm:[1,0,3,2] row_mask:0xf bank_mask:0xf
	v_perm_b32 v44, v48, v52, s32
	v_perm_b32 v45, v48, v52, s8
	v_perm_b32 v46, v49, v52, s61
	v_perm_b32 v47, v49, v52, s98
	v_pk_fma_f32 v[78:79], v[78:79], v[174:175], v[44:45]
	v_pk_fma_f32 v[80:81], v[80:81], v[176:177], v[46:47]
	v_perm_b32 v44, v50, v53, s32
	v_perm_b32 v45, v50, v53, s8
	v_perm_b32 v46, v51, v53, s61
	v_perm_b32 v47, v51, v53, s98
	v_pk_fma_f32 v[74:75], v[74:75], v[178:179], v[44:45]
	v_pk_fma_f32 v[76:77], v[76:77], v[180:181], v[46:47]
	v_perm_b32 v44, v104, v108, s32
	v_perm_b32 v45, v104, v108, s8
	v_perm_b32 v46, v105, v108, s61
	v_perm_b32 v47, v105, v108, s98
	v_pk_fma_f32 v[70:71], v[70:71], v[182:183], v[44:45]
	v_pk_fma_f32 v[72:73], v[72:73], v[184:185], v[46:47]
	v_perm_b32 v44, v106, v109, s32
	v_perm_b32 v45, v106, v109, s8
	v_perm_b32 v46, v107, v109, s61
	v_perm_b32 v47, v107, v109, s98
	v_pk_fma_f32 v[66:67], v[66:67], v[186:187], v[44:45]
	v_pk_fma_f32 v[68:69], v[68:69], v[188:189], v[46:47]
	v_add_u32_e32 v44, 0x80, v78
	v_add_u32_e32 v45, 0x80, v79
	v_add_u32_e32 v46, 0x80, v80
	v_add_u32_e32 v47, 0x80, v81
	v_perm_b32 v48, v45, v44, s78
	v_perm_b32 v49, v47, v46, s78
	v_perm_b32 v42, v45, v44, s79
	v_perm_b32 v43, v47, v46, s79
	v_perm_b32 v56, v43, v42, s60
	v_add_u32_e32 v44, 0x80, v74
	v_add_u32_e32 v45, 0x80, v75
	v_add_u32_e32 v46, 0x80, v76
	v_add_u32_e32 v47, 0x80, v77
	v_perm_b32 v50, v45, v44, s78
	v_perm_b32 v51, v47, v46, s78
	v_perm_b32 v42, v45, v44, s79
	v_perm_b32 v43, v47, v46, s79
	v_perm_b32 v57, v43, v42, s60
	v_add_u32_e32 v44, 0x80, v70
	v_add_u32_e32 v45, 0x80, v71
	v_add_u32_e32 v46, 0x80, v72
	v_add_u32_e32 v47, 0x80, v73
	v_perm_b32 v52, v45, v44, s78
	v_perm_b32 v53, v47, v46, s78
	v_perm_b32 v42, v45, v44, s79
	v_perm_b32 v43, v47, v46, s79
	v_perm_b32 v168, v43, v42, s60
	v_add_u32_e32 v44, 0x80, v66
	v_add_u32_e32 v45, 0x80, v67
	v_add_u32_e32 v46, 0x80, v68
	v_add_u32_e32 v47, 0x80, v69
	v_perm_b32 v54, v45, v44, s78
	v_perm_b32 v55, v47, v46, s78
	v_perm_b32 v42, v45, v44, s79
	v_perm_b32 v43, v47, v46, s79
	v_perm_b32 v169, v43, v42, s60
	s_mov_b64 vcc, s[66:67]
	v_cndmask_b32_dpp v98, v52, v48, vcc quad_perm:[1,0,3,2] row_mask:0xf bank_mask:0xf
	v_cndmask_b32_dpp v99, v53, v49, vcc quad_perm:[1,0,3,2] row_mask:0xf bank_mask:0xf
	v_cndmask_b32_dpp v100, v54, v50, vcc quad_perm:[1,0,3,2] row_mask:0xf bank_mask:0xf
	v_cndmask_b32_dpp v101, v55, v51, vcc quad_perm:[1,0,3,2] row_mask:0xf bank_mask:0xf
	s_mov_b64 vcc, s[62:63]
	v_cndmask_b32_dpp v52, v48, v52, vcc quad_perm:[1,0,3,2] row_mask:0xf bank_mask:0xf
	v_cndmask_b32_dpp v53, v49, v53, vcc quad_perm:[1,0,3,2] row_mask:0xf bank_mask:0xf
	v_cndmask_b32_dpp v54, v50, v54, vcc quad_perm:[1,0,3,2] row_mask:0xf bank_mask:0xf
	v_cndmask_b32_dpp v55, v51, v55, vcc quad_perm:[1,0,3,2] row_mask:0xf bank_mask:0xf
	s_mov_b64 vcc, s[66:67]
	v_cndmask_b32_dpp v104, v168, v56, vcc quad_perm:[1,0,3,2] row_mask:0xf bank_mask:0xf
	v_cndmask_b32_dpp v105, v169, v57, vcc quad_perm:[1,0,3,2] row_mask:0xf bank_mask:0xf
	s_mov_b64 vcc, s[62:63]
	v_cndmask_b32_dpp v168, v56, v168, vcc quad_perm:[1,0,3,2] row_mask:0xf bank_mask:0xf
	v_cndmask_b32_dpp v169, v57, v169, vcc quad_perm:[1,0,3,2] row_mask:0xf bank_mask:0xf
	s_add_u32 s88, s58, 0x40000
	s_addc_u32 s89, s59, 0
	s_add_u32 s90, s74, 0x20000
	s_addc_u32 s91, s75, 0
	global_store_dwordx4 v171, v[98:101], s[88:89]
	global_store_dwordx4 v171, v[52:55], s[88:89] offset:2048
	global_store_dwordx2 v170, v[104:105], s[90:91]
	global_store_dwordx2 v170, v[168:169], s[90:91] offset:1024
	s_add_u32 s84, s58, 0x50000
	s_addc_u32 s85, s59, 0
	s_add_u32 s86, s74, 0x28000
	s_addc_u32 s87, s75, 0
	global_load_dwordx4 v[66:69], v171, s[84:85]
	global_load_dwordx2 v[70:71], v170, s[86:87]
	global_load_dwordx4 v[72:75], v171, s[84:85] offset:2048
	global_load_dwordx2 v[76:77], v170, s[86:87] offset:1024
	s_waitcnt vmcnt(8)
	s_mov_b64 vcc, s[66:67]
	v_cndmask_b32_dpp v48, v88, v82, vcc quad_perm:[1,0,3,2] row_mask:0xf bank_mask:0xf
	v_cndmask_b32_dpp v49, v89, v83, vcc quad_perm:[1,0,3,2] row_mask:0xf bank_mask:0xf
	v_cndmask_b32_dpp v50, v90, v84, vcc quad_perm:[1,0,3,2] row_mask:0xf bank_mask:0xf
	v_cndmask_b32_dpp v51, v91, v85, vcc quad_perm:[1,0,3,2] row_mask:0xf bank_mask:0xf
	s_mov_b64 vcc, s[62:63]
	v_cndmask_b32_dpp v88, v82, v88, vcc quad_perm:[1,0,3,2] row_mask:0xf bank_mask:0xf
	v_cndmask_b32_dpp v89, v83, v89, vcc quad_perm:[1,0,3,2] row_mask:0xf bank_mask:0xf
	v_cndmask_b32_dpp v90, v84, v90, vcc quad_perm:[1,0,3,2] row_mask:0xf bank_mask:0xf
	v_cndmask_b32_dpp v91, v85, v91, vcc quad_perm:[1,0,3,2] row_mask:0xf bank_mask:0xf
	s_mov_b64 vcc, s[66:67]
	v_cndmask_b32_dpp v52, v92, v86, vcc quad_perm:[1,0,3,2] row_mask:0xf bank_mask:0xf
	v_cndmask_b32_dpp v53, v93, v87, vcc quad_perm:[1,0,3,2] row_mask:0xf bank_mask:0xf
	s_mov_b64 vcc, s[62:63]
	v_cndmask_b32_dpp v92, v86, v92, vcc quad_perm:[1,0,3,2] row_mask:0xf bank_mask:0xf
	v_cndmask_b32_dpp v93, v87, v93, vcc quad_perm:[1,0,3,2] row_mask:0xf bank_mask:0xf
	v_perm_b32 v44, v48, v52, s32
	v_perm_b32 v45, v48, v52, s8
	v_perm_b32 v46, v49, v52, s61
	v_perm_b32 v47, v49, v52, s98
	v_pk_fma_f32 v[62:63], v[62:63], v[174:175], v[44:45]
	v_pk_fma_f32 v[64:65], v[64:65], v[176:177], v[46:47]
	v_perm_b32 v44, v50, v53, s32
	v_perm_b32 v45, v50, v53, s8
	v_perm_b32 v46, v51, v53, s61
	v_perm_b32 v47, v51, v53, s98
	v_pk_fma_f32 v[58:59], v[58:59], v[178:179], v[44:45]
	v_pk_fma_f32 v[60:61], v[60:61], v[180:181], v[46:47]
	v_perm_b32 v44, v88, v92, s32
	v_perm_b32 v45, v88, v92, s8
	v_perm_b32 v46, v89, v92, s61
	v_perm_b32 v47, v89, v92, s98
	v_pk_fma_f32 v[38:39], v[38:39], v[182:183], v[44:45]
	v_pk_fma_f32 v[40:41], v[40:41], v[184:185], v[46:47]
	v_perm_b32 v44, v90, v93, s32
	v_perm_b32 v45, v90, v93, s8
	v_perm_b32 v46, v91, v93, s61
	v_perm_b32 v47, v91, v93, s98
	v_pk_fma_f32 v[34:35], v[34:35], v[186:187], v[44:45]
	v_pk_fma_f32 v[36:37], v[36:37], v[188:189], v[46:47]
	v_add_u32_e32 v44, 0x80, v62
	v_add_u32_e32 v45, 0x80, v63
	v_add_u32_e32 v46, 0x80, v64
	v_add_u32_e32 v47, 0x80, v65
	v_perm_b32 v48, v45, v44, s78
	v_perm_b32 v49, v47, v46, s78
	v_perm_b32 v42, v45, v44, s79
	v_perm_b32 v43, v47, v46, s79
	v_perm_b32 v56, v43, v42, s60
	v_add_u32_e32 v44, 0x80, v58
	v_add_u32_e32 v45, 0x80, v59
	v_add_u32_e32 v46, 0x80, v60
	v_add_u32_e32 v47, 0x80, v61
	v_perm_b32 v50, v45, v44, s78
	v_perm_b32 v51, v47, v46, s78
	v_perm_b32 v42, v45, v44, s79
	v_perm_b32 v43, v47, v46, s79
	v_perm_b32 v57, v43, v42, s60
	v_add_u32_e32 v44, 0x80, v38
	v_add_u32_e32 v45, 0x80, v39
	v_add_u32_e32 v46, 0x80, v40
	v_add_u32_e32 v47, 0x80, v41
	v_perm_b32 v52, v45, v44, s78
	v_perm_b32 v53, v47, v46, s78
	v_perm_b32 v42, v45, v44, s79
	v_perm_b32 v43, v47, v46, s79
	v_perm_b32 v168, v43, v42, s60
	v_add_u32_e32 v44, 0x80, v34
	v_add_u32_e32 v45, 0x80, v35
	v_add_u32_e32 v46, 0x80, v36
	v_add_u32_e32 v47, 0x80, v37
	v_perm_b32 v54, v45, v44, s78
	v_perm_b32 v55, v47, v46, s78
	v_perm_b32 v42, v45, v44, s79
	v_perm_b32 v43, v47, v46, s79
	v_perm_b32 v169, v43, v42, s60
	s_mov_b64 vcc, s[66:67]
	v_cndmask_b32_dpp v82, v52, v48, vcc quad_perm:[1,0,3,2] row_mask:0xf bank_mask:0xf
	v_cndmask_b32_dpp v83, v53, v49, vcc quad_perm:[1,0,3,2] row_mask:0xf bank_mask:0xf
	v_cndmask_b32_dpp v84, v54, v50, vcc quad_perm:[1,0,3,2] row_mask:0xf bank_mask:0xf
	v_cndmask_b32_dpp v85, v55, v51, vcc quad_perm:[1,0,3,2] row_mask:0xf bank_mask:0xf
	s_mov_b64 vcc, s[62:63]
	v_cndmask_b32_dpp v52, v48, v52, vcc quad_perm:[1,0,3,2] row_mask:0xf bank_mask:0xf
	v_cndmask_b32_dpp v53, v49, v53, vcc quad_perm:[1,0,3,2] row_mask:0xf bank_mask:0xf
	v_cndmask_b32_dpp v54, v50, v54, vcc quad_perm:[1,0,3,2] row_mask:0xf bank_mask:0xf
	v_cndmask_b32_dpp v55, v51, v55, vcc quad_perm:[1,0,3,2] row_mask:0xf bank_mask:0xf
	s_mov_b64 vcc, s[66:67]
	v_cndmask_b32_dpp v88, v168, v56, vcc quad_perm:[1,0,3,2] row_mask:0xf bank_mask:0xf
	v_cndmask_b32_dpp v89, v169, v57, vcc quad_perm:[1,0,3,2] row_mask:0xf bank_mask:0xf
	s_mov_b64 vcc, s[62:63]
	v_cndmask_b32_dpp v168, v56, v168, vcc quad_perm:[1,0,3,2] row_mask:0xf bank_mask:0xf
	v_cndmask_b32_dpp v169, v57, v169, vcc quad_perm:[1,0,3,2] row_mask:0xf bank_mask:0xf
	s_add_u32 s88, s58, 0x48000
	s_addc_u32 s89, s59, 0
	s_add_u32 s90, s74, 0x24000
	s_addc_u32 s91, s75, 0
	global_store_dwordx4 v171, v[82:85], s[88:89]
	global_store_dwordx4 v171, v[52:55], s[88:89] offset:2048
	global_store_dwordx2 v170, v[88:89], s[90:91]
	global_store_dwordx2 v170, v[168:169], s[90:91] offset:1024
	s_add_u32 s84, s58, 0x58000
	s_addc_u32 s85, s59, 0
	s_add_u32 s86, s74, 0x2c000
	s_addc_u32 s87, s75, 0
	global_load_dwordx4 v[34:37], v171, s[84:85]
	global_load_dwordx2 v[38:39], v170, s[86:87]
	global_load_dwordx4 v[58:61], v171, s[84:85] offset:2048
	global_load_dwordx2 v[40:41], v170, s[86:87] offset:1024
	s_waitcnt vmcnt(8)
	s_mov_b64 vcc, s[66:67]
	v_cndmask_b32_dpp v48, v72, v66, vcc quad_perm:[1,0,3,2] row_mask:0xf bank_mask:0xf
	v_cndmask_b32_dpp v49, v73, v67, vcc quad_perm:[1,0,3,2] row_mask:0xf bank_mask:0xf
	v_cndmask_b32_dpp v50, v74, v68, vcc quad_perm:[1,0,3,2] row_mask:0xf bank_mask:0xf
	v_cndmask_b32_dpp v51, v75, v69, vcc quad_perm:[1,0,3,2] row_mask:0xf bank_mask:0xf
	s_mov_b64 vcc, s[62:63]
	v_cndmask_b32_dpp v72, v66, v72, vcc quad_perm:[1,0,3,2] row_mask:0xf bank_mask:0xf
	v_cndmask_b32_dpp v73, v67, v73, vcc quad_perm:[1,0,3,2] row_mask:0xf bank_mask:0xf
	v_cndmask_b32_dpp v74, v68, v74, vcc quad_perm:[1,0,3,2] row_mask:0xf bank_mask:0xf
	v_cndmask_b32_dpp v75, v69, v75, vcc quad_perm:[1,0,3,2] row_mask:0xf bank_mask:0xf
	s_mov_b64 vcc, s[66:67]
	v_cndmask_b32_dpp v52, v76, v70, vcc quad_perm:[1,0,3,2] row_mask:0xf bank_mask:0xf
	v_cndmask_b32_dpp v53, v77, v71, vcc quad_perm:[1,0,3,2] row_mask:0xf bank_mask:0xf
	s_mov_b64 vcc, s[62:63]
	v_cndmask_b32_dpp v76, v70, v76, vcc quad_perm:[1,0,3,2] row_mask:0xf bank_mask:0xf
	v_cndmask_b32_dpp v77, v71, v77, vcc quad_perm:[1,0,3,2] row_mask:0xf bank_mask:0xf
	v_perm_b32 v44, v48, v52, s32
	v_perm_b32 v45, v48, v52, s8
	v_perm_b32 v46, v49, v52, s61
	v_perm_b32 v47, v49, v52, s98
	v_pk_fma_f32 v[30:31], v[30:31], v[174:175], v[44:45]
	v_pk_fma_f32 v[32:33], v[32:33], v[176:177], v[46:47]
	v_perm_b32 v44, v50, v53, s32
	v_perm_b32 v45, v50, v53, s8
	v_perm_b32 v46, v51, v53, s61
	v_perm_b32 v47, v51, v53, s98
	v_pk_fma_f32 v[26:27], v[26:27], v[178:179], v[44:45]
	v_pk_fma_f32 v[28:29], v[28:29], v[180:181], v[46:47]
	v_perm_b32 v44, v72, v76, s32
	v_perm_b32 v45, v72, v76, s8
	v_perm_b32 v46, v73, v76, s61
	v_perm_b32 v47, v73, v76, s98
	v_pk_fma_f32 v[22:23], v[22:23], v[182:183], v[44:45]
	v_pk_fma_f32 v[24:25], v[24:25], v[184:185], v[46:47]
	v_perm_b32 v44, v74, v77, s32
	v_perm_b32 v45, v74, v77, s8
	v_perm_b32 v46, v75, v77, s61
	v_perm_b32 v47, v75, v77, s98
	v_pk_fma_f32 v[18:19], v[18:19], v[186:187], v[44:45]
	v_pk_fma_f32 v[20:21], v[20:21], v[188:189], v[46:47]
	v_add_u32_e32 v44, 0x80, v30
	v_add_u32_e32 v45, 0x80, v31
	v_add_u32_e32 v46, 0x80, v32
	v_add_u32_e32 v47, 0x80, v33
	v_perm_b32 v48, v45, v44, s78
	v_perm_b32 v49, v47, v46, s78
	v_perm_b32 v42, v45, v44, s79
	v_perm_b32 v43, v47, v46, s79
	v_perm_b32 v56, v43, v42, s60
	v_add_u32_e32 v44, 0x80, v26
	v_add_u32_e32 v45, 0x80, v27
	v_add_u32_e32 v46, 0x80, v28
	v_add_u32_e32 v47, 0x80, v29
	v_perm_b32 v50, v45, v44, s78
	v_perm_b32 v51, v47, v46, s78
	v_perm_b32 v42, v45, v44, s79
	v_perm_b32 v43, v47, v46, s79
	v_perm_b32 v57, v43, v42, s60
	v_add_u32_e32 v44, 0x80, v22
	v_add_u32_e32 v45, 0x80, v23
	v_add_u32_e32 v46, 0x80, v24
	v_add_u32_e32 v47, 0x80, v25
	v_perm_b32 v52, v45, v44, s78
	v_perm_b32 v53, v47, v46, s78
	v_perm_b32 v42, v45, v44, s79
	v_perm_b32 v43, v47, v46, s79
	v_perm_b32 v168, v43, v42, s60
	v_add_u32_e32 v44, 0x80, v18
	v_add_u32_e32 v45, 0x80, v19
	v_add_u32_e32 v46, 0x80, v20
	v_add_u32_e32 v47, 0x80, v21
	v_perm_b32 v54, v45, v44, s78
	v_perm_b32 v55, v47, v46, s78
	v_perm_b32 v42, v45, v44, s79
	v_perm_b32 v43, v47, v46, s79
	v_perm_b32 v169, v43, v42, s60
	s_mov_b64 vcc, s[66:67]
	v_cndmask_b32_dpp v66, v52, v48, vcc quad_perm:[1,0,3,2] row_mask:0xf bank_mask:0xf
	v_cndmask_b32_dpp v67, v53, v49, vcc quad_perm:[1,0,3,2] row_mask:0xf bank_mask:0xf
	v_cndmask_b32_dpp v68, v54, v50, vcc quad_perm:[1,0,3,2] row_mask:0xf bank_mask:0xf
	v_cndmask_b32_dpp v69, v55, v51, vcc quad_perm:[1,0,3,2] row_mask:0xf bank_mask:0xf
	s_mov_b64 vcc, s[62:63]
	v_cndmask_b32_dpp v52, v48, v52, vcc quad_perm:[1,0,3,2] row_mask:0xf bank_mask:0xf
	v_cndmask_b32_dpp v53, v49, v53, vcc quad_perm:[1,0,3,2] row_mask:0xf bank_mask:0xf
	v_cndmask_b32_dpp v54, v50, v54, vcc quad_perm:[1,0,3,2] row_mask:0xf bank_mask:0xf
	v_cndmask_b32_dpp v55, v51, v55, vcc quad_perm:[1,0,3,2] row_mask:0xf bank_mask:0xf
	s_mov_b64 vcc, s[66:67]
	v_cndmask_b32_dpp v72, v168, v56, vcc quad_perm:[1,0,3,2] row_mask:0xf bank_mask:0xf
	v_cndmask_b32_dpp v73, v169, v57, vcc quad_perm:[1,0,3,2] row_mask:0xf bank_mask:0xf
	s_mov_b64 vcc, s[62:63]
	v_cndmask_b32_dpp v168, v56, v168, vcc quad_perm:[1,0,3,2] row_mask:0xf bank_mask:0xf
	v_cndmask_b32_dpp v169, v57, v169, vcc quad_perm:[1,0,3,2] row_mask:0xf bank_mask:0xf
	s_add_u32 s88, s58, 0x50000
	s_addc_u32 s89, s59, 0
	s_add_u32 s90, s74, 0x28000
	s_addc_u32 s91, s75, 0
	global_store_dwordx4 v171, v[66:69], s[88:89]
	global_store_dwordx4 v171, v[52:55], s[88:89] offset:2048
	global_store_dwordx2 v170, v[72:73], s[90:91]
	global_store_dwordx2 v170, v[168:169], s[90:91] offset:1024
	s_waitcnt vmcnt(4)
	s_mov_b64 vcc, s[66:67]
	v_cndmask_b32_dpp v48, v58, v34, vcc quad_perm:[1,0,3,2] row_mask:0xf bank_mask:0xf
	v_cndmask_b32_dpp v49, v59, v35, vcc quad_perm:[1,0,3,2] row_mask:0xf bank_mask:0xf
	v_cndmask_b32_dpp v50, v60, v36, vcc quad_perm:[1,0,3,2] row_mask:0xf bank_mask:0xf
	v_cndmask_b32_dpp v51, v61, v37, vcc quad_perm:[1,0,3,2] row_mask:0xf bank_mask:0xf
	s_mov_b64 vcc, s[62:63]
	v_cndmask_b32_dpp v58, v34, v58, vcc quad_perm:[1,0,3,2] row_mask:0xf bank_mask:0xf
	v_cndmask_b32_dpp v59, v35, v59, vcc quad_perm:[1,0,3,2] row_mask:0xf bank_mask:0xf
	v_cndmask_b32_dpp v60, v36, v60, vcc quad_perm:[1,0,3,2] row_mask:0xf bank_mask:0xf
	v_cndmask_b32_dpp v61, v37, v61, vcc quad_perm:[1,0,3,2] row_mask:0xf bank_mask:0xf
	s_mov_b64 vcc, s[66:67]
	v_cndmask_b32_dpp v52, v40, v38, vcc quad_perm:[1,0,3,2] row_mask:0xf bank_mask:0xf
	v_cndmask_b32_dpp v53, v41, v39, vcc quad_perm:[1,0,3,2] row_mask:0xf bank_mask:0xf
	s_mov_b64 vcc, s[62:63]
	v_cndmask_b32_dpp v40, v38, v40, vcc quad_perm:[1,0,3,2] row_mask:0xf bank_mask:0xf
	v_cndmask_b32_dpp v41, v39, v41, vcc quad_perm:[1,0,3,2] row_mask:0xf bank_mask:0xf
	v_perm_b32 v44, v48, v52, s32
	v_perm_b32 v45, v48, v52, s8
	v_perm_b32 v46, v49, v52, s61
	v_perm_b32 v47, v49, v52, s98
	v_pk_fma_f32 v[14:15], v[14:15], v[174:175], v[44:45]
	v_pk_fma_f32 v[16:17], v[16:17], v[176:177], v[46:47]
	v_perm_b32 v44, v50, v53, s32
	v_perm_b32 v45, v50, v53, s8
	v_perm_b32 v46, v51, v53, s61
	v_perm_b32 v47, v51, v53, s98
	v_pk_fma_f32 v[10:11], v[10:11], v[178:179], v[44:45]
	v_pk_fma_f32 v[12:13], v[12:13], v[180:181], v[46:47]
	v_perm_b32 v44, v58, v40, s32
	v_perm_b32 v45, v58, v40, s8
	v_perm_b32 v46, v59, v40, s61
	v_perm_b32 v47, v59, v40, s98
	v_pk_fma_f32 v[6:7], v[6:7], v[182:183], v[44:45]
	v_pk_fma_f32 v[8:9], v[8:9], v[184:185], v[46:47]
	v_perm_b32 v44, v60, v41, s32
	v_perm_b32 v45, v60, v41, s8
	v_perm_b32 v46, v61, v41, s61
	v_perm_b32 v47, v61, v41, s98
	v_pk_fma_f32 v[2:3], v[2:3], v[186:187], v[44:45]
	v_pk_fma_f32 v[4:5], v[4:5], v[188:189], v[46:47]
	v_add_u32_e32 v44, 0x80, v14
	v_add_u32_e32 v45, 0x80, v15
	v_add_u32_e32 v46, 0x80, v16
	v_add_u32_e32 v47, 0x80, v17
	v_perm_b32 v48, v45, v44, s78
	v_perm_b32 v49, v47, v46, s78
	v_perm_b32 v42, v45, v44, s79
	v_perm_b32 v43, v47, v46, s79
	v_perm_b32 v56, v43, v42, s60
	v_add_u32_e32 v44, 0x80, v10
	v_add_u32_e32 v45, 0x80, v11
	v_add_u32_e32 v46, 0x80, v12
	v_add_u32_e32 v47, 0x80, v13
	v_perm_b32 v50, v45, v44, s78
	v_perm_b32 v51, v47, v46, s78
	v_perm_b32 v42, v45, v44, s79
	v_perm_b32 v43, v47, v46, s79
	v_perm_b32 v57, v43, v42, s60
	v_add_u32_e32 v44, 0x80, v6
	v_add_u32_e32 v45, 0x80, v7
	v_add_u32_e32 v46, 0x80, v8
	v_add_u32_e32 v47, 0x80, v9
	v_perm_b32 v52, v45, v44, s78
	v_perm_b32 v53, v47, v46, s78
	v_perm_b32 v42, v45, v44, s79
	v_perm_b32 v43, v47, v46, s79
	v_perm_b32 v168, v43, v42, s60
	v_add_u32_e32 v44, 0x80, v2
	v_add_u32_e32 v45, 0x80, v3
	v_add_u32_e32 v46, 0x80, v4
	v_add_u32_e32 v47, 0x80, v5
	v_perm_b32 v54, v45, v44, s78
	v_perm_b32 v55, v47, v46, s78
	v_perm_b32 v42, v45, v44, s79
	v_perm_b32 v43, v47, v46, s79
	v_perm_b32 v169, v43, v42, s60
	s_mov_b64 vcc, s[66:67]
	v_cndmask_b32_dpp v34, v52, v48, vcc quad_perm:[1,0,3,2] row_mask:0xf bank_mask:0xf
	v_cndmask_b32_dpp v35, v53, v49, vcc quad_perm:[1,0,3,2] row_mask:0xf bank_mask:0xf
	v_cndmask_b32_dpp v36, v54, v50, vcc quad_perm:[1,0,3,2] row_mask:0xf bank_mask:0xf
	v_cndmask_b32_dpp v37, v55, v51, vcc quad_perm:[1,0,3,2] row_mask:0xf bank_mask:0xf
	s_mov_b64 vcc, s[62:63]
	v_cndmask_b32_dpp v52, v48, v52, vcc quad_perm:[1,0,3,2] row_mask:0xf bank_mask:0xf
	v_cndmask_b32_dpp v53, v49, v53, vcc quad_perm:[1,0,3,2] row_mask:0xf bank_mask:0xf
	v_cndmask_b32_dpp v54, v50, v54, vcc quad_perm:[1,0,3,2] row_mask:0xf bank_mask:0xf
	v_cndmask_b32_dpp v55, v51, v55, vcc quad_perm:[1,0,3,2] row_mask:0xf bank_mask:0xf
	s_mov_b64 vcc, s[66:67]
	v_cndmask_b32_dpp v58, v168, v56, vcc quad_perm:[1,0,3,2] row_mask:0xf bank_mask:0xf
	v_cndmask_b32_dpp v59, v169, v57, vcc quad_perm:[1,0,3,2] row_mask:0xf bank_mask:0xf
	s_mov_b64 vcc, s[62:63]
	v_cndmask_b32_dpp v168, v56, v168, vcc quad_perm:[1,0,3,2] row_mask:0xf bank_mask:0xf
	v_cndmask_b32_dpp v169, v57, v169, vcc quad_perm:[1,0,3,2] row_mask:0xf bank_mask:0xf
	s_add_u32 s88, s58, 0x58000
	s_addc_u32 s89, s59, 0
	s_add_u32 s90, s74, 0x2c000
	s_addc_u32 s91, s75, 0
	global_store_dwordx4 v171, v[34:37], s[88:89]
	global_store_dwordx4 v171, v[52:55], s[88:89] offset:2048
	global_store_dwordx2 v170, v[58:59], s[90:91]
	global_store_dwordx2 v170, v[168:169], s[90:91] offset:1024
	v_readlane_b32 s70, v244, 53
	v_readlane_b32 s71, v244, 54
	v_readlane_b32 s56, v246, 3
	v_readlane_b32 s57, v246, 4
